# P3: kv-up unit rotation 140->56 so the 8 WGs with a 4th kv-up unit are ones with a single q-up unit; q-up epilogue: qng gains hoisted + SSQ row prefetched one block ahead
# speedup vs baseline: 1.0163x; 1.0037x over previous
;     __device__ __forceinline__ void epi(Acc& acc, const Unit& u, int wr, int wc, int fr, int fq) const {
;     ...
;             for (int m = 0; m < 4; ++m) { const int row = u.pm * 256 + ai * 128 + rl0 + m * 16;
;                 const f32x4 q0 = *(const f32x4*)(SSQ + (size_t)row * 8), q1 = *(const f32x4*)(SSQ + (size_t)row * 8 + 4);
;                 const float rq = rsqrtf((((q0[0] + q0[1]) + (q0[2] + q0[3])) + ((q1[0] + q1[1]) + (q1[2] + q1[3]))) * (1.f / 384.f) + EPS);
;     ...
;                     const int pos = row < MP ? (row & 4095) : 2048 + ((row - MP) & 63);
;                     const float* rp = rope + (size_t)pos * 32 + (fq & 1) * 8;
;                     const f32x4 c0 = *(const f32x4*)rp, c1 = *(const f32x4*)(rp + 4), s0 = *(const f32x4*)(rp + 16), s1 = *(const f32x4*)(rp + 20);
;                     const f32x4 g0 = *(const f32x4*)(qrg + fq * 8), g1 = *(const f32x4*)(qrg + fq * 8 + 4);
.LBB0_566:
	s_lshl_b32 s4, s83, 8
	v_mov_b32_e32 v189, v179
	v_mov_b32_e32 v128, v182
	s_add_i32 s4, s4, s49
	s_cmp_gt_i32 s82, 1
	v_add_u32_e32 v170, s4, v189
	v_ashrrev_i32_e32 v171, 31, v170
	v_lshlrev_b32_e32 v166, 3, v128
	v_cmp_gt_i32_e32 vcc, 2, v128
	v_lshlrev_b64 v[128:129], 5, v[170:171]
	v_lshl_add_u64 v[132:133], s[68:69], 0, v[128:129]
	global_load_dwordx4 v[128:131], v[132:133], off
	s_nop 0
	global_load_dwordx4 v[132:135], v[132:133], off offset:16
	v_cndmask_b32_e64 v168, 1.0, -1.0, vcc
	v_readlane_b32 s12, v238, 20
	s_cselect_b64 s[8:9], -1, 0
	v_and_b32_e32 v138, 8, v166
	v_ashrrev_i32_e32 v167, 31, v166
	v_readlane_b32 s12, v238, 20
	v_readlane_b32 s13, v238, 21
	v_lshl_add_u64 v[228:229], v[166:167], 2, s[12:13]
	global_load_dwordx4 v[212:215], v[228:229], off
	global_load_dwordx4 v[216:219], v[228:229], off offset:16
	global_load_dwordx4 v[220:223], v[228:229], off offset:128
	global_load_dwordx4 v[224:227], v[228:229], off offset:144
	v_add_u32_e32 v228, 0x10, v170
	v_ashrrev_i32_e32 v229, 31, v228
	v_lshlrev_b64 v[228:229], 5, v[228:229]
	v_lshl_add_u64 v[228:229], s[68:69], 0, v[228:229]
	global_load_dwordx4 v[230:233], v[228:229], off
	global_load_dwordx4 v[234:237], v[228:229], off offset:16
	v_and_b32_e32 v190, 63, v189
	v_readlane_b32 s14, v238, 22
	v_readlane_b32 s15, v238, 23
	v_mov_b32_e32 v169, v168
	s_mov_b64 s[4:5], -1
	v_or_b32_e32 v171, 0x800, v190
	v_lshlrev_b32_e32 v172, 2, v138
	v_lshl_add_u64 v[174:175], v[166:167], 2, s[14:15]
	v_readlane_b32 s13, v238, 21
	v_readlane_b32 s16, v238, 24
	v_readlane_b32 s17, v238, 25
	v_readlane_b32 s18, v238, 26
	v_readlane_b32 s19, v238, 27
	v_readlane_b32 s20, v238, 28
	v_readlane_b32 s21, v238, 29
	v_readlane_b32 s22, v238, 30
	v_readlane_b32 s23, v238, 31
	v_readlane_b32 s24, v238, 32
	v_readlane_b32 s25, v238, 33
	v_readlane_b32 s26, v238, 34
	v_readlane_b32 s27, v238, 35
	s_waitcnt vmcnt(0)
	v_mov_b32_e32 v136, v128
	v_mov_b32_e32 v137, v132
	v_mov_b32_e32 v132, v129
	v_pk_add_f32 v[128:129], v[136:137], v[132:133]
	v_mov_b32_e32 v132, v130
	v_mov_b32_e32 v133, v134
	v_mov_b32_e32 v134, v131
	v_pk_add_f32 v[130:131], v[132:133], v[134:135]
	s_nop 0
	v_pk_add_f32 v[128:129], v[128:129], v[130:131]
	s_nop 0
	v_add_f32_e32 v128, v128, v129
	v_fmamk_f32 v128, v128, 0x3b2aaaab, v187
	v_cmp_gt_f32_e32 vcc, s45, v128
	v_mul_f32_e32 v129, 0x4b800000, v128
	s_nop 0
	v_cndmask_b32_e32 v128, v128, v129, vcc
	v_rsq_f32_e32 v128, v128
	s_nop 0
	v_mul_f32_e32 v129, 0x45800000, v128
	v_cndmask_b32_e32 v178, v128, v129, vcc
	s_and_b64 vcc, exec, s[8:9]
	s_cbranch_vccz .LBB0_568
	v_cmp_gt_i32_e32 vcc, s50, v170
	v_and_b32_e32 v128, 0xfff, v170
	v_mov_b32_e32 v173, v161
	v_cndmask_b32_e32 v128, v171, v128, vcc
	v_lshlrev_b32_e32 v160, 7, v128
	v_lshl_add_u64 v[128:129], s[76:77], 0, v[160:161]
	v_lshl_add_u64 v[136:137], v[128:129], 0, v[172:173]
	global_load_dwordx4 v[132:135], v[136:137], off offset:16
	global_load_dwordx4 v[140:143], v[136:137], off
	global_load_dwordx4 v[128:131], v[136:137], off offset:80
	s_nop 0
	global_load_dwordx4 v[136:139], v[136:137], off offset:64
	s_nop 0
	global_load_dwordx4 v[144:147], v[174:175], off offset:16
	global_load_dwordx4 v[148:151], v[174:175], off
	v_pk_mul_f32 v[180:181], v[126:127], v[178:179] op_sel_hi:[1,0]
	v_pk_mul_f32 v[192:193], v[124:125], v[178:179] op_sel_hi:[1,0]
	v_pk_mul_f32 v[198:199], v[180:181], v[180:181]
	v_pk_mul_f32 v[200:201], v[192:193], v[192:193]
	v_pk_mul_f32 v[194:195], v[122:123], v[178:179] op_sel_hi:[1,0]
	v_pk_mul_f32 v[196:197], v[120:121], v[178:179] op_sel_hi:[1,0]
	v_pk_mov_b32 v[202:203], v[200:201], v[198:199] op_sel:[1,0]
	v_mov_b32_e32 v201, v199
	v_and_b32_e32 v173, 64, v188
	v_pk_add_f32 v[198:199], v[202:203], v[200:201]
	v_pk_mul_f32 v[200:201], v[194:195], v[194:195]
	v_pk_mul_f32 v[202:203], v[196:197], v[196:197]
	v_xor_b32_e32 v160, 16, v188
	v_add_u32_e32 v176, 64, v173
	v_mov_b32_e32 v204, v200
	v_mov_b32_e32 v205, v202
	v_mov_b32_e32 v202, v201
	v_cmp_lt_i32_e32 vcc, v160, v176
	v_pk_add_f32 v[200:201], v[204:205], v[202:203]
	v_add_f32_e32 v191, v198, v199
	v_cndmask_b32_e32 v160, v188, v160, vcc
	v_add_f32_e32 v191, v201, v191
	v_lshlrev_b32_e32 v173, 2, v160
	v_add_f32_e32 v191, v200, v191
	ds_bpermute_b32 v198, v173, v191
	v_xor_b32_e32 v160, 32, v188
	v_cmp_lt_i32_e32 vcc, v160, v176
	v_mad_i64_i32 v[176:177], s[4:5], v170, s78, 0
	s_nop 0
	v_cndmask_b32_e32 v160, v188, v160, vcc
	v_lshlrev_b32_e32 v160, 2, v160
	s_waitcnt lgkmcnt(0)
	v_add_f32_e32 v191, v191, v198
	ds_bpermute_b32 v198, v160, v191
	s_waitcnt lgkmcnt(0)
	v_add_f32_e32 v191, v191, v198
	v_fmamk_f32 v191, v191, 0x3d000000, v187
	v_cmp_gt_f32_e32 vcc, s45, v191
	v_mul_f32_e32 v198, 0x4b800000, v191
	s_nop 0
	v_cndmask_b32_e32 v191, v191, v198, vcc
	v_rsq_f32_e32 v191, v191
	s_nop 0
	v_mul_f32_e32 v198, 0x45800000, v191
	v_cndmask_b32_e32 v198, v191, v198, vcc
	v_pk_mul_f32 v[192:193], v[192:193], v[198:199] op_sel_hi:[1,0]
	v_pk_mul_f32 v[180:181], v[180:181], v[198:199] op_sel_hi:[1,0]
	v_pk_mul_f32 v[196:197], v[196:197], v[198:199] op_sel_hi:[1,0]
	v_pk_mul_f32 v[194:195], v[194:195], v[198:199] op_sel_hi:[1,0]
	s_waitcnt vmcnt(1)
	v_pk_mul_f32 v[196:197], v[144:145], v[196:197]
	s_waitcnt vmcnt(0)
	v_pk_mul_f32 v[192:193], v[148:149], v[192:193]
	v_pk_mul_f32 v[180:181], v[150:151], v[180:181]
	ds_bpermute_b32 v198, v160, v192
	ds_bpermute_b32 v199, v160, v193
	ds_bpermute_b32 v202, v160, v180
	ds_bpermute_b32 v203, v160, v181
	v_pk_mul_f32 v[194:195], v[146:147], v[194:195]
	ds_bpermute_b32 v200, v160, v196
	ds_bpermute_b32 v201, v160, v197
	ds_bpermute_b32 v204, v160, v194
	ds_bpermute_b32 v205, v160, v195
	v_pk_mul_f32 v[208:209], v[142:143], v[180:181]
	v_pk_mul_f32 v[180:181], v[140:141], v[192:193]
	s_waitcnt lgkmcnt(6)
; __device__ __forceinline__ unsigned cvt_pk_bf16(float lo, float hi) { unsigned r; asm("v_cvt_pk_bf16_f32 %0, %1, %2" : "=v"(r) : "v"(lo), "v"(hi)); return r; }
;     __device__ __forceinline__ void epi(Acc& acc, const Unit& u, int wr, int wc, int fr, int fq) const {
;     ...
;                     for (int bj = 0; bj < 2; ++bj) { const int head = bj * 4 + wc;
;                         f32x4 v0 = acc[ai][bj][m][0] * rq, v1 = acc[ai][bj][m][1] * rq;
;                         float s = (v0[0] * v0[0] + v0[1] * v0[1]) + (v0[2] * v0[2] + v0[3] * v0[3]) + (v1[0] * v1[0] + v1[1] * v1[1]) + (v1[2] * v1[2] + v1[3] * v1[3]);
;                         s += __shfl_xor(s, 16); s += __shfl_xor(s, 32);
;                         const float r2 = rsqrtf(s * (1.f / 32.f) + EPS);
;                         v0 = v0 * r2 * g0; v1 = v1 * r2 * g1;
;                         f32x4 p0, p1;
; #pragma unroll
;                         for (int e = 0; e < 4; ++e) { p0[e] = __shfl_xor(v0[e], 32); p1[e] = __shfl_xor(v1[e], 32); }
;                         const f32x4 r0 = (v0 * c0 + p0 * s0 * sg) * QSCALE, r1 = (v1 * c1 + p1 * s1 * sg) * QSCALE;
;                         u32x4 w; w.x = cvt_pk_bf16(r0[0], r0[1]); w.y = cvt_pk_bf16(r0[2], r0[3]); w.z = cvt_pk_bf16(r1[0], r1[1]); w.w = cvt_pk_bf16(r1[2], r1[3]);
;                         *(u32x4*)(Q + (size_t)row * 768 + head * 96 + 64 + fq * 8) = w; }
	v_pk_mul_f32 v[198:199], v[136:137], v[198:199]
	s_waitcnt lgkmcnt(4)
	v_pk_mul_f32 v[192:193], v[138:139], v[202:203]
	v_pk_fma_f32 v[198:199], v[168:169], v[198:199], v[180:181]
	v_mov_b32_e32 v180, v168
	v_mov_b32_e32 v181, v168
	v_pk_fma_f32 v[192:193], v[180:181], v[192:193], v[208:209]
	v_pk_mul_f32 v[194:195], v[134:135], v[194:195]
	v_pk_mul_f32 v[202:203], v[192:193], s[52:53] op_sel_hi:[1,0]
	v_pk_mul_f32 v[192:193], v[198:199], s[52:53] op_sel_hi:[1,0]
	v_pk_mul_f32 v[196:197], v[132:133], v[196:197]
	s_waitcnt lgkmcnt(0)
	v_pk_mul_f32 v[198:199], v[130:131], v[204:205]
	v_pk_mul_f32 v[200:201], v[128:129], v[200:201]
	v_pk_fma_f32 v[194:195], v[180:181], v[198:199], v[194:195]
	v_pk_fma_f32 v[196:197], v[168:169], v[200:201], v[196:197]
	v_pk_mul_f32 v[198:199], v[194:195], s[52:53] op_sel_hi:[1,0]
	v_pk_mul_f32 v[194:195], v[196:197], s[52:53] op_sel_hi:[1,0]
	v_mov_b64_e32 v[196:197], s[64:65]
	v_mad_i64_i32 v[196:197], s[4:5], v170, s78, v[196:197]
	v_cvt_pk_bf16_f32 v192, v192, v193
	v_cvt_pk_bf16_f32 v193, v202, v203
	v_cvt_pk_bf16_f32 v194, v194, v195
	v_cvt_pk_bf16_f32 v195, v198, v199
	v_lshl_add_u64 v[196:197], v[166:167], 1, v[196:197]
	global_store_dwordx4 v[196:197], v[192:195], off offset:128
	v_pk_mul_f32 v[196:197], v[114:115], v[178:179] op_sel_hi:[1,0]
	v_pk_mul_f32 v[198:199], v[112:113], v[178:179] op_sel_hi:[1,0]
	v_pk_mul_f32 v[192:193], v[118:119], v[178:179] op_sel_hi:[1,0]
	v_pk_mul_f32 v[194:195], v[116:117], v[178:179] op_sel_hi:[1,0]
	v_pk_mul_f32 v[200:201], v[192:193], v[192:193]
	v_pk_mul_f32 v[202:203], v[194:195], v[194:195]
	s_mov_b64 s[4:5], 0
	v_pk_mov_b32 v[204:205], v[202:203], v[200:201] op_sel:[1,0]
	v_mov_b32_e32 v203, v201
	v_pk_add_f32 v[200:201], v[204:205], v[202:203]
	v_pk_mul_f32 v[202:203], v[196:197], v[196:197]
	v_pk_mul_f32 v[204:205], v[198:199], v[198:199]
	v_mov_b32_e32 v208, v202
	v_mov_b32_e32 v209, v204
	v_mov_b32_e32 v204, v203
	v_pk_add_f32 v[202:203], v[208:209], v[204:205]
	v_add_f32_e32 v191, v200, v201
	v_add_f32_e32 v191, v203, v191
	v_add_f32_e32 v191, v202, v191
	ds_bpermute_b32 v173, v173, v191
	s_waitcnt lgkmcnt(0)
	v_add_f32_e32 v173, v191, v173
	ds_bpermute_b32 v191, v160, v173
	s_waitcnt lgkmcnt(0)
	v_add_f32_e32 v173, v173, v191
	v_fmamk_f32 v173, v173, 0x3d000000, v187
	v_cmp_gt_f32_e32 vcc, s45, v173
	v_mul_f32_e32 v191, 0x4b800000, v173
	s_nop 0
	v_cndmask_b32_e32 v173, v173, v191, vcc
	v_rsq_f32_e32 v173, v173
	s_nop 0
	v_mul_f32_e32 v191, 0x45800000, v173
	v_cndmask_b32_e32 v200, v173, v191, vcc
	v_pk_mul_f32 v[194:195], v[194:195], v[200:201] op_sel_hi:[1,0]
	v_pk_mul_f32 v[192:193], v[192:193], v[200:201] op_sel_hi:[1,0]
	v_pk_mul_f32 v[148:149], v[148:149], v[194:195]
	v_pk_mul_f32 v[150:151], v[150:151], v[192:193]
	v_pk_mul_f32 v[192:193], v[198:199], v[200:201] op_sel_hi:[1,0]
	v_pk_mul_f32 v[194:195], v[196:197], v[200:201] op_sel_hi:[1,0]
	v_pk_mul_f32 v[144:145], v[144:145], v[192:193]
	v_pk_mul_f32 v[146:147], v[146:147], v[194:195]
	ds_bpermute_b32 v194, v160, v144
	ds_bpermute_b32 v195, v160, v145
	ds_bpermute_b32 v198, v160, v146
	ds_bpermute_b32 v199, v160, v147
	ds_bpermute_b32 v192, v160, v148
	ds_bpermute_b32 v193, v160, v149
	ds_bpermute_b32 v196, v160, v150
	ds_bpermute_b32 v197, v160, v151
	v_pk_mul_f32 v[134:135], v[134:135], v[146:147]
	v_pk_mul_f32 v[132:133], v[132:133], v[144:145]
	s_waitcnt lgkmcnt(4)
	v_pk_mul_f32 v[130:131], v[130:131], v[198:199]
	v_pk_mul_f32 v[128:129], v[128:129], v[194:195]
	v_pk_mul_f32 v[142:143], v[142:143], v[150:151]
	v_pk_mul_f32 v[140:141], v[140:141], v[148:149]
	s_waitcnt lgkmcnt(0)
	v_pk_mul_f32 v[138:139], v[138:139], v[196:197]
	v_pk_mul_f32 v[136:137], v[136:137], v[192:193]
	v_pk_fma_f32 v[128:129], v[168:169], v[128:129], v[132:133]
	v_pk_fma_f32 v[130:131], v[180:181], v[130:131], v[134:135]
	v_pk_fma_f32 v[136:137], v[168:169], v[136:137], v[140:141]
	v_pk_fma_f32 v[138:139], v[180:181], v[138:139], v[142:143]
	v_pk_mul_f32 v[132:133], v[130:131], s[52:53] op_sel_hi:[1,0]
	v_pk_mul_f32 v[130:131], v[128:129], s[52:53] op_sel_hi:[1,0]
	v_pk_mul_f32 v[138:139], v[138:139], s[52:53] op_sel_hi:[1,0]
	v_pk_mul_f32 v[136:137], v[136:137], s[52:53] op_sel_hi:[1,0]
	v_cvt_pk_bf16_f32 v129, v138, v139
	v_cvt_pk_bf16_f32 v130, v130, v131
	v_cvt_pk_bf16_f32 v131, v132, v133
	s_nop 0
	v_cvt_pk_bf16_f32 v128, v136, v137
; __device__ __forceinline__ unsigned cvt_pk_bf16(float lo, float hi) { unsigned r; asm("v_cvt_pk_bf16_f32 %0, %1, %2" : "=v"(r) : "v"(lo), "v"(hi)); return r; }
;     __device__ __forceinline__ void epi(Acc& acc, const Unit& u, int wr, int wc, int fr, int fq) const {
;     ...
;                 if (u.pn < 2) {
;                     const int head = u.pn * 4 + wc; float s = 0.f; f32x4 v[2][2];
; #pragma unroll
;                     for (int bj = 0; bj < 2; ++bj)
; #pragma unroll
;                         for (int n = 0; n < 2; ++n) { v[bj][n] = acc[ai][bj][m][n] * rq; const f32x4 x = v[bj][n]; s += (x[0] * x[0] + x[1] * x[1]) + (x[2] * x[2] + x[3] * x[3]); }
;                     s += __shfl_xor(s, 16); s += __shfl_xor(s, 32);
;                     const float r2 = rsqrtf(s * (1.f / 64.f) + EPS) * QSCALE;
; #pragma unroll
;                     for (int bj = 0; bj < 2; ++bj) { const f32x4 g0 = *(const f32x4*)(qng + bj * 32 + fq * 8), g1 = *(const f32x4*)(qng + bj * 32 + fq * 8 + 4);
;                         const f32x4 a = v[bj][0] * r2 * g0, b = v[bj][1] * r2 * g1;
;                         u32x4 w; w.x = cvt_pk_bf16(a[0], a[1]); w.y = cvt_pk_bf16(a[2], a[3]); w.z = cvt_pk_bf16(b[0], b[1]); w.w = cvt_pk_bf16(b[2], b[3]);
;                         *(u32x4*)(Q + (size_t)row * 768 + head * 96 + bj * 32 + fq * 8) = w; }
.LBB0_568:
	s_lshl_b32 s10, s82, 2
	s_or_b32 s10, s10, s48
	v_readlane_b32 s12, v238, 20
	s_mul_i32 s82, s10, 0x60
	v_readlane_b32 s13, v238, 21
	s_ashr_i32 s83, s82, 31
	s_mov_b64 s[10:11], 0x380
	s_andn2_b64 vcc, exec, s[4:5]
	v_lshl_add_u64 v[136:137], v[166:167], 2, s[12:13]
	s_mov_b64 s[4:5], s[62:63]
	v_readlane_b32 s14, v238, 22
	v_readlane_b32 s15, v238, 23
	v_readlane_b32 s16, v238, 24
	v_readlane_b32 s17, v238, 25
	v_readlane_b32 s18, v238, 26
	v_readlane_b32 s19, v238, 27
	v_readlane_b32 s20, v238, 28
	v_readlane_b32 s21, v238, 29
	v_readlane_b32 s22, v238, 30
	v_readlane_b32 s23, v238, 31
	v_readlane_b32 s24, v238, 32
	v_readlane_b32 s25, v238, 33
	v_readlane_b32 s26, v238, 34
	v_readlane_b32 s27, v238, 35
	s_cbranch_vccnz .LBB0_570
	v_pk_mul_f32 v[126:127], v[126:127], v[178:179] op_sel_hi:[1,0]
	v_pk_mul_f32 v[128:129], v[124:125], v[178:179] op_sel_hi:[1,0]
	v_pk_mul_f32 v[124:125], v[126:127], v[126:127]
	v_pk_mul_f32 v[130:131], v[128:129], v[128:129]
	v_pk_mul_f32 v[116:117], v[116:117], v[178:179] op_sel_hi:[1,0]
	v_pk_mov_b32 v[132:133], v[130:131], v[124:125] op_sel:[1,0]
	v_mov_b32_e32 v131, v125
	v_pk_add_f32 v[124:125], v[132:133], v[130:131]
	v_pk_mul_f32 v[130:131], v[122:123], v[178:179] op_sel_hi:[1,0]
	v_pk_mul_f32 v[132:133], v[120:121], v[178:179] op_sel_hi:[1,0]
	v_pk_mul_f32 v[120:121], v[130:131], v[130:131]
	v_pk_mul_f32 v[122:123], v[132:133], v[132:133]
	v_pk_mul_f32 v[118:119], v[118:119], v[178:179] op_sel_hi:[1,0]
	v_pk_mov_b32 v[134:135], v[122:123], v[120:121] op_sel:[1,0]
	v_mov_b32_e32 v123, v121
	v_pk_add_f32 v[120:121], v[134:135], v[122:123]
	v_pk_add_f32 v[124:125], v[124:125], v[124:125] op_sel_hi:[0,1]
	v_pk_add_f32 v[134:135], v[120:121], v[120:121] op_sel_hi:[0,1]
	v_mul_f32_e32 v120, v116, v116
	v_pk_fma_f32 v[138:139], v[116:117], v[116:117], v[120:121] op_sel_hi:[1,1,0]
	v_mul_f32_e32 v120, v118, v118
	v_pk_fma_f32 v[140:141], v[118:119], v[118:119], v[120:121] op_sel_hi:[1,1,0]
	v_pk_mul_f32 v[120:121], v[114:115], v[178:179] op_sel_hi:[1,0]
	v_pk_mul_f32 v[122:123], v[112:113], v[178:179] op_sel_hi:[1,0]
	v_mul_f32_e32 v124, v120, v120
	v_mul_f32_e32 v138, v122, v122
	v_mul_f32_e32 v140, v123, v123
	v_mul_f32_e32 v134, v121, v121
	v_pk_add_f32 v[112:113], v[138:139], v[140:141]
	v_pk_add_f32 v[114:115], v[124:125], v[134:135]
	v_mad_i64_i32 v[176:177], s[4:5], v170, s78, 0
	v_pk_add_f32 v[112:113], v[112:113], v[114:115]
	v_and_b32_e32 v114, 64, v188
	v_add_f32_e32 v112, v112, v113
	v_xor_b32_e32 v113, 16, v188
	v_add_u32_e32 v114, 64, v114
	v_cmp_lt_i32_e32 vcc, v113, v114
	s_mov_b64 s[10:11], 64
	s_nop 0
	v_cndmask_b32_e32 v113, v188, v113, vcc
	v_lshlrev_b32_e32 v113, 2, v113
	ds_bpermute_b32 v113, v113, v112
	s_waitcnt lgkmcnt(0)
	v_add_f32_e32 v112, v112, v113
	v_xor_b32_e32 v113, 32, v188
	v_cmp_lt_i32_e32 vcc, v113, v114
	s_nop 1
	v_cndmask_b32_e32 v113, v188, v113, vcc
	v_lshlrev_b32_e32 v113, 2, v113
	ds_bpermute_b32 v113, v113, v112
	s_waitcnt lgkmcnt(0)
	v_add_f32_e32 v112, v112, v113
	v_fmamk_f32 v112, v112, 0x3c800000, v187
	v_cmp_gt_f32_e32 vcc, s45, v112
	v_mul_f32_e32 v113, 0x4b800000, v112
	s_nop 0
	v_cndmask_b32_e32 v112, v112, v113, vcc
	v_rsq_f32_e32 v112, v112
	s_nop 0
	v_mul_f32_e32 v113, 0x45800000, v112
	v_cndmask_b32_e32 v112, v112, v113, vcc
	v_mul_f32_e32 v124, 0x3e16c740, v112
	v_pk_mul_f32 v[126:127], v[126:127], v[124:125] op_sel_hi:[1,0]
	v_pk_mul_f32 v[132:133], v[132:133], v[124:125] op_sel_hi:[1,0]
	v_pk_mul_f32 v[130:131], v[130:131], v[124:125] op_sel_hi:[1,0]
	v_pk_mul_f32 v[128:129], v[128:129], v[124:125] op_sel_hi:[1,0]
	v_pk_mul_f32 v[116:117], v[116:117], v[124:125] op_sel_hi:[1,0]
	v_pk_mul_f32 v[118:119], v[118:119], v[124:125] op_sel_hi:[1,0]
	v_pk_mul_f32 v[122:123], v[122:123], v[124:125] op_sel_hi:[1,0]
	v_pk_mul_f32 v[120:121], v[120:121], v[124:125] op_sel_hi:[1,0]
	v_pk_mul_f32 v[130:131], v[218:219], v[130:131]
	v_pk_mul_f32 v[126:127], v[214:215], v[126:127]
	v_pk_mul_f32 v[114:115], v[216:217], v[132:133]
	v_cvt_pk_bf16_f32 v113, v126, v127
	v_mov_b64_e32 v[126:127], s[42:43]
	v_mad_i64_i32 v[126:127], s[4:5], v170, s78, v[126:127]
	v_lshl_add_u64 v[126:127], s[82:83], 1, v[126:127]
	v_lshl_add_u64 v[126:127], v[166:167], 1, v[126:127]
	v_pk_mul_f32 v[128:129], v[212:213], v[128:129]
	v_cvt_pk_bf16_f32 v114, v114, v115
	v_cvt_pk_bf16_f32 v115, v130, v131
	s_mov_b64 s[4:5], s[82:83]
	v_cvt_pk_bf16_f32 v112, v128, v129
	global_store_dwordx4 v[126:127], v[112:115], off
	s_nop 1
	v_pk_mul_f32 v[114:115], v[226:227], v[120:121]
	v_pk_mul_f32 v[118:119], v[222:223], v[118:119]
	v_pk_mul_f32 v[116:117], v[220:221], v[116:117]
	v_pk_mul_f32 v[112:113], v[224:225], v[122:123]
	v_cvt_pk_bf16_f32 v128, v116, v117
	v_cvt_pk_bf16_f32 v129, v118, v119
	v_cvt_pk_bf16_f32 v131, v114, v115
	s_nop 0
	v_cvt_pk_bf16_f32 v130, v112, v113
;     __device__ __forceinline__ void epi(Acc& acc, const Unit& u, int wr, int wc, int fr, int fq) const {
;     ...
;             for (int m = 0; m < 4; ++m) { const int row = u.pm * 256 + ai * 128 + rl0 + m * 16;
;                 const f32x4 q0 = *(const f32x4*)(SSQ + (size_t)row * 8), q1 = *(const f32x4*)(SSQ + (size_t)row * 8 + 4);
;                 const float rq = rsqrtf((((q0[0] + q0[1]) + (q0[2] + q0[3])) + ((q1[0] + q1[1]) + (q1[2] + q1[3]))) * (1.f / 384.f) + EPS);
.LBB0_570:
	v_add_u32_e32 v112, 16, v189
	v_and_b32_e32 v122, 63, v112
	v_lshl_add_u64 v[112:113], s[42:43], 0, v[176:177]
	v_lshl_add_u64 v[112:113], s[4:5], 1, v[112:113]
	v_lshl_add_u64 v[112:113], v[112:113], 0, s[10:11]
	v_add_u32_e32 v138, 16, v170
	v_lshl_add_u64 v[112:113], v[166:167], 1, v[112:113]
	v_ashrrev_i32_e32 v139, 31, v138
	global_store_dwordx4 v[112:113], v[128:131], off
	v_lshlrev_b64 v[112:113], 5, v[138:139]
	v_lshl_add_u64 v[116:117], s[68:69], 0, v[112:113]
	v_readlane_b32 s16, v238, 55
	v_readlane_b32 s18, v238, 57
	s_mov_b64 s[10:11], -1
	v_or_b32_e32 v139, 0x800, v122
	v_readlane_b32 s17, v238, 56
	v_readlane_b32 s19, v238, 58
	s_mov_b64 s[14:15], s[36:37]
	s_waitcnt vmcnt(2)
	v_mov_b64_e32 v[112:113], v[230:231]
	v_mov_b64_e32 v[114:115], v[232:233]
	v_mov_b64_e32 v[116:117], v[234:235]
	v_mov_b64_e32 v[118:119], v[236:237]
	v_add_u32_e32 v228, 0x20, v170
	v_ashrrev_i32_e32 v229, 31, v228
	v_lshlrev_b64 v[228:229], 5, v[228:229]
	v_lshl_add_u64 v[228:229], s[68:69], 0, v[228:229]
	global_load_dwordx4 v[230:233], v[228:229], off
	global_load_dwordx4 v[234:237], v[228:229], off offset:16
	v_mov_b32_e32 v120, v112
	v_mov_b32_e32 v121, v116
	v_mov_b32_e32 v116, v113
	v_pk_add_f32 v[112:113], v[120:121], v[116:117]
	v_mov_b32_e32 v116, v114
	v_mov_b32_e32 v117, v118
	v_mov_b32_e32 v118, v115
	v_pk_add_f32 v[114:115], v[116:117], v[118:119]
	s_nop 0
	v_pk_add_f32 v[112:113], v[112:113], v[114:115]
	s_nop 0
	v_add_f32_e32 v112, v112, v113
	v_fmamk_f32 v112, v112, 0x3b2aaaab, v187
	v_cmp_gt_f32_e32 vcc, s45, v112
	v_mul_f32_e32 v113, 0x4b800000, v112
	s_nop 0
	v_cndmask_b32_e32 v112, v112, v113, vcc
	v_rsq_f32_e32 v112, v112
	s_nop 0
	v_mul_f32_e32 v113, 0x45800000, v112
	v_cndmask_b32_e32 v142, v112, v113, vcc
	v_cndmask_b32_e64 v112, 0, 1, s[8:9]
	v_cmp_ne_u32_e64 s[4:5], 1, v112
	s_andn2_b64 vcc, exec, s[8:9]
	s_cbranch_vccnz .LBB0_572
	s_movk_i32 s8, 0x7ff0
	v_cmp_gt_i32_e32 vcc, s8, v170
	v_and_b32_e32 v112, 0xfff, v138
	v_mov_b32_e32 v173, v161
	v_cndmask_b32_e32 v112, v139, v112, vcc
	v_lshlrev_b32_e32 v160, 7, v112
	v_lshl_add_u64 v[112:113], s[76:77], 0, v[160:161]
	v_lshl_add_u64 v[120:121], v[112:113], 0, v[172:173]
	global_load_dwordx4 v[116:119], v[120:121], off offset:16
	global_load_dwordx4 v[124:127], v[120:121], off
	global_load_dwordx4 v[112:115], v[120:121], off offset:80
	s_nop 0
	global_load_dwordx4 v[120:123], v[120:121], off offset:64
	s_nop 0
	global_load_dwordx4 v[128:131], v[174:175], off offset:16
	global_load_dwordx4 v[132:135], v[174:175], off
	v_and_b32_e32 v141, 64, v188
	v_xor_b32_e32 v140, 16, v188
	v_add_u32_e32 v141, 64, v141
	v_cmp_lt_i32_e32 vcc, v140, v141
	s_mov_b64 s[10:11], 0
	s_nop 0
	v_cndmask_b32_e32 v140, v188, v140, vcc
	v_lshlrev_b32_e32 v146, 2, v140
	v_xor_b32_e32 v140, 32, v188
	v_cmp_lt_i32_e32 vcc, v140, v141
	s_nop 1
	v_cndmask_b32_e32 v140, v188, v140, vcc
	v_lshlrev_b32_e32 v143, 2, v140
	v_pk_mul_f32 v[144:145], v[110:111], v[142:143] op_sel_hi:[1,0]
	v_pk_mul_f32 v[148:149], v[108:109], v[142:143] op_sel_hi:[1,0]
	v_pk_mul_f32 v[180:181], v[144:145], v[144:145]
	v_pk_mul_f32 v[192:193], v[148:149], v[148:149]
	v_pk_mul_f32 v[150:151], v[106:107], v[142:143] op_sel_hi:[1,0]
	v_pk_mul_f32 v[176:177], v[104:105], v[142:143] op_sel_hi:[1,0]
	v_pk_mov_b32 v[194:195], v[192:193], v[180:181] op_sel:[1,0]
	v_mov_b32_e32 v193, v181
	v_pk_add_f32 v[180:181], v[194:195], v[192:193]
	v_pk_mul_f32 v[192:193], v[150:151], v[150:151]
	v_pk_mul_f32 v[194:195], v[176:177], v[176:177]
	v_mov_b32_e32 v196, v192
	v_mov_b32_e32 v197, v194
	v_mov_b32_e32 v194, v193
	v_pk_add_f32 v[192:193], v[196:197], v[194:195]
	v_add_f32_e32 v147, v180, v181
	v_add_f32_e32 v147, v193, v147
	v_add_f32_e32 v147, v192, v147
	ds_bpermute_b32 v160, v146, v147
	v_mad_i64_i32 v[140:141], s[8:9], v138, s78, 0
	s_waitcnt lgkmcnt(0)
	v_add_f32_e32 v147, v147, v160
	ds_bpermute_b32 v160, v143, v147
	s_waitcnt lgkmcnt(0)
	v_add_f32_e32 v147, v147, v160
	v_fmamk_f32 v147, v147, 0x3d000000, v187
	v_cmp_gt_f32_e32 vcc, s45, v147
	v_mul_f32_e32 v160, 0x4b800000, v147
	s_nop 0
	v_cndmask_b32_e32 v147, v147, v160, vcc
	v_rsq_f32_e32 v147, v147
	s_nop 0
	v_mul_f32_e32 v160, 0x45800000, v147
	v_cndmask_b32_e32 v160, v147, v160, vcc
	v_pk_mul_f32 v[148:149], v[148:149], v[160:161] op_sel_hi:[1,0]
	v_pk_mul_f32 v[144:145], v[144:145], v[160:161] op_sel_hi:[1,0]
	v_pk_mul_f32 v[176:177], v[176:177], v[160:161] op_sel_hi:[1,0]
	v_pk_mul_f32 v[150:151], v[150:151], v[160:161] op_sel_hi:[1,0]
	s_waitcnt vmcnt(1)
	v_pk_mul_f32 v[176:177], v[128:129], v[176:177]
	s_waitcnt vmcnt(0)
	v_pk_mul_f32 v[148:149], v[132:133], v[148:149]
	v_pk_mul_f32 v[144:145], v[134:135], v[144:145]
	ds_bpermute_b32 v180, v143, v148
	ds_bpermute_b32 v181, v143, v149
	ds_bpermute_b32 v194, v143, v144
	ds_bpermute_b32 v195, v143, v145
	v_pk_mul_f32 v[150:151], v[130:131], v[150:151]
	ds_bpermute_b32 v192, v143, v176
	ds_bpermute_b32 v193, v143, v177
	ds_bpermute_b32 v196, v143, v150
	ds_bpermute_b32 v197, v143, v151
	v_pk_mul_f32 v[198:199], v[126:127], v[144:145]
	v_pk_mul_f32 v[144:145], v[124:125], v[148:149]
	s_waitcnt lgkmcnt(6)
	v_pk_mul_f32 v[180:181], v[120:121], v[180:181]
	s_waitcnt lgkmcnt(4)
	v_pk_mul_f32 v[148:149], v[122:123], v[194:195]
	v_pk_fma_f32 v[180:181], v[168:169], v[180:181], v[144:145]
	v_mov_b32_e32 v144, v168
	v_mov_b32_e32 v145, v168
	v_pk_fma_f32 v[148:149], v[144:145], v[148:149], v[198:199]
	v_pk_mul_f32 v[150:151], v[118:119], v[150:151]
	v_pk_mul_f32 v[194:195], v[148:149], s[52:53] op_sel_hi:[1,0]
	v_pk_mul_f32 v[148:149], v[180:181], s[52:53] op_sel_hi:[1,0]
	v_pk_mul_f32 v[176:177], v[116:117], v[176:177]
	s_waitcnt lgkmcnt(0)
; __device__ __forceinline__ unsigned cvt_pk_bf16(float lo, float hi) { unsigned r; asm("v_cvt_pk_bf16_f32 %0, %1, %2" : "=v"(r) : "v"(lo), "v"(hi)); return r; }
;     __device__ __forceinline__ void epi(Acc& acc, const Unit& u, int wr, int wc, int fr, int fq) const {
;     ...
;                     const int head = u.pn * 4 + wc; float s = 0.f; f32x4 v[2][2];
; #pragma unroll
;                     for (int bj = 0; bj < 2; ++bj)
; #pragma unroll
;                         for (int n = 0; n < 2; ++n) { v[bj][n] = acc[ai][bj][m][n] * rq; const f32x4 x = v[bj][n]; s += (x[0] * x[0] + x[1] * x[1]) + (x[2] * x[2] + x[3] * x[3]); }
;                     s += __shfl_xor(s, 16); s += __shfl_xor(s, 32);
;                     const float r2 = rsqrtf(s * (1.f / 64.f) + EPS) * QSCALE;
;     ...
;                     for (int bj = 0; bj < 2; ++bj) { const int head = bj * 4 + wc;
;                         f32x4 v0 = acc[ai][bj][m][0] * rq, v1 = acc[ai][bj][m][1] * rq;
;                         float s = (v0[0] * v0[0] + v0[1] * v0[1]) + (v0[2] * v0[2] + v0[3] * v0[3]) + (v1[0] * v1[0] + v1[1] * v1[1]) + (v1[2] * v1[2] + v1[3] * v1[3]);
;                         s += __shfl_xor(s, 16); s += __shfl_xor(s, 32);
;                         const float r2 = rsqrtf(s * (1.f / 32.f) + EPS);
;                         v0 = v0 * r2 * g0; v1 = v1 * r2 * g1;
;                         f32x4 p0, p1;
; #pragma unroll
;                         for (int e = 0; e < 4; ++e) { p0[e] = __shfl_xor(v0[e], 32); p1[e] = __shfl_xor(v1[e], 32); }
;                         const f32x4 r0 = (v0 * c0 + p0 * s0 * sg) * QSCALE, r1 = (v1 * c1 + p1 * s1 * sg) * QSCALE;
;                         u32x4 w; w.x = cvt_pk_bf16(r0[0], r0[1]); w.y = cvt_pk_bf16(r0[2], r0[3]); w.z = cvt_pk_bf16(r1[0], r1[1]); w.w = cvt_pk_bf16(r1[2], r1[3]);
;                         *(u32x4*)(Q + (size_t)row * 768 + head * 96 + 64 + fq * 8) = w; }
	v_pk_mul_f32 v[180:181], v[114:115], v[196:197]
	v_pk_mul_f32 v[192:193], v[112:113], v[192:193]
	v_pk_fma_f32 v[150:151], v[144:145], v[180:181], v[150:151]
	v_pk_fma_f32 v[176:177], v[168:169], v[192:193], v[176:177]
	v_pk_mul_f32 v[180:181], v[150:151], s[52:53] op_sel_hi:[1,0]
	v_pk_mul_f32 v[150:151], v[176:177], s[52:53] op_sel_hi:[1,0]
	v_mov_b64_e32 v[176:177], s[64:65]
	v_mad_i64_i32 v[176:177], s[8:9], v138, s78, v[176:177]
	v_cvt_pk_bf16_f32 v148, v148, v149
	v_cvt_pk_bf16_f32 v149, v194, v195
	v_cvt_pk_bf16_f32 v150, v150, v151
	v_cvt_pk_bf16_f32 v151, v180, v181
	v_lshl_add_u64 v[176:177], v[166:167], 1, v[176:177]
	global_store_dwordx4 v[176:177], v[148:151], off offset:128
	v_pk_mul_f32 v[176:177], v[98:99], v[142:143] op_sel_hi:[1,0]
	v_pk_mul_f32 v[180:181], v[96:97], v[142:143] op_sel_hi:[1,0]
	v_pk_mul_f32 v[148:149], v[102:103], v[142:143] op_sel_hi:[1,0]
	v_pk_mul_f32 v[150:151], v[100:101], v[142:143] op_sel_hi:[1,0]
	v_pk_mul_f32 v[192:193], v[148:149], v[148:149]
	v_pk_mul_f32 v[194:195], v[150:151], v[150:151]
	s_nop 0
	v_pk_mov_b32 v[196:197], v[194:195], v[192:193] op_sel:[1,0]
	v_mov_b32_e32 v195, v193
	v_pk_add_f32 v[192:193], v[196:197], v[194:195]
	v_pk_mul_f32 v[194:195], v[176:177], v[176:177]
	v_pk_mul_f32 v[196:197], v[180:181], v[180:181]
	v_mov_b32_e32 v198, v194
	v_mov_b32_e32 v199, v196
	v_mov_b32_e32 v196, v195
	v_pk_add_f32 v[194:195], v[198:199], v[196:197]
	v_add_f32_e32 v147, v192, v193
	v_add_f32_e32 v147, v195, v147
	v_add_f32_e32 v147, v194, v147
	ds_bpermute_b32 v146, v146, v147
	s_waitcnt lgkmcnt(0)
	v_add_f32_e32 v146, v147, v146
	ds_bpermute_b32 v147, v143, v146
	s_waitcnt lgkmcnt(0)
	v_add_f32_e32 v146, v146, v147
	v_fmamk_f32 v146, v146, 0x3d000000, v187
	v_cmp_gt_f32_e32 vcc, s45, v146
	v_mul_f32_e32 v147, 0x4b800000, v146
	s_nop 0
	v_cndmask_b32_e32 v146, v146, v147, vcc
	v_rsq_f32_e32 v146, v146
	s_nop 0
	v_mul_f32_e32 v147, 0x45800000, v146
	v_cndmask_b32_e32 v146, v146, v147, vcc
	v_pk_mul_f32 v[148:149], v[148:149], v[146:147] op_sel_hi:[1,0]
	v_pk_mul_f32 v[150:151], v[150:151], v[146:147] op_sel_hi:[1,0]
	v_pk_mul_f32 v[134:135], v[134:135], v[148:149]
	v_pk_mul_f32 v[148:149], v[180:181], v[146:147] op_sel_hi:[1,0]
	v_pk_mul_f32 v[146:147], v[176:177], v[146:147] op_sel_hi:[1,0]
	v_pk_mul_f32 v[128:129], v[128:129], v[148:149]
	v_pk_mul_f32 v[130:131], v[130:131], v[146:147]
	v_pk_mul_f32 v[132:133], v[132:133], v[150:151]
	ds_bpermute_b32 v148, v143, v128
	ds_bpermute_b32 v149, v143, v129
	ds_bpermute_b32 v176, v143, v130
	ds_bpermute_b32 v177, v143, v131
	ds_bpermute_b32 v146, v143, v132
	ds_bpermute_b32 v147, v143, v133
	ds_bpermute_b32 v150, v143, v134
	ds_bpermute_b32 v151, v143, v135
	v_pk_mul_f32 v[118:119], v[118:119], v[130:131]
	v_pk_mul_f32 v[116:117], v[116:117], v[128:129]
	s_waitcnt lgkmcnt(4)
	v_pk_mul_f32 v[114:115], v[114:115], v[176:177]
	v_pk_mul_f32 v[112:113], v[112:113], v[148:149]
	v_pk_mul_f32 v[126:127], v[126:127], v[134:135]
	v_pk_mul_f32 v[124:125], v[124:125], v[132:133]
	s_waitcnt lgkmcnt(0)
	v_pk_mul_f32 v[122:123], v[122:123], v[150:151]
	v_pk_mul_f32 v[120:121], v[120:121], v[146:147]
	v_pk_fma_f32 v[112:113], v[168:169], v[112:113], v[116:117]
	v_pk_fma_f32 v[114:115], v[144:145], v[114:115], v[118:119]
	v_pk_fma_f32 v[120:121], v[168:169], v[120:121], v[124:125]
	v_pk_fma_f32 v[122:123], v[144:145], v[122:123], v[126:127]
	v_pk_mul_f32 v[116:117], v[114:115], s[52:53] op_sel_hi:[1,0]
	v_pk_mul_f32 v[114:115], v[112:113], s[52:53] op_sel_hi:[1,0]
	v_pk_mul_f32 v[122:123], v[122:123], s[52:53] op_sel_hi:[1,0]
	v_pk_mul_f32 v[120:121], v[120:121], s[52:53] op_sel_hi:[1,0]
	v_cvt_pk_bf16_f32 v113, v122, v123
	v_cvt_pk_bf16_f32 v114, v114, v115
	v_cvt_pk_bf16_f32 v115, v116, v117
	s_nop 0
	v_cvt_pk_bf16_f32 v112, v120, v121
.LBB0_572:
	s_mov_b64 s[8:9], 0x380
	s_andn2_b64 vcc, exec, s[10:11]
	s_mov_b64 s[10:11], s[62:63]
	s_cbranch_vccnz .LBB0_574
	v_pk_mul_f32 v[110:111], v[110:111], v[142:143] op_sel_hi:[1,0]
	v_pk_mul_f32 v[112:113], v[108:109], v[142:143] op_sel_hi:[1,0]
	v_pk_mul_f32 v[108:109], v[110:111], v[110:111]
	v_pk_mul_f32 v[114:115], v[112:113], v[112:113]
	v_pk_mul_f32 v[100:101], v[100:101], v[142:143] op_sel_hi:[1,0]
	v_pk_mov_b32 v[116:117], v[114:115], v[108:109] op_sel:[1,0]
	v_mov_b32_e32 v115, v109
	v_pk_add_f32 v[108:109], v[116:117], v[114:115]
	v_pk_mul_f32 v[114:115], v[106:107], v[142:143] op_sel_hi:[1,0]
	v_pk_mul_f32 v[116:117], v[104:105], v[142:143] op_sel_hi:[1,0]
	v_pk_mul_f32 v[104:105], v[114:115], v[114:115]
	v_pk_mul_f32 v[106:107], v[116:117], v[116:117]
	v_pk_mul_f32 v[102:103], v[102:103], v[142:143] op_sel_hi:[1,0]
	v_pk_mov_b32 v[118:119], v[106:107], v[104:105] op_sel:[1,0]
	v_mov_b32_e32 v107, v105
	v_pk_add_f32 v[104:105], v[118:119], v[106:107]
	v_pk_add_f32 v[108:109], v[108:109], v[108:109] op_sel_hi:[0,1]
	v_pk_add_f32 v[118:119], v[104:105], v[104:105] op_sel_hi:[0,1]
	v_mul_f32_e32 v104, v100, v100
	v_pk_fma_f32 v[120:121], v[100:101], v[100:101], v[104:105] op_sel_hi:[1,1,0]
	v_mul_f32_e32 v104, v102, v102
	v_pk_fma_f32 v[122:123], v[102:103], v[102:103], v[104:105] op_sel_hi:[1,1,0]
	v_pk_mul_f32 v[104:105], v[98:99], v[142:143] op_sel_hi:[1,0]
	v_pk_mul_f32 v[106:107], v[96:97], v[142:143] op_sel_hi:[1,0]
	v_mul_f32_e32 v108, v104, v104
	v_mul_f32_e32 v120, v106, v106
	v_mul_f32_e32 v122, v107, v107
	v_mul_f32_e32 v118, v105, v105
	v_pk_add_f32 v[96:97], v[120:121], v[122:123]
	v_pk_add_f32 v[98:99], v[108:109], v[118:119]
	v_mad_i64_i32 v[140:141], s[8:9], v138, s78, 0
	v_pk_add_f32 v[96:97], v[96:97], v[98:99]
	v_and_b32_e32 v98, 64, v188
	v_add_f32_e32 v96, v96, v97
	v_xor_b32_e32 v97, 16, v188
	v_add_u32_e32 v98, 64, v98
	v_cmp_lt_i32_e32 vcc, v97, v98
	s_mov_b64 s[10:11], s[82:83]
	s_nop 0
	v_cndmask_b32_e32 v97, v188, v97, vcc
	v_lshlrev_b32_e32 v97, 2, v97
	ds_bpermute_b32 v97, v97, v96
	s_waitcnt lgkmcnt(0)
; __device__ __forceinline__ unsigned cvt_pk_bf16(float lo, float hi) { unsigned r; asm("v_cvt_pk_bf16_f32 %0, %1, %2" : "=v"(r) : "v"(lo), "v"(hi)); return r; }
;     __device__ __forceinline__ void epi(Acc& acc, const Unit& u, int wr, int wc, int fr, int fq) const {
;     ...
;             for (int m = 0; m < 4; ++m) { const int row = u.pm * 256 + ai * 128 + rl0 + m * 16;
;                 const f32x4 q0 = *(const f32x4*)(SSQ + (size_t)row * 8), q1 = *(const f32x4*)(SSQ + (size_t)row * 8 + 4);
;                 const float rq = rsqrtf((((q0[0] + q0[1]) + (q0[2] + q0[3])) + ((q1[0] + q1[1]) + (q1[2] + q1[3]))) * (1.f / 384.f) + EPS);
;     ...
;                     const float r2 = rsqrtf(s * (1.f / 64.f) + EPS) * QSCALE;
; #pragma unroll
;                     for (int bj = 0; bj < 2; ++bj) { const f32x4 g0 = *(const f32x4*)(qng + bj * 32 + fq * 8), g1 = *(const f32x4*)(qng + bj * 32 + fq * 8 + 4);
;                         const f32x4 a = v[bj][0] * r2 * g0, b = v[bj][1] * r2 * g1;
;                         u32x4 w; w.x = cvt_pk_bf16(a[0], a[1]); w.y = cvt_pk_bf16(a[2], a[3]); w.z = cvt_pk_bf16(b[0], b[1]); w.w = cvt_pk_bf16(b[2], b[3]);
;                         *(u32x4*)(Q + (size_t)row * 768 + head * 96 + bj * 32 + fq * 8) = w; }
	v_add_f32_e32 v96, v96, v97
	v_xor_b32_e32 v97, 32, v188
	v_cmp_lt_i32_e32 vcc, v97, v98
	s_nop 1
	v_cndmask_b32_e32 v97, v188, v97, vcc
	v_lshlrev_b32_e32 v97, 2, v97
	ds_bpermute_b32 v97, v97, v96
	s_waitcnt lgkmcnt(0)
	v_add_f32_e32 v96, v96, v97
	v_fmamk_f32 v96, v96, 0x3c800000, v187
	v_cmp_gt_f32_e32 vcc, s45, v96
	v_mul_f32_e32 v97, 0x4b800000, v96
	s_nop 0
	v_cndmask_b32_e32 v96, v96, v97, vcc
	v_rsq_f32_e32 v96, v96
	s_nop 0
	v_mul_f32_e32 v97, 0x45800000, v96
	v_cndmask_b32_e32 v96, v96, v97, vcc
	v_mul_f32_e32 v108, 0x3e16c740, v96
	v_pk_mul_f32 v[110:111], v[110:111], v[108:109] op_sel_hi:[1,0]
	v_pk_mul_f32 v[116:117], v[116:117], v[108:109] op_sel_hi:[1,0]
	v_pk_mul_f32 v[114:115], v[114:115], v[108:109] op_sel_hi:[1,0]
	v_pk_mul_f32 v[112:113], v[112:113], v[108:109] op_sel_hi:[1,0]
	v_pk_mul_f32 v[100:101], v[100:101], v[108:109] op_sel_hi:[1,0]
	v_pk_mul_f32 v[102:103], v[102:103], v[108:109] op_sel_hi:[1,0]
	v_pk_mul_f32 v[106:107], v[106:107], v[108:109] op_sel_hi:[1,0]
	v_pk_mul_f32 v[104:105], v[104:105], v[108:109] op_sel_hi:[1,0]
	v_pk_mul_f32 v[114:115], v[218:219], v[114:115]
	v_pk_mul_f32 v[110:111], v[214:215], v[110:111]
	v_pk_mul_f32 v[98:99], v[216:217], v[116:117]
	v_cvt_pk_bf16_f32 v97, v110, v111
	v_mov_b64_e32 v[110:111], s[42:43]
	v_mad_i64_i32 v[110:111], s[8:9], v138, s78, v[110:111]
	v_lshl_add_u64 v[110:111], s[82:83], 1, v[110:111]
	v_lshl_add_u64 v[110:111], v[166:167], 1, v[110:111]
	v_pk_mul_f32 v[112:113], v[212:213], v[112:113]
	v_cvt_pk_bf16_f32 v98, v98, v99
	v_cvt_pk_bf16_f32 v99, v114, v115
	s_mov_b64 s[8:9], 64
	v_cvt_pk_bf16_f32 v96, v112, v113
	global_store_dwordx4 v[110:111], v[96:99], off
	s_nop 1
	v_pk_mul_f32 v[98:99], v[226:227], v[104:105]
	v_pk_mul_f32 v[102:103], v[222:223], v[102:103]
	v_pk_mul_f32 v[100:101], v[220:221], v[100:101]
	v_pk_mul_f32 v[96:97], v[224:225], v[106:107]
	v_cvt_pk_bf16_f32 v112, v100, v101
	v_cvt_pk_bf16_f32 v113, v102, v103
	v_cvt_pk_bf16_f32 v115, v98, v99
	s_nop 0
	v_cvt_pk_bf16_f32 v114, v96, v97
.LBB0_574:
	v_lshl_add_u64 v[96:97], s[42:43], 0, v[140:141]
	v_lshl_add_u64 v[96:97], s[10:11], 1, v[96:97]
	v_lshl_add_u64 v[96:97], v[96:97], 0, s[8:9]
	v_add_u32_e32 v120, 32, v170
	v_lshl_add_u64 v[96:97], v[166:167], 1, v[96:97]
	v_ashrrev_i32_e32 v121, 31, v120
	global_store_dwordx4 v[96:97], v[112:115], off
	v_lshlrev_b64 v[96:97], 5, v[120:121]
	v_lshl_add_u64 v[100:101], s[68:69], 0, v[96:97]
	s_mov_b64 s[10:11], -1
	s_and_b64 vcc, exec, s[4:5]
	s_waitcnt vmcnt(2)
	v_mov_b64_e32 v[96:97], v[230:231]
	v_mov_b64_e32 v[98:99], v[232:233]
	v_mov_b64_e32 v[100:101], v[234:235]
	v_mov_b64_e32 v[102:103], v[236:237]
	v_add_u32_e32 v228, 0x30, v170
	v_ashrrev_i32_e32 v229, 31, v228
	v_lshlrev_b64 v[228:229], 5, v[228:229]
	v_lshl_add_u64 v[228:229], s[68:69], 0, v[228:229]
	global_load_dwordx4 v[230:233], v[228:229], off
	global_load_dwordx4 v[234:237], v[228:229], off offset:16
	v_mov_b32_e32 v104, v96
	v_mov_b32_e32 v105, v100
	v_mov_b32_e32 v100, v97
	v_mov_b32_e32 v96, v98
	v_mov_b32_e32 v97, v102
	v_mov_b32_e32 v102, v99
	v_pk_add_f32 v[98:99], v[104:105], v[100:101]
	v_pk_add_f32 v[96:97], v[96:97], v[102:103]
	s_nop 0
	v_pk_add_f32 v[96:97], v[98:99], v[96:97]
	s_nop 0
	v_add_f32_e32 v96, v96, v97
	v_fmamk_f32 v96, v96, 0x3b2aaaab, v187
	v_mul_f32_e32 v97, 0x4b800000, v96
	v_cmp_gt_f32_e64 s[8:9], s45, v96
	s_nop 1
	v_cndmask_b32_e64 v96, v96, v97, s[8:9]
	v_rsq_f32_e32 v96, v96
	v_xor_b32_e32 v97, 32, v190
	v_or_b32_e32 v121, 0x800, v97
	v_mul_f32_e32 v98, 0x45800000, v96
	v_cndmask_b32_e64 v124, v96, v98, s[8:9]
	s_cbranch_vccnz .LBB0_576
	s_movk_i32 s8, 0x7fe0
	v_cmp_gt_i32_e32 vcc, s8, v170
	v_and_b32_e32 v96, 0xfff, v120
	v_mov_b32_e32 v173, v161
	v_cndmask_b32_e32 v96, v121, v96, vcc
	v_lshlrev_b32_e32 v160, 7, v96
	v_lshl_add_u64 v[96:97], s[76:77], 0, v[160:161]
	v_lshl_add_u64 v[104:105], v[96:97], 0, v[172:173]
	global_load_dwordx4 v[100:103], v[104:105], off offset:16
	global_load_dwordx4 v[108:111], v[104:105], off
	global_load_dwordx4 v[96:99], v[104:105], off offset:80
	s_nop 0
	global_load_dwordx4 v[104:107], v[104:105], off offset:64
	s_nop 0
	global_load_dwordx4 v[112:115], v[174:175], off offset:16
	global_load_dwordx4 v[116:119], v[174:175], off
	v_and_b32_e32 v123, 64, v188
	v_xor_b32_e32 v122, 16, v188
	v_add_u32_e32 v123, 64, v123
	v_cmp_lt_i32_e32 vcc, v122, v123
	s_mov_b64 s[10:11], 0
	s_nop 0
	v_cndmask_b32_e32 v122, v188, v122, vcc
	v_lshlrev_b32_e32 v128, 2, v122
	v_xor_b32_e32 v122, 32, v188
	v_cmp_lt_i32_e32 vcc, v122, v123
	s_nop 1
	v_cndmask_b32_e32 v122, v188, v122, vcc
	v_lshlrev_b32_e32 v125, 2, v122
	v_pk_mul_f32 v[126:127], v[94:95], v[124:125] op_sel_hi:[1,0]
	v_pk_mul_f32 v[130:131], v[92:93], v[124:125] op_sel_hi:[1,0]
	v_pk_mul_f32 v[140:141], v[126:127], v[126:127]
	v_pk_mul_f32 v[142:143], v[130:131], v[130:131]
	v_pk_mul_f32 v[132:133], v[90:91], v[124:125] op_sel_hi:[1,0]
	v_pk_mul_f32 v[134:135], v[88:89], v[124:125] op_sel_hi:[1,0]
	v_pk_mov_b32 v[144:145], v[142:143], v[140:141] op_sel:[1,0]
	v_mov_b32_e32 v143, v141
	v_pk_add_f32 v[140:141], v[144:145], v[142:143]
	v_pk_mul_f32 v[142:143], v[132:133], v[132:133]
	v_pk_mul_f32 v[144:145], v[134:135], v[134:135]
	v_mov_b32_e32 v146, v142
	v_mov_b32_e32 v147, v144
	v_mov_b32_e32 v144, v143
	v_pk_add_f32 v[142:143], v[146:147], v[144:145]
	v_add_f32_e32 v129, v140, v141
	v_add_f32_e32 v129, v143, v129
	v_add_f32_e32 v129, v142, v129
	ds_bpermute_b32 v138, v128, v129
	v_mad_i64_i32 v[122:123], s[8:9], v120, s78, 0
	s_waitcnt lgkmcnt(0)
	v_add_f32_e32 v129, v129, v138
	ds_bpermute_b32 v138, v125, v129
	s_waitcnt lgkmcnt(0)
; __device__ __forceinline__ unsigned cvt_pk_bf16(float lo, float hi) { unsigned r; asm("v_cvt_pk_bf16_f32 %0, %1, %2" : "=v"(r) : "v"(lo), "v"(hi)); return r; }
;     __device__ __forceinline__ void epi(Acc& acc, const Unit& u, int wr, int wc, int fr, int fq) const {
;     ...
;                     for (int bj = 0; bj < 2; ++bj) { const int head = bj * 4 + wc;
;                         f32x4 v0 = acc[ai][bj][m][0] * rq, v1 = acc[ai][bj][m][1] * rq;
;                         float s = (v0[0] * v0[0] + v0[1] * v0[1]) + (v0[2] * v0[2] + v0[3] * v0[3]) + (v1[0] * v1[0] + v1[1] * v1[1]) + (v1[2] * v1[2] + v1[3] * v1[3]);
;                         s += __shfl_xor(s, 16); s += __shfl_xor(s, 32);
;                         const float r2 = rsqrtf(s * (1.f / 32.f) + EPS);
;                         v0 = v0 * r2 * g0; v1 = v1 * r2 * g1;
;                         f32x4 p0, p1;
; #pragma unroll
;                         for (int e = 0; e < 4; ++e) { p0[e] = __shfl_xor(v0[e], 32); p1[e] = __shfl_xor(v1[e], 32); }
;                         const f32x4 r0 = (v0 * c0 + p0 * s0 * sg) * QSCALE, r1 = (v1 * c1 + p1 * s1 * sg) * QSCALE;
;                         u32x4 w; w.x = cvt_pk_bf16(r0[0], r0[1]); w.y = cvt_pk_bf16(r0[2], r0[3]); w.z = cvt_pk_bf16(r1[0], r1[1]); w.w = cvt_pk_bf16(r1[2], r1[3]);
;                         *(u32x4*)(Q + (size_t)row * 768 + head * 96 + 64 + fq * 8) = w; }
	v_add_f32_e32 v129, v129, v138
	v_fmamk_f32 v129, v129, 0x3d000000, v187
	v_cmp_gt_f32_e32 vcc, s45, v129
	v_mul_f32_e32 v138, 0x4b800000, v129
	s_nop 0
	v_cndmask_b32_e32 v129, v129, v138, vcc
	v_rsq_f32_e32 v129, v129
	s_nop 0
	v_mul_f32_e32 v138, 0x45800000, v129
	v_cndmask_b32_e32 v138, v129, v138, vcc
	v_pk_mul_f32 v[130:131], v[130:131], v[138:139] op_sel_hi:[1,0]
	v_pk_mul_f32 v[126:127], v[126:127], v[138:139] op_sel_hi:[1,0]
	v_pk_mul_f32 v[134:135], v[134:135], v[138:139] op_sel_hi:[1,0]
	v_pk_mul_f32 v[132:133], v[132:133], v[138:139] op_sel_hi:[1,0]
	s_waitcnt vmcnt(1)
	v_pk_mul_f32 v[134:135], v[112:113], v[134:135]
	s_waitcnt vmcnt(0)
	v_pk_mul_f32 v[130:131], v[116:117], v[130:131]
	v_pk_mul_f32 v[126:127], v[118:119], v[126:127]
	ds_bpermute_b32 v140, v125, v130
	ds_bpermute_b32 v141, v125, v131
	ds_bpermute_b32 v144, v125, v126
	ds_bpermute_b32 v145, v125, v127
	v_pk_mul_f32 v[132:133], v[114:115], v[132:133]
	ds_bpermute_b32 v142, v125, v134
	ds_bpermute_b32 v143, v125, v135
	ds_bpermute_b32 v146, v125, v132
	ds_bpermute_b32 v147, v125, v133
	v_pk_mul_f32 v[148:149], v[110:111], v[126:127]
	v_pk_mul_f32 v[126:127], v[108:109], v[130:131]
	s_waitcnt lgkmcnt(6)
	v_pk_mul_f32 v[140:141], v[104:105], v[140:141]
	s_waitcnt lgkmcnt(4)
	v_pk_mul_f32 v[130:131], v[106:107], v[144:145]
	v_pk_fma_f32 v[140:141], v[168:169], v[140:141], v[126:127]
	v_mov_b32_e32 v126, v168
	v_mov_b32_e32 v127, v168
	v_pk_fma_f32 v[130:131], v[126:127], v[130:131], v[148:149]
	v_pk_mul_f32 v[132:133], v[102:103], v[132:133]
	v_pk_mul_f32 v[144:145], v[130:131], s[52:53] op_sel_hi:[1,0]
	v_pk_mul_f32 v[130:131], v[140:141], s[52:53] op_sel_hi:[1,0]
	v_pk_mul_f32 v[134:135], v[100:101], v[134:135]
	s_waitcnt lgkmcnt(0)
	v_pk_mul_f32 v[140:141], v[98:99], v[146:147]
	v_pk_mul_f32 v[142:143], v[96:97], v[142:143]
	v_pk_fma_f32 v[132:133], v[126:127], v[140:141], v[132:133]
	v_pk_fma_f32 v[134:135], v[168:169], v[142:143], v[134:135]
	v_pk_mul_f32 v[140:141], v[132:133], s[52:53] op_sel_hi:[1,0]
	v_pk_mul_f32 v[132:133], v[134:135], s[52:53] op_sel_hi:[1,0]
	v_mov_b64_e32 v[134:135], s[64:65]
	v_mad_i64_i32 v[134:135], s[8:9], v120, s78, v[134:135]
	v_cvt_pk_bf16_f32 v130, v130, v131
	v_cvt_pk_bf16_f32 v131, v144, v145
	v_cvt_pk_bf16_f32 v132, v132, v133
	v_cvt_pk_bf16_f32 v133, v140, v141
	v_lshl_add_u64 v[134:135], v[166:167], 1, v[134:135]
	global_store_dwordx4 v[134:135], v[130:133], off offset:128
	v_pk_mul_f32 v[134:135], v[82:83], v[124:125] op_sel_hi:[1,0]
	v_pk_mul_f32 v[140:141], v[80:81], v[124:125] op_sel_hi:[1,0]
	v_pk_mul_f32 v[130:131], v[86:87], v[124:125] op_sel_hi:[1,0]
	v_pk_mul_f32 v[132:133], v[84:85], v[124:125] op_sel_hi:[1,0]
	v_pk_mul_f32 v[142:143], v[130:131], v[130:131]
	v_pk_mul_f32 v[144:145], v[132:133], v[132:133]
	s_nop 0
	v_pk_mov_b32 v[146:147], v[144:145], v[142:143] op_sel:[1,0]
	v_mov_b32_e32 v145, v143
	v_pk_add_f32 v[142:143], v[146:147], v[144:145]
	v_pk_mul_f32 v[144:145], v[134:135], v[134:135]
	v_pk_mul_f32 v[146:147], v[140:141], v[140:141]
	v_mov_b32_e32 v148, v144
	v_mov_b32_e32 v149, v146
	v_mov_b32_e32 v146, v145
	v_pk_add_f32 v[144:145], v[148:149], v[146:147]
	v_add_f32_e32 v129, v142, v143
	v_add_f32_e32 v129, v145, v129
	v_add_f32_e32 v129, v144, v129
	ds_bpermute_b32 v128, v128, v129
	s_waitcnt lgkmcnt(0)
	v_add_f32_e32 v128, v129, v128
	ds_bpermute_b32 v129, v125, v128
	s_waitcnt lgkmcnt(0)
	v_add_f32_e32 v128, v128, v129
	v_fmamk_f32 v128, v128, 0x3d000000, v187
	v_cmp_gt_f32_e32 vcc, s45, v128
	v_mul_f32_e32 v129, 0x4b800000, v128
	s_nop 0
	v_cndmask_b32_e32 v128, v128, v129, vcc
	v_rsq_f32_e32 v128, v128
	s_nop 0
	v_mul_f32_e32 v129, 0x45800000, v128
	v_cndmask_b32_e32 v128, v128, v129, vcc
	v_pk_mul_f32 v[130:131], v[130:131], v[128:129] op_sel_hi:[1,0]
	v_pk_mul_f32 v[132:133], v[132:133], v[128:129] op_sel_hi:[1,0]
	v_pk_mul_f32 v[118:119], v[118:119], v[130:131]
	v_pk_mul_f32 v[130:131], v[140:141], v[128:129] op_sel_hi:[1,0]
	v_pk_mul_f32 v[128:129], v[134:135], v[128:129] op_sel_hi:[1,0]
	v_pk_mul_f32 v[112:113], v[112:113], v[130:131]
	v_pk_mul_f32 v[114:115], v[114:115], v[128:129]
	v_pk_mul_f32 v[116:117], v[116:117], v[132:133]
	ds_bpermute_b32 v130, v125, v112
	ds_bpermute_b32 v131, v125, v113
	ds_bpermute_b32 v134, v125, v114
	ds_bpermute_b32 v135, v125, v115
	ds_bpermute_b32 v128, v125, v116
	ds_bpermute_b32 v129, v125, v117
	ds_bpermute_b32 v132, v125, v118
	ds_bpermute_b32 v133, v125, v119
	v_pk_mul_f32 v[102:103], v[102:103], v[114:115]
	v_pk_mul_f32 v[100:101], v[100:101], v[112:113]
	s_waitcnt lgkmcnt(4)
	v_pk_mul_f32 v[98:99], v[98:99], v[134:135]
	v_pk_mul_f32 v[96:97], v[96:97], v[130:131]
	v_pk_mul_f32 v[110:111], v[110:111], v[118:119]
	v_pk_mul_f32 v[108:109], v[108:109], v[116:117]
	s_waitcnt lgkmcnt(0)
	v_pk_mul_f32 v[106:107], v[106:107], v[132:133]
	v_pk_mul_f32 v[104:105], v[104:105], v[128:129]
	v_pk_fma_f32 v[96:97], v[168:169], v[96:97], v[100:101]
	v_pk_fma_f32 v[98:99], v[126:127], v[98:99], v[102:103]
	v_pk_fma_f32 v[104:105], v[168:169], v[104:105], v[108:109]
	v_pk_fma_f32 v[106:107], v[126:127], v[106:107], v[110:111]
	v_pk_mul_f32 v[100:101], v[98:99], s[52:53] op_sel_hi:[1,0]
	v_pk_mul_f32 v[98:99], v[96:97], s[52:53] op_sel_hi:[1,0]
	v_pk_mul_f32 v[106:107], v[106:107], s[52:53] op_sel_hi:[1,0]
	v_pk_mul_f32 v[104:105], v[104:105], s[52:53] op_sel_hi:[1,0]
	v_cvt_pk_bf16_f32 v97, v106, v107
	v_cvt_pk_bf16_f32 v98, v98, v99
	v_cvt_pk_bf16_f32 v99, v100, v101
	s_nop 0
	v_cvt_pk_bf16_f32 v96, v104, v105
; __device__ __forceinline__ unsigned cvt_pk_bf16(float lo, float hi) { unsigned r; asm("v_cvt_pk_bf16_f32 %0, %1, %2" : "=v"(r) : "v"(lo), "v"(hi)); return r; }
;     __device__ __forceinline__ void epi(Acc& acc, const Unit& u, int wr, int wc, int fr, int fq) const {
;     ...
;             for (int m = 0; m < 4; ++m) { const int row = u.pm * 256 + ai * 128 + rl0 + m * 16;
;                 const f32x4 q0 = *(const f32x4*)(SSQ + (size_t)row * 8), q1 = *(const f32x4*)(SSQ + (size_t)row * 8 + 4);
;                 const float rq = rsqrtf((((q0[0] + q0[1]) + (q0[2] + q0[3])) + ((q1[0] + q1[1]) + (q1[2] + q1[3]))) * (1.f / 384.f) + EPS);
;                 if (u.pn < 2) {
;                     const int head = u.pn * 4 + wc; float s = 0.f; f32x4 v[2][2];
; #pragma unroll
;                     for (int bj = 0; bj < 2; ++bj)
; #pragma unroll
;                         for (int n = 0; n < 2; ++n) { v[bj][n] = acc[ai][bj][m][n] * rq; const f32x4 x = v[bj][n]; s += (x[0] * x[0] + x[1] * x[1]) + (x[2] * x[2] + x[3] * x[3]); }
;                     s += __shfl_xor(s, 16); s += __shfl_xor(s, 32);
;                     const float r2 = rsqrtf(s * (1.f / 64.f) + EPS) * QSCALE;
; #pragma unroll
;                     for (int bj = 0; bj < 2; ++bj) { const f32x4 g0 = *(const f32x4*)(qng + bj * 32 + fq * 8), g1 = *(const f32x4*)(qng + bj * 32 + fq * 8 + 4);
;                         const f32x4 a = v[bj][0] * r2 * g0, b = v[bj][1] * r2 * g1;
;                         u32x4 w; w.x = cvt_pk_bf16(a[0], a[1]); w.y = cvt_pk_bf16(a[2], a[3]); w.z = cvt_pk_bf16(b[0], b[1]); w.w = cvt_pk_bf16(b[2], b[3]);
;                         *(u32x4*)(Q + (size_t)row * 768 + head * 96 + bj * 32 + fq * 8) = w; }
.LBB0_576:
	s_mov_b64 s[8:9], 0x380
	s_andn2_b64 vcc, exec, s[10:11]
	s_mov_b64 s[10:11], s[62:63]
	s_cbranch_vccnz .LBB0_578
	v_pk_mul_f32 v[94:95], v[94:95], v[124:125] op_sel_hi:[1,0]
	v_pk_mul_f32 v[96:97], v[92:93], v[124:125] op_sel_hi:[1,0]
	v_pk_mul_f32 v[92:93], v[94:95], v[94:95]
	v_pk_mul_f32 v[98:99], v[96:97], v[96:97]
	v_pk_mul_f32 v[84:85], v[84:85], v[124:125] op_sel_hi:[1,0]
	v_pk_mov_b32 v[100:101], v[98:99], v[92:93] op_sel:[1,0]
	v_mov_b32_e32 v99, v93
	v_pk_add_f32 v[92:93], v[100:101], v[98:99]
	v_pk_mul_f32 v[98:99], v[90:91], v[124:125] op_sel_hi:[1,0]
	v_pk_mul_f32 v[100:101], v[88:89], v[124:125] op_sel_hi:[1,0]
	v_pk_mul_f32 v[88:89], v[98:99], v[98:99]
	v_pk_mul_f32 v[90:91], v[100:101], v[100:101]
	v_pk_mul_f32 v[86:87], v[86:87], v[124:125] op_sel_hi:[1,0]
	v_pk_mov_b32 v[102:103], v[90:91], v[88:89] op_sel:[1,0]
	v_mov_b32_e32 v91, v89
	v_pk_add_f32 v[88:89], v[102:103], v[90:91]
	v_pk_add_f32 v[92:93], v[92:93], v[92:93] op_sel_hi:[0,1]
	v_pk_add_f32 v[102:103], v[88:89], v[88:89] op_sel_hi:[0,1]
	v_mul_f32_e32 v88, v84, v84
	v_pk_fma_f32 v[104:105], v[84:85], v[84:85], v[88:89] op_sel_hi:[1,1,0]
	v_mul_f32_e32 v88, v86, v86
	v_pk_fma_f32 v[106:107], v[86:87], v[86:87], v[88:89] op_sel_hi:[1,1,0]
	v_pk_mul_f32 v[88:89], v[82:83], v[124:125] op_sel_hi:[1,0]
	v_pk_mul_f32 v[90:91], v[80:81], v[124:125] op_sel_hi:[1,0]
	v_mul_f32_e32 v92, v88, v88
	v_mul_f32_e32 v104, v90, v90
	v_mul_f32_e32 v106, v91, v91
	v_mul_f32_e32 v102, v89, v89
	v_pk_add_f32 v[80:81], v[104:105], v[106:107]
	v_pk_add_f32 v[82:83], v[92:93], v[102:103]
	v_mad_i64_i32 v[122:123], s[8:9], v120, s78, 0
	v_pk_add_f32 v[80:81], v[80:81], v[82:83]
	v_and_b32_e32 v82, 64, v188
	v_add_f32_e32 v80, v80, v81
	v_xor_b32_e32 v81, 16, v188
	v_add_u32_e32 v82, 64, v82
	v_cmp_lt_i32_e32 vcc, v81, v82
	s_mov_b64 s[10:11], s[82:83]
	s_nop 0
	v_cndmask_b32_e32 v81, v188, v81, vcc
	v_lshlrev_b32_e32 v81, 2, v81
	ds_bpermute_b32 v81, v81, v80
	s_waitcnt lgkmcnt(0)
	v_add_f32_e32 v80, v80, v81
	v_xor_b32_e32 v81, 32, v188
	v_cmp_lt_i32_e32 vcc, v81, v82
	s_nop 1
	v_cndmask_b32_e32 v81, v188, v81, vcc
	v_lshlrev_b32_e32 v81, 2, v81
	ds_bpermute_b32 v81, v81, v80
	s_waitcnt lgkmcnt(0)
	v_add_f32_e32 v80, v80, v81
	v_fmamk_f32 v80, v80, 0x3c800000, v187
	v_cmp_gt_f32_e32 vcc, s45, v80
	v_mul_f32_e32 v81, 0x4b800000, v80
	s_nop 0
	v_cndmask_b32_e32 v80, v80, v81, vcc
	v_rsq_f32_e32 v80, v80
	s_nop 0
	v_mul_f32_e32 v81, 0x45800000, v80
	v_cndmask_b32_e32 v80, v80, v81, vcc
	v_mul_f32_e32 v92, 0x3e16c740, v80
	v_pk_mul_f32 v[94:95], v[94:95], v[92:93] op_sel_hi:[1,0]
	v_pk_mul_f32 v[100:101], v[100:101], v[92:93] op_sel_hi:[1,0]
	v_pk_mul_f32 v[98:99], v[98:99], v[92:93] op_sel_hi:[1,0]
	v_pk_mul_f32 v[96:97], v[96:97], v[92:93] op_sel_hi:[1,0]
	v_pk_mul_f32 v[84:85], v[84:85], v[92:93] op_sel_hi:[1,0]
	v_pk_mul_f32 v[86:87], v[86:87], v[92:93] op_sel_hi:[1,0]
	v_pk_mul_f32 v[90:91], v[90:91], v[92:93] op_sel_hi:[1,0]
	v_pk_mul_f32 v[88:89], v[88:89], v[92:93] op_sel_hi:[1,0]
	v_pk_mul_f32 v[98:99], v[218:219], v[98:99]
	v_pk_mul_f32 v[94:95], v[214:215], v[94:95]
	v_pk_mul_f32 v[82:83], v[216:217], v[100:101]
	v_cvt_pk_bf16_f32 v81, v94, v95
	v_mov_b64_e32 v[94:95], s[42:43]
	v_mad_i64_i32 v[94:95], s[8:9], v120, s78, v[94:95]
	v_lshl_add_u64 v[94:95], s[82:83], 1, v[94:95]
	v_lshl_add_u64 v[94:95], v[166:167], 1, v[94:95]
	v_pk_mul_f32 v[96:97], v[212:213], v[96:97]
	v_cvt_pk_bf16_f32 v82, v82, v83
	v_cvt_pk_bf16_f32 v83, v98, v99
	s_mov_b64 s[8:9], 64
	v_cvt_pk_bf16_f32 v80, v96, v97
	global_store_dwordx4 v[94:95], v[80:83], off
	s_nop 1
	v_pk_mul_f32 v[82:83], v[226:227], v[88:89]
	v_pk_mul_f32 v[86:87], v[222:223], v[86:87]
	v_pk_mul_f32 v[84:85], v[220:221], v[84:85]
	v_pk_mul_f32 v[80:81], v[224:225], v[90:91]
	v_cvt_pk_bf16_f32 v96, v84, v85
	v_cvt_pk_bf16_f32 v97, v86, v87
	v_cvt_pk_bf16_f32 v99, v82, v83
	s_nop 0
	v_cvt_pk_bf16_f32 v98, v80, v81
.LBB0_578:
	v_lshl_add_u64 v[80:81], s[42:43], 0, v[122:123]
	v_lshl_add_u64 v[80:81], s[10:11], 1, v[80:81]
	v_lshl_add_u64 v[80:81], v[80:81], 0, s[8:9]
	v_add_u32_e32 v104, 48, v170
	v_lshl_add_u64 v[80:81], v[166:167], 1, v[80:81]
	v_ashrrev_i32_e32 v105, 31, v104
	global_store_dwordx4 v[80:81], v[96:99], off
	v_lshlrev_b64 v[80:81], 5, v[104:105]
	v_lshl_add_u64 v[84:85], s[68:69], 0, v[80:81]
	v_add_u32_e32 v90, 48, v189
	s_mov_b64 s[10:11], -1
	s_and_b64 vcc, exec, s[4:5]
	s_waitcnt vmcnt(2)
	v_mov_b64_e32 v[80:81], v[230:231]
	v_mov_b64_e32 v[82:83], v[232:233]
	v_mov_b64_e32 v[84:85], v[234:235]
	v_mov_b64_e32 v[86:87], v[236:237]
	v_add_u32_e32 v228, 0x80, v170
	v_ashrrev_i32_e32 v229, 31, v228
	v_lshlrev_b64 v[228:229], 5, v[228:229]
	v_lshl_add_u64 v[228:229], s[68:69], 0, v[228:229]
	global_load_dwordx4 v[230:233], v[228:229], off
	global_load_dwordx4 v[234:237], v[228:229], off offset:16
	v_mov_b32_e32 v88, v80
	v_mov_b32_e32 v89, v84
	v_mov_b32_e32 v84, v81
	v_mov_b32_e32 v80, v82
	v_mov_b32_e32 v81, v86
	v_mov_b32_e32 v86, v83
	v_pk_add_f32 v[82:83], v[88:89], v[84:85]
	v_pk_add_f32 v[80:81], v[80:81], v[86:87]
	s_nop 0
	v_pk_add_f32 v[80:81], v[82:83], v[80:81]
	s_nop 0
	v_add_f32_e32 v80, v80, v81
	v_fmamk_f32 v80, v80, 0x3b2aaaab, v187
	v_mul_f32_e32 v81, 0x4b800000, v80
	v_cmp_gt_f32_e64 s[8:9], s45, v80
	s_nop 1
	v_cndmask_b32_e64 v80, v80, v81, s[8:9]
	v_rsq_f32_e32 v80, v80
	v_and_b32_e32 v81, 63, v90
	v_or_b32_e32 v105, 0x800, v81
	v_mul_f32_e32 v82, 0x45800000, v80
	v_cndmask_b32_e64 v108, v80, v82, s[8:9]
	s_cbranch_vccnz .LBB0_580
;     __device__ __forceinline__ void epi(Acc& acc, const Unit& u, int wr, int wc, int fr, int fq) const {
;     ...
;                     const int pos = row < MP ? (row & 4095) : 2048 + ((row - MP) & 63);
;                     const float* rp = rope + (size_t)pos * 32 + (fq & 1) * 8;
;                     const f32x4 c0 = *(const f32x4*)rp, c1 = *(const f32x4*)(rp + 4), s0 = *(const f32x4*)(rp + 16), s1 = *(const f32x4*)(rp + 20);
;                     const f32x4 g0 = *(const f32x4*)(qrg + fq * 8), g1 = *(const f32x4*)(qrg + fq * 8 + 4);
;                     const float sg = fq < 2 ? -1.f : 1.f;
; #pragma unroll
;                     for (int bj = 0; bj < 2; ++bj) { const int head = bj * 4 + wc;
;                         f32x4 v0 = acc[ai][bj][m][0] * rq, v1 = acc[ai][bj][m][1] * rq;
;                         float s = (v0[0] * v0[0] + v0[1] * v0[1]) + (v0[2] * v0[2] + v0[3] * v0[3]) + (v1[0] * v1[0] + v1[1] * v1[1]) + (v1[2] * v1[2] + v1[3] * v1[3]);
;                         s += __shfl_xor(s, 16); s += __shfl_xor(s, 32);
;                         const float r2 = rsqrtf(s * (1.f / 32.f) + EPS);
;                         v0 = v0 * r2 * g0; v1 = v1 * r2 * g1;
	s_movk_i32 s8, 0x7fd0
	v_cmp_gt_i32_e32 vcc, s8, v170
	v_and_b32_e32 v80, 0xfff, v104
	v_mov_b32_e32 v173, v161
	v_cndmask_b32_e32 v80, v105, v80, vcc
	v_lshlrev_b32_e32 v160, 7, v80
	v_lshl_add_u64 v[80:81], s[76:77], 0, v[160:161]
	v_lshl_add_u64 v[88:89], v[80:81], 0, v[172:173]
	global_load_dwordx4 v[84:87], v[88:89], off offset:16
	global_load_dwordx4 v[92:95], v[88:89], off
	global_load_dwordx4 v[80:83], v[88:89], off offset:80
	s_nop 0
	global_load_dwordx4 v[88:91], v[88:89], off offset:64
	s_nop 0
	global_load_dwordx4 v[96:99], v[174:175], off offset:16
	global_load_dwordx4 v[100:103], v[174:175], off
	v_and_b32_e32 v107, 64, v188
	v_xor_b32_e32 v106, 16, v188
	v_add_u32_e32 v107, 64, v107
	v_cmp_lt_i32_e32 vcc, v106, v107
	s_mov_b64 s[10:11], 0
	s_nop 0
	v_cndmask_b32_e32 v106, v188, v106, vcc
	v_lshlrev_b32_e32 v112, 2, v106
	v_xor_b32_e32 v106, 32, v188
	v_cmp_lt_i32_e32 vcc, v106, v107
	s_nop 1
	v_cndmask_b32_e32 v106, v188, v106, vcc
	v_lshlrev_b32_e32 v109, 2, v106
	v_pk_mul_f32 v[110:111], v[78:79], v[108:109] op_sel_hi:[1,0]
	v_pk_mul_f32 v[114:115], v[76:77], v[108:109] op_sel_hi:[1,0]
	v_pk_mul_f32 v[122:123], v[110:111], v[110:111]
	v_pk_mul_f32 v[124:125], v[114:115], v[114:115]
	v_pk_mul_f32 v[116:117], v[74:75], v[108:109] op_sel_hi:[1,0]
	v_pk_mul_f32 v[118:119], v[72:73], v[108:109] op_sel_hi:[1,0]
	v_pk_mov_b32 v[126:127], v[124:125], v[122:123] op_sel:[1,0]
	v_mov_b32_e32 v125, v123
	v_pk_add_f32 v[122:123], v[126:127], v[124:125]
	v_pk_mul_f32 v[124:125], v[116:117], v[116:117]
	v_pk_mul_f32 v[126:127], v[118:119], v[118:119]
	v_mov_b32_e32 v128, v124
	v_mov_b32_e32 v129, v126
	v_mov_b32_e32 v126, v125
	v_pk_add_f32 v[124:125], v[128:129], v[126:127]
	v_add_f32_e32 v113, v122, v123
	v_add_f32_e32 v113, v125, v113
	v_add_f32_e32 v113, v124, v113
	ds_bpermute_b32 v120, v112, v113
	v_mad_i64_i32 v[106:107], s[8:9], v104, s78, 0
	s_waitcnt lgkmcnt(0)
	v_add_f32_e32 v113, v113, v120
	ds_bpermute_b32 v120, v109, v113
	s_waitcnt lgkmcnt(0)
	v_add_f32_e32 v113, v113, v120
	v_fmamk_f32 v113, v113, 0x3d000000, v187
	v_cmp_gt_f32_e32 vcc, s45, v113
	v_mul_f32_e32 v120, 0x4b800000, v113
	s_nop 0
	v_cndmask_b32_e32 v113, v113, v120, vcc
	v_rsq_f32_e32 v113, v113
	s_nop 0
	v_mul_f32_e32 v120, 0x45800000, v113
	v_cndmask_b32_e32 v120, v113, v120, vcc
	v_pk_mul_f32 v[114:115], v[114:115], v[120:121] op_sel_hi:[1,0]
	v_pk_mul_f32 v[110:111], v[110:111], v[120:121] op_sel_hi:[1,0]
	v_pk_mul_f32 v[118:119], v[118:119], v[120:121] op_sel_hi:[1,0]
	v_pk_mul_f32 v[116:117], v[116:117], v[120:121] op_sel_hi:[1,0]
	s_waitcnt vmcnt(1)
	v_pk_mul_f32 v[118:119], v[96:97], v[118:119]
	s_waitcnt vmcnt(0)
	v_pk_mul_f32 v[114:115], v[100:101], v[114:115]
	v_pk_mul_f32 v[110:111], v[102:103], v[110:111]
	ds_bpermute_b32 v122, v109, v114
	ds_bpermute_b32 v123, v109, v115
	ds_bpermute_b32 v126, v109, v110
	ds_bpermute_b32 v127, v109, v111
	v_pk_mul_f32 v[116:117], v[98:99], v[116:117]
	ds_bpermute_b32 v124, v109, v118
	ds_bpermute_b32 v125, v109, v119
	ds_bpermute_b32 v128, v109, v116
	ds_bpermute_b32 v129, v109, v117
	v_pk_mul_f32 v[130:131], v[94:95], v[110:111]
	v_pk_mul_f32 v[110:111], v[92:93], v[114:115]
	s_waitcnt lgkmcnt(6)
	v_pk_mul_f32 v[122:123], v[88:89], v[122:123]
	s_waitcnt lgkmcnt(4)
	v_pk_mul_f32 v[114:115], v[90:91], v[126:127]
	v_pk_fma_f32 v[122:123], v[168:169], v[122:123], v[110:111]
	v_mov_b32_e32 v110, v168
	v_mov_b32_e32 v111, v168
	v_pk_fma_f32 v[114:115], v[110:111], v[114:115], v[130:131]
	v_pk_mul_f32 v[116:117], v[86:87], v[116:117]
	v_pk_mul_f32 v[126:127], v[114:115], s[52:53] op_sel_hi:[1,0]
	v_pk_mul_f32 v[114:115], v[122:123], s[52:53] op_sel_hi:[1,0]
	v_pk_mul_f32 v[118:119], v[84:85], v[118:119]
	s_waitcnt lgkmcnt(0)
	v_pk_mul_f32 v[122:123], v[82:83], v[128:129]
	v_pk_mul_f32 v[124:125], v[80:81], v[124:125]
	v_pk_fma_f32 v[116:117], v[110:111], v[122:123], v[116:117]
	v_pk_fma_f32 v[118:119], v[168:169], v[124:125], v[118:119]
	v_pk_mul_f32 v[122:123], v[116:117], s[52:53] op_sel_hi:[1,0]
	v_pk_mul_f32 v[116:117], v[118:119], s[52:53] op_sel_hi:[1,0]
	v_mov_b64_e32 v[118:119], s[64:65]
	v_mad_i64_i32 v[118:119], s[8:9], v104, s78, v[118:119]
	v_cvt_pk_bf16_f32 v114, v114, v115
	v_cvt_pk_bf16_f32 v115, v126, v127
	v_cvt_pk_bf16_f32 v116, v116, v117
	v_cvt_pk_bf16_f32 v117, v122, v123
	v_lshl_add_u64 v[118:119], v[166:167], 1, v[118:119]
	global_store_dwordx4 v[118:119], v[114:117], off offset:128
	v_pk_mul_f32 v[118:119], v[66:67], v[108:109] op_sel_hi:[1,0]
	v_pk_mul_f32 v[122:123], v[64:65], v[108:109] op_sel_hi:[1,0]
	v_pk_mul_f32 v[114:115], v[70:71], v[108:109] op_sel_hi:[1,0]
	v_pk_mul_f32 v[116:117], v[68:69], v[108:109] op_sel_hi:[1,0]
	v_pk_mul_f32 v[124:125], v[114:115], v[114:115]
	v_pk_mul_f32 v[126:127], v[116:117], v[116:117]
	s_nop 0
	v_pk_mov_b32 v[128:129], v[126:127], v[124:125] op_sel:[1,0]
	v_mov_b32_e32 v127, v125
	v_pk_add_f32 v[124:125], v[128:129], v[126:127]
	v_pk_mul_f32 v[126:127], v[118:119], v[118:119]
	v_pk_mul_f32 v[128:129], v[122:123], v[122:123]
	v_mov_b32_e32 v130, v126
	v_mov_b32_e32 v131, v128
	v_mov_b32_e32 v128, v127
	v_pk_add_f32 v[126:127], v[130:131], v[128:129]
	v_add_f32_e32 v113, v124, v125
	v_add_f32_e32 v113, v127, v113
	v_add_f32_e32 v113, v126, v113
	ds_bpermute_b32 v112, v112, v113
	s_waitcnt lgkmcnt(0)
	v_add_f32_e32 v112, v113, v112
	ds_bpermute_b32 v113, v109, v112
	s_waitcnt lgkmcnt(0)
; __device__ __forceinline__ unsigned cvt_pk_bf16(float lo, float hi) { unsigned r; asm("v_cvt_pk_bf16_f32 %0, %1, %2" : "=v"(r) : "v"(lo), "v"(hi)); return r; }
;     __device__ __forceinline__ void epi(Acc& acc, const Unit& u, int wr, int wc, int fr, int fq) const {
;     ...
;                     const int head = u.pn * 4 + wc; float s = 0.f; f32x4 v[2][2];
; #pragma unroll
;                     for (int bj = 0; bj < 2; ++bj)
; #pragma unroll
;                         for (int n = 0; n < 2; ++n) { v[bj][n] = acc[ai][bj][m][n] * rq; const f32x4 x = v[bj][n]; s += (x[0] * x[0] + x[1] * x[1]) + (x[2] * x[2] + x[3] * x[3]); }
;                     s += __shfl_xor(s, 16); s += __shfl_xor(s, 32);
;                     const float r2 = rsqrtf(s * (1.f / 64.f) + EPS) * QSCALE;
;     ...
;                         v0 = v0 * r2 * g0; v1 = v1 * r2 * g1;
;                         f32x4 p0, p1;
; #pragma unroll
;                         for (int e = 0; e < 4; ++e) { p0[e] = __shfl_xor(v0[e], 32); p1[e] = __shfl_xor(v1[e], 32); }
;                         const f32x4 r0 = (v0 * c0 + p0 * s0 * sg) * QSCALE, r1 = (v1 * c1 + p1 * s1 * sg) * QSCALE;
;                         u32x4 w; w.x = cvt_pk_bf16(r0[0], r0[1]); w.y = cvt_pk_bf16(r0[2], r0[3]); w.z = cvt_pk_bf16(r1[0], r1[1]); w.w = cvt_pk_bf16(r1[2], r1[3]);
;                         *(u32x4*)(Q + (size_t)row * 768 + head * 96 + 64 + fq * 8) = w; }
	v_add_f32_e32 v112, v112, v113
	v_fmamk_f32 v112, v112, 0x3d000000, v187
	v_cmp_gt_f32_e32 vcc, s45, v112
	v_mul_f32_e32 v113, 0x4b800000, v112
	s_nop 0
	v_cndmask_b32_e32 v112, v112, v113, vcc
	v_rsq_f32_e32 v112, v112
	s_nop 0
	v_mul_f32_e32 v113, 0x45800000, v112
	v_cndmask_b32_e32 v112, v112, v113, vcc
	v_pk_mul_f32 v[114:115], v[114:115], v[112:113] op_sel_hi:[1,0]
	v_pk_mul_f32 v[116:117], v[116:117], v[112:113] op_sel_hi:[1,0]
	v_pk_mul_f32 v[102:103], v[102:103], v[114:115]
	v_pk_mul_f32 v[114:115], v[122:123], v[112:113] op_sel_hi:[1,0]
	v_pk_mul_f32 v[112:113], v[118:119], v[112:113] op_sel_hi:[1,0]
	v_pk_mul_f32 v[96:97], v[96:97], v[114:115]
	v_pk_mul_f32 v[98:99], v[98:99], v[112:113]
	v_pk_mul_f32 v[100:101], v[100:101], v[116:117]
	ds_bpermute_b32 v114, v109, v96
	ds_bpermute_b32 v115, v109, v97
	ds_bpermute_b32 v118, v109, v98
	ds_bpermute_b32 v119, v109, v99
	ds_bpermute_b32 v112, v109, v100
	ds_bpermute_b32 v113, v109, v101
	ds_bpermute_b32 v116, v109, v102
	ds_bpermute_b32 v117, v109, v103
	v_pk_mul_f32 v[86:87], v[86:87], v[98:99]
	v_pk_mul_f32 v[84:85], v[84:85], v[96:97]
	s_waitcnt lgkmcnt(4)
	v_pk_mul_f32 v[82:83], v[82:83], v[118:119]
	v_pk_mul_f32 v[80:81], v[80:81], v[114:115]
	v_pk_mul_f32 v[94:95], v[94:95], v[102:103]
	v_pk_mul_f32 v[92:93], v[92:93], v[100:101]
	s_waitcnt lgkmcnt(0)
	v_pk_mul_f32 v[90:91], v[90:91], v[116:117]
	v_pk_mul_f32 v[88:89], v[88:89], v[112:113]
	v_pk_fma_f32 v[80:81], v[168:169], v[80:81], v[84:85]
	v_pk_fma_f32 v[82:83], v[110:111], v[82:83], v[86:87]
	v_pk_fma_f32 v[88:89], v[168:169], v[88:89], v[92:93]
	v_pk_fma_f32 v[90:91], v[110:111], v[90:91], v[94:95]
	v_pk_mul_f32 v[84:85], v[82:83], s[52:53] op_sel_hi:[1,0]
	v_pk_mul_f32 v[82:83], v[80:81], s[52:53] op_sel_hi:[1,0]
	v_pk_mul_f32 v[90:91], v[90:91], s[52:53] op_sel_hi:[1,0]
	v_pk_mul_f32 v[88:89], v[88:89], s[52:53] op_sel_hi:[1,0]
	v_cvt_pk_bf16_f32 v81, v90, v91
	v_cvt_pk_bf16_f32 v82, v82, v83
	v_cvt_pk_bf16_f32 v83, v84, v85
	s_nop 0
	v_cvt_pk_bf16_f32 v80, v88, v89
.LBB0_580:
	s_mov_b64 s[8:9], 0x380
	s_andn2_b64 vcc, exec, s[10:11]
	s_mov_b64 s[10:11], s[62:63]
	s_cbranch_vccnz .LBB0_582
	v_pk_mul_f32 v[78:79], v[78:79], v[108:109] op_sel_hi:[1,0]
	v_pk_mul_f32 v[80:81], v[76:77], v[108:109] op_sel_hi:[1,0]
	v_pk_mul_f32 v[76:77], v[78:79], v[78:79]
	v_pk_mul_f32 v[82:83], v[80:81], v[80:81]
	v_pk_mul_f32 v[68:69], v[68:69], v[108:109] op_sel_hi:[1,0]
	v_pk_mov_b32 v[84:85], v[82:83], v[76:77] op_sel:[1,0]
	v_mov_b32_e32 v83, v77
	v_pk_add_f32 v[76:77], v[84:85], v[82:83]
	v_pk_mul_f32 v[82:83], v[74:75], v[108:109] op_sel_hi:[1,0]
	v_pk_mul_f32 v[84:85], v[72:73], v[108:109] op_sel_hi:[1,0]
	v_pk_mul_f32 v[72:73], v[82:83], v[82:83]
	v_pk_mul_f32 v[74:75], v[84:85], v[84:85]
	v_pk_mul_f32 v[70:71], v[70:71], v[108:109] op_sel_hi:[1,0]
	v_pk_mov_b32 v[86:87], v[74:75], v[72:73] op_sel:[1,0]
	v_mov_b32_e32 v75, v73
	v_pk_add_f32 v[72:73], v[86:87], v[74:75]
	v_pk_add_f32 v[76:77], v[76:77], v[76:77] op_sel_hi:[0,1]
	v_pk_add_f32 v[86:87], v[72:73], v[72:73] op_sel_hi:[0,1]
	v_mul_f32_e32 v72, v68, v68
	v_pk_fma_f32 v[88:89], v[68:69], v[68:69], v[72:73] op_sel_hi:[1,1,0]
	v_mul_f32_e32 v72, v70, v70
	v_pk_fma_f32 v[90:91], v[70:71], v[70:71], v[72:73] op_sel_hi:[1,1,0]
	v_pk_mul_f32 v[72:73], v[66:67], v[108:109] op_sel_hi:[1,0]
	v_pk_mul_f32 v[74:75], v[64:65], v[108:109] op_sel_hi:[1,0]
	v_mul_f32_e32 v76, v72, v72
	v_mul_f32_e32 v88, v74, v74
	v_mul_f32_e32 v90, v75, v75
	v_mul_f32_e32 v86, v73, v73
	v_pk_add_f32 v[64:65], v[88:89], v[90:91]
	v_pk_add_f32 v[66:67], v[76:77], v[86:87]
	v_mad_i64_i32 v[106:107], s[8:9], v104, s78, 0
	v_pk_add_f32 v[64:65], v[64:65], v[66:67]
	v_and_b32_e32 v66, 64, v188
	v_add_f32_e32 v64, v64, v65
	v_xor_b32_e32 v65, 16, v188
	v_add_u32_e32 v66, 64, v66
	v_cmp_lt_i32_e32 vcc, v65, v66
	s_mov_b64 s[10:11], s[82:83]
	s_nop 0
	v_cndmask_b32_e32 v65, v188, v65, vcc
	v_lshlrev_b32_e32 v65, 2, v65
	ds_bpermute_b32 v65, v65, v64
	s_waitcnt lgkmcnt(0)
	v_add_f32_e32 v64, v64, v65
	v_xor_b32_e32 v65, 32, v188
	v_cmp_lt_i32_e32 vcc, v65, v66
	s_nop 1
	v_cndmask_b32_e32 v65, v188, v65, vcc
	v_lshlrev_b32_e32 v65, 2, v65
	ds_bpermute_b32 v65, v65, v64
	s_waitcnt lgkmcnt(0)
	v_add_f32_e32 v64, v64, v65
	v_fmamk_f32 v64, v64, 0x3c800000, v187
	v_cmp_gt_f32_e32 vcc, s45, v64
	v_mul_f32_e32 v65, 0x4b800000, v64
	s_nop 0
	v_cndmask_b32_e32 v64, v64, v65, vcc
	v_rsq_f32_e32 v64, v64
	s_nop 0
	v_mul_f32_e32 v65, 0x45800000, v64
	v_cndmask_b32_e32 v64, v64, v65, vcc
	v_mul_f32_e32 v76, 0x3e16c740, v64
	v_pk_mul_f32 v[78:79], v[78:79], v[76:77] op_sel_hi:[1,0]
	v_pk_mul_f32 v[84:85], v[84:85], v[76:77] op_sel_hi:[1,0]
	v_pk_mul_f32 v[82:83], v[82:83], v[76:77] op_sel_hi:[1,0]
	v_pk_mul_f32 v[80:81], v[80:81], v[76:77] op_sel_hi:[1,0]
	v_pk_mul_f32 v[68:69], v[68:69], v[76:77] op_sel_hi:[1,0]
	v_pk_mul_f32 v[70:71], v[70:71], v[76:77] op_sel_hi:[1,0]
	v_pk_mul_f32 v[74:75], v[74:75], v[76:77] op_sel_hi:[1,0]
	v_pk_mul_f32 v[72:73], v[72:73], v[76:77] op_sel_hi:[1,0]
	v_pk_mul_f32 v[82:83], v[218:219], v[82:83]
	v_pk_mul_f32 v[78:79], v[214:215], v[78:79]
	v_pk_mul_f32 v[66:67], v[216:217], v[84:85]
	v_cvt_pk_bf16_f32 v65, v78, v79
	v_mov_b64_e32 v[78:79], s[42:43]
	v_mad_i64_i32 v[78:79], s[8:9], v104, s78, v[78:79]
	v_lshl_add_u64 v[78:79], s[82:83], 1, v[78:79]
	v_lshl_add_u64 v[78:79], v[166:167], 1, v[78:79]
	v_pk_mul_f32 v[80:81], v[212:213], v[80:81]
	v_cvt_pk_bf16_f32 v66, v66, v67
	v_cvt_pk_bf16_f32 v67, v82, v83
	s_mov_b64 s[8:9], 64
	v_cvt_pk_bf16_f32 v64, v80, v81
	global_store_dwordx4 v[78:79], v[64:67], off
	s_nop 1
	v_pk_mul_f32 v[66:67], v[226:227], v[72:73]
	v_pk_mul_f32 v[70:71], v[222:223], v[70:71]
	v_pk_mul_f32 v[68:69], v[220:221], v[68:69]
	v_pk_mul_f32 v[64:65], v[224:225], v[74:75]
	v_cvt_pk_bf16_f32 v80, v68, v69
	v_cvt_pk_bf16_f32 v81, v70, v71
	v_cvt_pk_bf16_f32 v83, v66, v67
	s_nop 0
	v_cvt_pk_bf16_f32 v82, v64, v65
;     __device__ __forceinline__ void epi(Acc& acc, const Unit& u, int wr, int wc, int fr, int fq) const {
;     ...
;             for (int m = 0; m < 4; ++m) { const int row = u.pm * 256 + ai * 128 + rl0 + m * 16;
;                 const f32x4 q0 = *(const f32x4*)(SSQ + (size_t)row * 8), q1 = *(const f32x4*)(SSQ + (size_t)row * 8 + 4);
;                 const float rq = rsqrtf((((q0[0] + q0[1]) + (q0[2] + q0[3])) + ((q1[0] + q1[1]) + (q1[2] + q1[3]))) * (1.f / 384.f) + EPS);
;     ...
;                     const int pos = row < MP ? (row & 4095) : 2048 + ((row - MP) & 63);
;                     const float* rp = rope + (size_t)pos * 32 + (fq & 1) * 8;
;                     const f32x4 c0 = *(const f32x4*)rp, c1 = *(const f32x4*)(rp + 4), s0 = *(const f32x4*)(rp + 16), s1 = *(const f32x4*)(rp + 20);
;                     const f32x4 g0 = *(const f32x4*)(qrg + fq * 8), g1 = *(const f32x4*)(qrg + fq * 8 + 4);
;                     const float sg = fq < 2 ? -1.f : 1.f;
; #pragma unroll
;                     for (int bj = 0; bj < 2; ++bj) { const int head = bj * 4 + wc;
;                         f32x4 v0 = acc[ai][bj][m][0] * rq, v1 = acc[ai][bj][m][1] * rq;
;                         float s = (v0[0] * v0[0] + v0[1] * v0[1]) + (v0[2] * v0[2] + v0[3] * v0[3]) + (v1[0] * v1[0] + v1[1] * v1[1]) + (v1[2] * v1[2] + v1[3] * v1[3]);
;                         s += __shfl_xor(s, 16); s += __shfl_xor(s, 32);
;                         const float r2 = rsqrtf(s * (1.f / 32.f) + EPS);
;                         v0 = v0 * r2 * g0; v1 = v1 * r2 * g1;
.LBB0_582:
	v_lshl_add_u64 v[64:65], s[42:43], 0, v[106:107]
	v_lshl_add_u64 v[64:65], s[10:11], 1, v[64:65]
	v_lshl_add_u64 v[64:65], v[64:65], 0, s[8:9]
	v_add_u32_e32 v88, 0x80, v170
	v_lshl_add_u64 v[64:65], v[166:167], 1, v[64:65]
	v_ashrrev_i32_e32 v89, 31, v88
	global_store_dwordx4 v[64:65], v[80:83], off
	v_lshlrev_b64 v[64:65], 5, v[88:89]
	v_lshl_add_u64 v[68:69], s[68:69], 0, v[64:65]
	s_and_b64 vcc, exec, s[4:5]
	s_mov_b64 s[10:11], -1
	s_waitcnt vmcnt(2)
	v_mov_b64_e32 v[64:65], v[230:231]
	v_mov_b64_e32 v[66:67], v[232:233]
	v_mov_b64_e32 v[68:69], v[234:235]
	v_mov_b64_e32 v[70:71], v[236:237]
	v_add_u32_e32 v228, 0x90, v170
	v_ashrrev_i32_e32 v229, 31, v228
	v_lshlrev_b64 v[228:229], 5, v[228:229]
	v_lshl_add_u64 v[228:229], s[68:69], 0, v[228:229]
	global_load_dwordx4 v[230:233], v[228:229], off
	global_load_dwordx4 v[234:237], v[228:229], off offset:16
	v_mov_b32_e32 v72, v64
	v_mov_b32_e32 v73, v68
	v_mov_b32_e32 v68, v65
	v_mov_b32_e32 v64, v66
	v_mov_b32_e32 v65, v70
	v_mov_b32_e32 v70, v67
	v_pk_add_f32 v[66:67], v[72:73], v[68:69]
	v_pk_add_f32 v[64:65], v[64:65], v[70:71]
	s_nop 0
	v_pk_add_f32 v[64:65], v[66:67], v[64:65]
	s_nop 0
	v_add_f32_e32 v64, v64, v65
	v_fmamk_f32 v64, v64, 0x3b2aaaab, v187
	v_mul_f32_e32 v65, 0x4b800000, v64
	v_cmp_gt_f32_e64 s[8:9], s45, v64
	s_nop 1
	v_cndmask_b32_e64 v64, v64, v65, s[8:9]
	v_rsq_f32_e32 v64, v64
	s_nop 0
	v_mul_f32_e32 v65, 0x45800000, v64
	v_cndmask_b32_e64 v92, v64, v65, s[8:9]
	s_cbranch_vccnz .LBB0_584
	v_cmp_gt_i32_e32 vcc, s50, v88
	v_and_b32_e32 v64, 0xfff, v88
	v_mov_b32_e32 v173, v161
	v_cndmask_b32_e32 v64, v171, v64, vcc
	v_lshlrev_b32_e32 v160, 7, v64
	v_lshl_add_u64 v[64:65], s[76:77], 0, v[160:161]
	v_lshl_add_u64 v[72:73], v[64:65], 0, v[172:173]
	global_load_dwordx4 v[68:71], v[72:73], off offset:16
	global_load_dwordx4 v[76:79], v[72:73], off
	global_load_dwordx4 v[64:67], v[72:73], off offset:80
	s_nop 0
	global_load_dwordx4 v[72:75], v[72:73], off offset:64
	s_nop 0
	global_load_dwordx4 v[80:83], v[174:175], off offset:16
	global_load_dwordx4 v[84:87], v[174:175], off
	v_and_b32_e32 v90, 64, v188
	v_xor_b32_e32 v89, 16, v188
	v_add_u32_e32 v90, 64, v90
	v_cmp_lt_i32_e32 vcc, v89, v90
	s_mov_b64 s[10:11], 0
	s_nop 0
	v_cndmask_b32_e32 v89, v188, v89, vcc
	v_lshlrev_b32_e32 v93, 2, v89
	v_pk_mul_f32 v[94:95], v[62:63], v[92:93] op_sel_hi:[1,0]
	v_pk_mul_f32 v[96:97], v[60:61], v[92:93] op_sel_hi:[1,0]
	v_pk_mul_f32 v[102:103], v[94:95], v[94:95]
	v_pk_mul_f32 v[106:107], v[96:97], v[96:97]
	v_pk_mul_f32 v[98:99], v[58:59], v[92:93] op_sel_hi:[1,0]
	v_pk_mul_f32 v[100:101], v[56:57], v[92:93] op_sel_hi:[1,0]
	v_pk_mov_b32 v[108:109], v[106:107], v[102:103] op_sel:[1,0]
	v_mov_b32_e32 v107, v103
	v_pk_add_f32 v[102:103], v[108:109], v[106:107]
	v_pk_mul_f32 v[106:107], v[98:99], v[98:99]
	v_pk_mul_f32 v[108:109], v[100:101], v[100:101]
	v_mov_b32_e32 v110, v106
	v_mov_b32_e32 v111, v108
	v_mov_b32_e32 v108, v107
	v_pk_add_f32 v[106:107], v[110:111], v[108:109]
	v_add_f32_e32 v102, v102, v103
	v_add_f32_e32 v102, v107, v102
	v_add_f32_e32 v102, v106, v102
	ds_bpermute_b32 v103, v93, v102
	v_xor_b32_e32 v89, 32, v188
	v_cmp_lt_i32_e32 vcc, v89, v90
	v_mad_i64_i32 v[90:91], s[8:9], v88, s78, 0
	s_nop 0
	v_cndmask_b32_e32 v89, v188, v89, vcc
	v_lshlrev_b32_e32 v89, 2, v89
	s_waitcnt lgkmcnt(0)
	v_add_f32_e32 v102, v102, v103
	ds_bpermute_b32 v103, v89, v102
	s_waitcnt lgkmcnt(0)
	v_add_f32_e32 v102, v102, v103
	v_fmamk_f32 v102, v102, 0x3d000000, v187
	v_cmp_gt_f32_e32 vcc, s45, v102
	v_mul_f32_e32 v103, 0x4b800000, v102
	s_nop 0
	v_cndmask_b32_e32 v102, v102, v103, vcc
	v_rsq_f32_e32 v102, v102
	s_nop 0
	v_mul_f32_e32 v103, 0x45800000, v102
	v_cndmask_b32_e32 v102, v102, v103, vcc
	v_pk_mul_f32 v[96:97], v[96:97], v[102:103] op_sel_hi:[1,0]
	v_pk_mul_f32 v[94:95], v[94:95], v[102:103] op_sel_hi:[1,0]
	v_pk_mul_f32 v[100:101], v[100:101], v[102:103] op_sel_hi:[1,0]
	v_pk_mul_f32 v[98:99], v[98:99], v[102:103] op_sel_hi:[1,0]
	s_waitcnt vmcnt(1)
	v_pk_mul_f32 v[100:101], v[80:81], v[100:101]
	s_waitcnt vmcnt(0)
	v_pk_mul_f32 v[96:97], v[84:85], v[96:97]
	v_pk_mul_f32 v[94:95], v[86:87], v[94:95]
	ds_bpermute_b32 v102, v89, v96
	ds_bpermute_b32 v103, v89, v97
	ds_bpermute_b32 v108, v89, v94
	ds_bpermute_b32 v109, v89, v95
	v_pk_mul_f32 v[98:99], v[82:83], v[98:99]
	ds_bpermute_b32 v106, v89, v100
	ds_bpermute_b32 v107, v89, v101
	ds_bpermute_b32 v110, v89, v98
	ds_bpermute_b32 v111, v89, v99
	v_pk_mul_f32 v[112:113], v[78:79], v[94:95]
	v_pk_mul_f32 v[94:95], v[76:77], v[96:97]
	s_waitcnt lgkmcnt(6)
	v_pk_mul_f32 v[102:103], v[72:73], v[102:103]
	s_waitcnt lgkmcnt(4)
	v_pk_mul_f32 v[96:97], v[74:75], v[108:109]
	v_pk_fma_f32 v[102:103], v[168:169], v[102:103], v[94:95]
	v_mov_b32_e32 v94, v168
	v_mov_b32_e32 v95, v168
	v_pk_fma_f32 v[96:97], v[94:95], v[96:97], v[112:113]
	v_pk_mul_f32 v[98:99], v[70:71], v[98:99]
	v_pk_mul_f32 v[108:109], v[96:97], s[52:53] op_sel_hi:[1,0]
	v_pk_mul_f32 v[96:97], v[102:103], s[52:53] op_sel_hi:[1,0]
	v_pk_mul_f32 v[100:101], v[68:69], v[100:101]
	s_waitcnt lgkmcnt(0)
; __device__ __forceinline__ unsigned cvt_pk_bf16(float lo, float hi) { unsigned r; asm("v_cvt_pk_bf16_f32 %0, %1, %2" : "=v"(r) : "v"(lo), "v"(hi)); return r; }
;     __device__ __forceinline__ void epi(Acc& acc, const Unit& u, int wr, int wc, int fr, int fq) const {
;     ...
;                     const int head = u.pn * 4 + wc; float s = 0.f; f32x4 v[2][2];
; #pragma unroll
;                     for (int bj = 0; bj < 2; ++bj)
; #pragma unroll
;                         for (int n = 0; n < 2; ++n) { v[bj][n] = acc[ai][bj][m][n] * rq; const f32x4 x = v[bj][n]; s += (x[0] * x[0] + x[1] * x[1]) + (x[2] * x[2] + x[3] * x[3]); }
;                     s += __shfl_xor(s, 16); s += __shfl_xor(s, 32);
;                     const float r2 = rsqrtf(s * (1.f / 64.f) + EPS) * QSCALE;
;     ...
;                         v0 = v0 * r2 * g0; v1 = v1 * r2 * g1;
;                         f32x4 p0, p1;
; #pragma unroll
;                         for (int e = 0; e < 4; ++e) { p0[e] = __shfl_xor(v0[e], 32); p1[e] = __shfl_xor(v1[e], 32); }
;                         const f32x4 r0 = (v0 * c0 + p0 * s0 * sg) * QSCALE, r1 = (v1 * c1 + p1 * s1 * sg) * QSCALE;
;                         u32x4 w; w.x = cvt_pk_bf16(r0[0], r0[1]); w.y = cvt_pk_bf16(r0[2], r0[3]); w.z = cvt_pk_bf16(r1[0], r1[1]); w.w = cvt_pk_bf16(r1[2], r1[3]);
;                         *(u32x4*)(Q + (size_t)row * 768 + head * 96 + 64 + fq * 8) = w; }
	v_pk_mul_f32 v[102:103], v[66:67], v[110:111]
	v_pk_mul_f32 v[106:107], v[64:65], v[106:107]
	v_pk_fma_f32 v[98:99], v[94:95], v[102:103], v[98:99]
	v_pk_fma_f32 v[100:101], v[168:169], v[106:107], v[100:101]
	v_pk_mul_f32 v[102:103], v[98:99], s[52:53] op_sel_hi:[1,0]
	v_pk_mul_f32 v[98:99], v[100:101], s[52:53] op_sel_hi:[1,0]
	v_mov_b64_e32 v[100:101], s[64:65]
	v_mad_i64_i32 v[100:101], s[8:9], v88, s78, v[100:101]
	v_cvt_pk_bf16_f32 v96, v96, v97
	v_cvt_pk_bf16_f32 v97, v108, v109
	v_cvt_pk_bf16_f32 v98, v98, v99
	v_cvt_pk_bf16_f32 v99, v102, v103
	v_lshl_add_u64 v[100:101], v[166:167], 1, v[100:101]
	global_store_dwordx4 v[100:101], v[96:99], off offset:128
	v_pk_mul_f32 v[100:101], v[50:51], v[92:93] op_sel_hi:[1,0]
	v_pk_mul_f32 v[102:103], v[48:49], v[92:93] op_sel_hi:[1,0]
	v_pk_mul_f32 v[96:97], v[54:55], v[92:93] op_sel_hi:[1,0]
	v_pk_mul_f32 v[98:99], v[52:53], v[92:93] op_sel_hi:[1,0]
	v_pk_mul_f32 v[106:107], v[96:97], v[96:97]
	v_pk_mul_f32 v[108:109], v[98:99], v[98:99]
	s_nop 0
	v_pk_mov_b32 v[110:111], v[108:109], v[106:107] op_sel:[1,0]
	v_mov_b32_e32 v109, v107
	v_pk_add_f32 v[106:107], v[110:111], v[108:109]
	v_pk_mul_f32 v[108:109], v[100:101], v[100:101]
	v_pk_mul_f32 v[110:111], v[102:103], v[102:103]
	v_mov_b32_e32 v112, v108
	v_mov_b32_e32 v113, v110
	v_mov_b32_e32 v110, v109
	v_pk_add_f32 v[108:109], v[112:113], v[110:111]
	v_add_f32_e32 v104, v106, v107
	v_add_f32_e32 v104, v109, v104
	v_add_f32_e32 v104, v108, v104
	ds_bpermute_b32 v93, v93, v104
	s_waitcnt lgkmcnt(0)
	v_add_f32_e32 v93, v104, v93
	ds_bpermute_b32 v104, v89, v93
	s_waitcnt lgkmcnt(0)
	v_add_f32_e32 v93, v93, v104
	v_fmamk_f32 v93, v93, 0x3d000000, v187
	v_cmp_gt_f32_e32 vcc, s45, v93
	v_mul_f32_e32 v104, 0x4b800000, v93
	s_nop 0
	v_cndmask_b32_e32 v93, v93, v104, vcc
	v_rsq_f32_e32 v93, v93
	s_nop 0
	v_mul_f32_e32 v104, 0x45800000, v93
	v_cndmask_b32_e32 v104, v93, v104, vcc
	v_pk_mul_f32 v[98:99], v[98:99], v[104:105] op_sel_hi:[1,0]
	v_pk_mul_f32 v[96:97], v[96:97], v[104:105] op_sel_hi:[1,0]
	v_pk_mul_f32 v[84:85], v[84:85], v[98:99]
	v_pk_mul_f32 v[86:87], v[86:87], v[96:97]
	v_pk_mul_f32 v[96:97], v[102:103], v[104:105] op_sel_hi:[1,0]
	v_pk_mul_f32 v[98:99], v[100:101], v[104:105] op_sel_hi:[1,0]
	v_pk_mul_f32 v[80:81], v[80:81], v[96:97]
	v_pk_mul_f32 v[82:83], v[82:83], v[98:99]
	ds_bpermute_b32 v98, v89, v80
	ds_bpermute_b32 v99, v89, v81
	ds_bpermute_b32 v102, v89, v82
	ds_bpermute_b32 v103, v89, v83
	ds_bpermute_b32 v96, v89, v84
	ds_bpermute_b32 v97, v89, v85
	ds_bpermute_b32 v100, v89, v86
	ds_bpermute_b32 v101, v89, v87
	v_pk_mul_f32 v[70:71], v[70:71], v[82:83]
	v_pk_mul_f32 v[68:69], v[68:69], v[80:81]
	s_waitcnt lgkmcnt(4)
	v_pk_mul_f32 v[66:67], v[66:67], v[102:103]
	v_pk_mul_f32 v[64:65], v[64:65], v[98:99]
	v_pk_mul_f32 v[78:79], v[78:79], v[86:87]
	v_pk_mul_f32 v[76:77], v[76:77], v[84:85]
	s_waitcnt lgkmcnt(0)
	v_pk_mul_f32 v[74:75], v[74:75], v[100:101]
	v_pk_mul_f32 v[72:73], v[72:73], v[96:97]
	v_pk_fma_f32 v[64:65], v[168:169], v[64:65], v[68:69]
	v_pk_fma_f32 v[66:67], v[94:95], v[66:67], v[70:71]
	v_pk_fma_f32 v[72:73], v[168:169], v[72:73], v[76:77]
	v_pk_fma_f32 v[74:75], v[94:95], v[74:75], v[78:79]
	v_pk_mul_f32 v[68:69], v[66:67], s[52:53] op_sel_hi:[1,0]
	v_pk_mul_f32 v[66:67], v[64:65], s[52:53] op_sel_hi:[1,0]
	v_pk_mul_f32 v[74:75], v[74:75], s[52:53] op_sel_hi:[1,0]
	v_pk_mul_f32 v[72:73], v[72:73], s[52:53] op_sel_hi:[1,0]
	v_cvt_pk_bf16_f32 v65, v74, v75
	v_cvt_pk_bf16_f32 v66, v66, v67
	v_cvt_pk_bf16_f32 v67, v68, v69
	s_nop 0
	v_cvt_pk_bf16_f32 v64, v72, v73
.LBB0_584:
	s_mov_b64 s[8:9], 0x380
	s_andn2_b64 vcc, exec, s[10:11]
	s_mov_b64 s[10:11], s[62:63]
	s_cbranch_vccnz .LBB0_586
	v_pk_mul_f32 v[62:63], v[62:63], v[92:93] op_sel_hi:[1,0]
	v_pk_mul_f32 v[64:65], v[60:61], v[92:93] op_sel_hi:[1,0]
	v_pk_mul_f32 v[60:61], v[62:63], v[62:63]
	v_pk_mul_f32 v[66:67], v[64:65], v[64:65]
	v_pk_mul_f32 v[52:53], v[52:53], v[92:93] op_sel_hi:[1,0]
	v_pk_mov_b32 v[68:69], v[66:67], v[60:61] op_sel:[1,0]
	v_mov_b32_e32 v67, v61
	v_pk_add_f32 v[60:61], v[68:69], v[66:67]
	v_pk_mul_f32 v[66:67], v[58:59], v[92:93] op_sel_hi:[1,0]
	v_pk_mul_f32 v[68:69], v[56:57], v[92:93] op_sel_hi:[1,0]
	v_pk_mul_f32 v[56:57], v[66:67], v[66:67]
	v_pk_mul_f32 v[58:59], v[68:69], v[68:69]
	v_pk_mul_f32 v[54:55], v[54:55], v[92:93] op_sel_hi:[1,0]
	v_pk_mov_b32 v[70:71], v[58:59], v[56:57] op_sel:[1,0]
	v_mov_b32_e32 v59, v57
	v_pk_add_f32 v[56:57], v[70:71], v[58:59]
	v_pk_add_f32 v[60:61], v[60:61], v[60:61] op_sel_hi:[0,1]
	v_pk_add_f32 v[70:71], v[56:57], v[56:57] op_sel_hi:[0,1]
	v_mul_f32_e32 v56, v52, v52
	v_pk_fma_f32 v[72:73], v[52:53], v[52:53], v[56:57] op_sel_hi:[1,1,0]
	v_mul_f32_e32 v56, v54, v54
	v_pk_fma_f32 v[74:75], v[54:55], v[54:55], v[56:57] op_sel_hi:[1,1,0]
	v_pk_mul_f32 v[56:57], v[50:51], v[92:93] op_sel_hi:[1,0]
	v_pk_mul_f32 v[58:59], v[48:49], v[92:93] op_sel_hi:[1,0]
	v_mul_f32_e32 v60, v56, v56
	v_mul_f32_e32 v72, v58, v58
	v_mul_f32_e32 v74, v59, v59
	v_mul_f32_e32 v70, v57, v57
	v_pk_add_f32 v[48:49], v[72:73], v[74:75]
	v_pk_add_f32 v[50:51], v[60:61], v[70:71]
	v_mad_i64_i32 v[90:91], s[8:9], v88, s78, 0
	v_pk_add_f32 v[48:49], v[48:49], v[50:51]
	v_and_b32_e32 v50, 64, v188
	v_add_f32_e32 v48, v48, v49
	v_xor_b32_e32 v49, 16, v188
	v_add_u32_e32 v50, 64, v50
	v_cmp_lt_i32_e32 vcc, v49, v50
	s_mov_b64 s[10:11], s[82:83]
	s_nop 0
	v_cndmask_b32_e32 v49, v188, v49, vcc
	v_lshlrev_b32_e32 v49, 2, v49
	ds_bpermute_b32 v49, v49, v48
	s_waitcnt lgkmcnt(0)
	v_add_f32_e32 v48, v48, v49
	v_xor_b32_e32 v49, 32, v188
	v_cmp_lt_i32_e32 vcc, v49, v50
	s_nop 1
	v_cndmask_b32_e32 v49, v188, v49, vcc
	v_lshlrev_b32_e32 v49, 2, v49
	ds_bpermute_b32 v49, v49, v48
	s_waitcnt lgkmcnt(0)
; __device__ __forceinline__ unsigned cvt_pk_bf16(float lo, float hi) { unsigned r; asm("v_cvt_pk_bf16_f32 %0, %1, %2" : "=v"(r) : "v"(lo), "v"(hi)); return r; }
;     __device__ __forceinline__ void epi(Acc& acc, const Unit& u, int wr, int wc, int fr, int fq) const {
;     ...
;             for (int m = 0; m < 4; ++m) { const int row = u.pm * 256 + ai * 128 + rl0 + m * 16;
;                 const f32x4 q0 = *(const f32x4*)(SSQ + (size_t)row * 8), q1 = *(const f32x4*)(SSQ + (size_t)row * 8 + 4);
;                 const float rq = rsqrtf((((q0[0] + q0[1]) + (q0[2] + q0[3])) + ((q1[0] + q1[1]) + (q1[2] + q1[3]))) * (1.f / 384.f) + EPS);
;     ...
;                     const float r2 = rsqrtf(s * (1.f / 64.f) + EPS) * QSCALE;
; #pragma unroll
;                     for (int bj = 0; bj < 2; ++bj) { const f32x4 g0 = *(const f32x4*)(qng + bj * 32 + fq * 8), g1 = *(const f32x4*)(qng + bj * 32 + fq * 8 + 4);
;                         const f32x4 a = v[bj][0] * r2 * g0, b = v[bj][1] * r2 * g1;
;                         u32x4 w; w.x = cvt_pk_bf16(a[0], a[1]); w.y = cvt_pk_bf16(a[2], a[3]); w.z = cvt_pk_bf16(b[0], b[1]); w.w = cvt_pk_bf16(b[2], b[3]);
;                         *(u32x4*)(Q + (size_t)row * 768 + head * 96 + bj * 32 + fq * 8) = w; }
	v_add_f32_e32 v48, v48, v49
	v_fmamk_f32 v48, v48, 0x3c800000, v187
	v_cmp_gt_f32_e32 vcc, s45, v48
	v_mul_f32_e32 v49, 0x4b800000, v48
	s_nop 0
	v_cndmask_b32_e32 v48, v48, v49, vcc
	v_rsq_f32_e32 v48, v48
	s_nop 0
	v_mul_f32_e32 v49, 0x45800000, v48
	v_cndmask_b32_e32 v48, v48, v49, vcc
	v_mul_f32_e32 v60, 0x3e16c740, v48
	v_pk_mul_f32 v[62:63], v[62:63], v[60:61] op_sel_hi:[1,0]
	v_pk_mul_f32 v[68:69], v[68:69], v[60:61] op_sel_hi:[1,0]
	v_pk_mul_f32 v[66:67], v[66:67], v[60:61] op_sel_hi:[1,0]
	v_pk_mul_f32 v[64:65], v[64:65], v[60:61] op_sel_hi:[1,0]
	v_pk_mul_f32 v[52:53], v[52:53], v[60:61] op_sel_hi:[1,0]
	v_pk_mul_f32 v[54:55], v[54:55], v[60:61] op_sel_hi:[1,0]
	v_pk_mul_f32 v[58:59], v[58:59], v[60:61] op_sel_hi:[1,0]
	v_pk_mul_f32 v[56:57], v[56:57], v[60:61] op_sel_hi:[1,0]
	v_pk_mul_f32 v[66:67], v[218:219], v[66:67]
	v_pk_mul_f32 v[62:63], v[214:215], v[62:63]
	v_pk_mul_f32 v[50:51], v[216:217], v[68:69]
	v_cvt_pk_bf16_f32 v49, v62, v63
	v_mov_b64_e32 v[62:63], s[42:43]
	v_mad_i64_i32 v[62:63], s[8:9], v88, s78, v[62:63]
	v_lshl_add_u64 v[62:63], s[82:83], 1, v[62:63]
	v_lshl_add_u64 v[62:63], v[166:167], 1, v[62:63]
	v_pk_mul_f32 v[64:65], v[212:213], v[64:65]
	v_cvt_pk_bf16_f32 v50, v50, v51
	v_cvt_pk_bf16_f32 v51, v66, v67
	s_mov_b64 s[8:9], 64
	v_cvt_pk_bf16_f32 v48, v64, v65
	global_store_dwordx4 v[62:63], v[48:51], off
	s_nop 1
	v_pk_mul_f32 v[50:51], v[226:227], v[56:57]
	v_pk_mul_f32 v[54:55], v[222:223], v[54:55]
	v_pk_mul_f32 v[52:53], v[220:221], v[52:53]
	v_pk_mul_f32 v[48:49], v[224:225], v[58:59]
	v_cvt_pk_bf16_f32 v64, v52, v53
	v_cvt_pk_bf16_f32 v65, v54, v55
	v_cvt_pk_bf16_f32 v67, v50, v51
	s_nop 0
	v_cvt_pk_bf16_f32 v66, v48, v49
.LBB0_586:
	v_lshl_add_u64 v[48:49], s[42:43], 0, v[90:91]
	v_lshl_add_u64 v[48:49], s[10:11], 1, v[48:49]
	v_lshl_add_u64 v[48:49], v[48:49], 0, s[8:9]
	v_add_u32_e32 v72, 0x90, v170
	v_lshl_add_u64 v[48:49], v[166:167], 1, v[48:49]
	v_ashrrev_i32_e32 v73, 31, v72
	global_store_dwordx4 v[48:49], v[64:67], off
	v_lshlrev_b64 v[48:49], 5, v[72:73]
	v_lshl_add_u64 v[52:53], s[68:69], 0, v[48:49]
	s_and_b64 vcc, exec, s[4:5]
	s_mov_b64 s[10:11], -1
	s_waitcnt vmcnt(2)
	v_mov_b64_e32 v[48:49], v[230:231]
	v_mov_b64_e32 v[50:51], v[232:233]
	v_mov_b64_e32 v[52:53], v[234:235]
	v_mov_b64_e32 v[54:55], v[236:237]
	v_add_u32_e32 v228, 0xa0, v170
	v_ashrrev_i32_e32 v229, 31, v228
	v_lshlrev_b64 v[228:229], 5, v[228:229]
	v_lshl_add_u64 v[228:229], s[68:69], 0, v[228:229]
	global_load_dwordx4 v[230:233], v[228:229], off
	global_load_dwordx4 v[234:237], v[228:229], off offset:16
	v_mov_b32_e32 v56, v48
	v_mov_b32_e32 v57, v52
	v_mov_b32_e32 v52, v49
	v_mov_b32_e32 v48, v50
	v_mov_b32_e32 v49, v54
	v_mov_b32_e32 v54, v51
	v_pk_add_f32 v[50:51], v[56:57], v[52:53]
	v_pk_add_f32 v[48:49], v[48:49], v[54:55]
	s_nop 0
	v_pk_add_f32 v[48:49], v[50:51], v[48:49]
	s_nop 0
	v_add_f32_e32 v48, v48, v49
	v_fmamk_f32 v48, v48, 0x3b2aaaab, v187
	v_mul_f32_e32 v49, 0x4b800000, v48
	v_cmp_gt_f32_e64 s[8:9], s45, v48
	s_nop 1
	v_cndmask_b32_e64 v48, v48, v49, s[8:9]
	v_rsq_f32_e32 v48, v48
	s_nop 0
	v_mul_f32_e32 v49, 0x45800000, v48
	v_cndmask_b32_e64 v76, v48, v49, s[8:9]
	s_cbranch_vccnz .LBB0_588
	v_cmp_gt_i32_e32 vcc, s50, v72
	v_and_b32_e32 v48, 0xfff, v72
	v_mov_b32_e32 v173, v161
	v_cndmask_b32_e32 v48, v139, v48, vcc
	v_lshlrev_b32_e32 v160, 7, v48
	v_lshl_add_u64 v[48:49], s[76:77], 0, v[160:161]
	v_lshl_add_u64 v[56:57], v[48:49], 0, v[172:173]
	global_load_dwordx4 v[52:55], v[56:57], off offset:16
	global_load_dwordx4 v[60:63], v[56:57], off
	global_load_dwordx4 v[48:51], v[56:57], off offset:80
	s_nop 0
	global_load_dwordx4 v[56:59], v[56:57], off offset:64
	s_nop 0
	global_load_dwordx4 v[64:67], v[174:175], off offset:16
	global_load_dwordx4 v[68:71], v[174:175], off
	v_and_b32_e32 v74, 64, v188
	v_xor_b32_e32 v73, 16, v188
	v_add_u32_e32 v74, 64, v74
	v_cmp_lt_i32_e32 vcc, v73, v74
	s_mov_b64 s[10:11], 0
	s_nop 0
	v_cndmask_b32_e32 v73, v188, v73, vcc
	v_lshlrev_b32_e32 v77, 2, v73
	v_pk_mul_f32 v[78:79], v[46:47], v[76:77] op_sel_hi:[1,0]
	v_pk_mul_f32 v[80:81], v[44:45], v[76:77] op_sel_hi:[1,0]
	v_pk_mul_f32 v[86:87], v[78:79], v[78:79]
	v_pk_mul_f32 v[88:89], v[80:81], v[80:81]
	v_pk_mul_f32 v[82:83], v[42:43], v[76:77] op_sel_hi:[1,0]
	v_pk_mul_f32 v[84:85], v[40:41], v[76:77] op_sel_hi:[1,0]
	v_pk_mov_b32 v[90:91], v[88:89], v[86:87] op_sel:[1,0]
	v_mov_b32_e32 v89, v87
	v_pk_add_f32 v[86:87], v[90:91], v[88:89]
	v_pk_mul_f32 v[88:89], v[82:83], v[82:83]
	v_pk_mul_f32 v[90:91], v[84:85], v[84:85]
	v_mov_b32_e32 v92, v88
	v_mov_b32_e32 v93, v90
	v_mov_b32_e32 v90, v89
	v_pk_add_f32 v[88:89], v[92:93], v[90:91]
	v_add_f32_e32 v86, v86, v87
	v_add_f32_e32 v86, v89, v86
	v_add_f32_e32 v86, v88, v86
	ds_bpermute_b32 v87, v77, v86
	v_xor_b32_e32 v73, 32, v188
	v_cmp_lt_i32_e32 vcc, v73, v74
	v_mad_i64_i32 v[74:75], s[8:9], v72, s78, 0
	s_nop 0
	v_cndmask_b32_e32 v73, v188, v73, vcc
	v_lshlrev_b32_e32 v73, 2, v73
	s_waitcnt lgkmcnt(0)
	v_add_f32_e32 v86, v86, v87
	ds_bpermute_b32 v87, v73, v86
	s_waitcnt lgkmcnt(0)
	v_add_f32_e32 v86, v86, v87
	v_fmamk_f32 v86, v86, 0x3d000000, v187
	v_cmp_gt_f32_e32 vcc, s45, v86
	v_mul_f32_e32 v87, 0x4b800000, v86
	s_nop 0
	v_cndmask_b32_e32 v86, v86, v87, vcc
	v_rsq_f32_e32 v86, v86
	s_nop 0
	v_mul_f32_e32 v87, 0x45800000, v86
	v_cndmask_b32_e32 v86, v86, v87, vcc
	v_pk_mul_f32 v[80:81], v[80:81], v[86:87] op_sel_hi:[1,0]
	v_pk_mul_f32 v[78:79], v[78:79], v[86:87] op_sel_hi:[1,0]
	v_pk_mul_f32 v[84:85], v[84:85], v[86:87] op_sel_hi:[1,0]
	v_pk_mul_f32 v[82:83], v[82:83], v[86:87] op_sel_hi:[1,0]
	s_waitcnt vmcnt(1)
	v_pk_mul_f32 v[84:85], v[64:65], v[84:85]
	s_waitcnt vmcnt(0)
; __device__ __forceinline__ unsigned cvt_pk_bf16(float lo, float hi) { unsigned r; asm("v_cvt_pk_bf16_f32 %0, %1, %2" : "=v"(r) : "v"(lo), "v"(hi)); return r; }
;     __device__ __forceinline__ void epi(Acc& acc, const Unit& u, int wr, int wc, int fr, int fq) const {
;     ...
;                     for (int bj = 0; bj < 2; ++bj) { const int head = bj * 4 + wc;
;                         f32x4 v0 = acc[ai][bj][m][0] * rq, v1 = acc[ai][bj][m][1] * rq;
;                         float s = (v0[0] * v0[0] + v0[1] * v0[1]) + (v0[2] * v0[2] + v0[3] * v0[3]) + (v1[0] * v1[0] + v1[1] * v1[1]) + (v1[2] * v1[2] + v1[3] * v1[3]);
;                         s += __shfl_xor(s, 16); s += __shfl_xor(s, 32);
;                         const float r2 = rsqrtf(s * (1.f / 32.f) + EPS);
;                         v0 = v0 * r2 * g0; v1 = v1 * r2 * g1;
;                         f32x4 p0, p1;
; #pragma unroll
;                         for (int e = 0; e < 4; ++e) { p0[e] = __shfl_xor(v0[e], 32); p1[e] = __shfl_xor(v1[e], 32); }
;                         const f32x4 r0 = (v0 * c0 + p0 * s0 * sg) * QSCALE, r1 = (v1 * c1 + p1 * s1 * sg) * QSCALE;
;                         u32x4 w; w.x = cvt_pk_bf16(r0[0], r0[1]); w.y = cvt_pk_bf16(r0[2], r0[3]); w.z = cvt_pk_bf16(r1[0], r1[1]); w.w = cvt_pk_bf16(r1[2], r1[3]);
;                         *(u32x4*)(Q + (size_t)row * 768 + head * 96 + 64 + fq * 8) = w; }
	v_pk_mul_f32 v[80:81], v[68:69], v[80:81]
	v_pk_mul_f32 v[78:79], v[70:71], v[78:79]
	ds_bpermute_b32 v86, v73, v80
	ds_bpermute_b32 v87, v73, v81
	ds_bpermute_b32 v90, v73, v78
	ds_bpermute_b32 v91, v73, v79
	v_pk_mul_f32 v[82:83], v[66:67], v[82:83]
	ds_bpermute_b32 v88, v73, v84
	ds_bpermute_b32 v89, v73, v85
	ds_bpermute_b32 v92, v73, v82
	ds_bpermute_b32 v93, v73, v83
	v_pk_mul_f32 v[94:95], v[62:63], v[78:79]
	v_pk_mul_f32 v[78:79], v[60:61], v[80:81]
	s_waitcnt lgkmcnt(6)
	v_pk_mul_f32 v[86:87], v[56:57], v[86:87]
	s_waitcnt lgkmcnt(4)
	v_pk_mul_f32 v[80:81], v[58:59], v[90:91]
	v_pk_fma_f32 v[86:87], v[168:169], v[86:87], v[78:79]
	v_mov_b32_e32 v78, v168
	v_mov_b32_e32 v79, v168
	v_pk_fma_f32 v[80:81], v[78:79], v[80:81], v[94:95]
	v_pk_mul_f32 v[82:83], v[54:55], v[82:83]
	v_pk_mul_f32 v[90:91], v[80:81], s[52:53] op_sel_hi:[1,0]
	v_pk_mul_f32 v[80:81], v[86:87], s[52:53] op_sel_hi:[1,0]
	v_pk_mul_f32 v[84:85], v[52:53], v[84:85]
	s_waitcnt lgkmcnt(0)
	v_pk_mul_f32 v[86:87], v[50:51], v[92:93]
	v_pk_mul_f32 v[88:89], v[48:49], v[88:89]
	v_pk_fma_f32 v[82:83], v[78:79], v[86:87], v[82:83]
	v_pk_fma_f32 v[84:85], v[168:169], v[88:89], v[84:85]
	v_pk_mul_f32 v[86:87], v[82:83], s[52:53] op_sel_hi:[1,0]
	v_pk_mul_f32 v[82:83], v[84:85], s[52:53] op_sel_hi:[1,0]
	v_mov_b64_e32 v[84:85], s[64:65]
	v_mad_i64_i32 v[84:85], s[8:9], v72, s78, v[84:85]
	v_cvt_pk_bf16_f32 v80, v80, v81
	v_cvt_pk_bf16_f32 v81, v90, v91
	v_cvt_pk_bf16_f32 v82, v82, v83
	v_cvt_pk_bf16_f32 v83, v86, v87
	v_lshl_add_u64 v[84:85], v[166:167], 1, v[84:85]
	global_store_dwordx4 v[84:85], v[80:83], off offset:128
	v_pk_mul_f32 v[84:85], v[34:35], v[76:77] op_sel_hi:[1,0]
	v_pk_mul_f32 v[86:87], v[32:33], v[76:77] op_sel_hi:[1,0]
	v_pk_mul_f32 v[80:81], v[38:39], v[76:77] op_sel_hi:[1,0]
	v_pk_mul_f32 v[82:83], v[36:37], v[76:77] op_sel_hi:[1,0]
	v_pk_mul_f32 v[88:89], v[80:81], v[80:81]
	v_pk_mul_f32 v[90:91], v[82:83], v[82:83]
	s_nop 0
	v_pk_mov_b32 v[92:93], v[90:91], v[88:89] op_sel:[1,0]
	v_mov_b32_e32 v91, v89
	v_pk_add_f32 v[88:89], v[92:93], v[90:91]
	v_pk_mul_f32 v[90:91], v[84:85], v[84:85]
	v_pk_mul_f32 v[92:93], v[86:87], v[86:87]
	v_mov_b32_e32 v94, v90
	v_mov_b32_e32 v95, v92
	v_mov_b32_e32 v92, v91
	v_pk_add_f32 v[90:91], v[94:95], v[92:93]
	v_add_f32_e32 v88, v88, v89
	v_add_f32_e32 v88, v91, v88
	v_add_f32_e32 v88, v90, v88
	ds_bpermute_b32 v77, v77, v88
	s_waitcnt lgkmcnt(0)
	v_add_f32_e32 v77, v88, v77
	ds_bpermute_b32 v88, v73, v77
	s_waitcnt lgkmcnt(0)
	v_add_f32_e32 v77, v77, v88
	v_fmamk_f32 v77, v77, 0x3d000000, v187
	v_cmp_gt_f32_e32 vcc, s45, v77
	v_mul_f32_e32 v88, 0x4b800000, v77
	s_nop 0
	v_cndmask_b32_e32 v77, v77, v88, vcc
	v_rsq_f32_e32 v77, v77
	s_nop 0
	v_mul_f32_e32 v88, 0x45800000, v77
	v_cndmask_b32_e32 v88, v77, v88, vcc
	v_pk_mul_f32 v[82:83], v[82:83], v[88:89] op_sel_hi:[1,0]
	v_pk_mul_f32 v[80:81], v[80:81], v[88:89] op_sel_hi:[1,0]
	v_pk_mul_f32 v[68:69], v[68:69], v[82:83]
	v_pk_mul_f32 v[70:71], v[70:71], v[80:81]
	v_pk_mul_f32 v[80:81], v[86:87], v[88:89] op_sel_hi:[1,0]
	v_pk_mul_f32 v[82:83], v[84:85], v[88:89] op_sel_hi:[1,0]
	v_pk_mul_f32 v[64:65], v[64:65], v[80:81]
	v_pk_mul_f32 v[66:67], v[66:67], v[82:83]
	ds_bpermute_b32 v82, v73, v64
	ds_bpermute_b32 v83, v73, v65
	ds_bpermute_b32 v86, v73, v66
	ds_bpermute_b32 v87, v73, v67
	ds_bpermute_b32 v80, v73, v68
	ds_bpermute_b32 v81, v73, v69
	ds_bpermute_b32 v84, v73, v70
	ds_bpermute_b32 v85, v73, v71
	v_pk_mul_f32 v[54:55], v[54:55], v[66:67]
	v_pk_mul_f32 v[52:53], v[52:53], v[64:65]
	s_waitcnt lgkmcnt(4)
	v_pk_mul_f32 v[50:51], v[50:51], v[86:87]
	v_pk_mul_f32 v[48:49], v[48:49], v[82:83]
	v_pk_mul_f32 v[62:63], v[62:63], v[70:71]
	v_pk_mul_f32 v[60:61], v[60:61], v[68:69]
	s_waitcnt lgkmcnt(0)
	v_pk_mul_f32 v[58:59], v[58:59], v[84:85]
	v_pk_mul_f32 v[56:57], v[56:57], v[80:81]
	v_pk_fma_f32 v[48:49], v[168:169], v[48:49], v[52:53]
	v_pk_fma_f32 v[50:51], v[78:79], v[50:51], v[54:55]
	v_pk_fma_f32 v[56:57], v[168:169], v[56:57], v[60:61]
	v_pk_fma_f32 v[58:59], v[78:79], v[58:59], v[62:63]
	v_pk_mul_f32 v[52:53], v[50:51], s[52:53] op_sel_hi:[1,0]
	v_pk_mul_f32 v[50:51], v[48:49], s[52:53] op_sel_hi:[1,0]
	v_pk_mul_f32 v[58:59], v[58:59], s[52:53] op_sel_hi:[1,0]
	v_pk_mul_f32 v[56:57], v[56:57], s[52:53] op_sel_hi:[1,0]
	v_cvt_pk_bf16_f32 v49, v58, v59
	v_cvt_pk_bf16_f32 v50, v50, v51
	v_cvt_pk_bf16_f32 v51, v52, v53
	s_nop 0
	v_cvt_pk_bf16_f32 v48, v56, v57
; __device__ __forceinline__ unsigned cvt_pk_bf16(float lo, float hi) { unsigned r; asm("v_cvt_pk_bf16_f32 %0, %1, %2" : "=v"(r) : "v"(lo), "v"(hi)); return r; }
;     __device__ __forceinline__ void epi(Acc& acc, const Unit& u, int wr, int wc, int fr, int fq) const {
;     ...
;             for (int m = 0; m < 4; ++m) { const int row = u.pm * 256 + ai * 128 + rl0 + m * 16;
;                 const f32x4 q0 = *(const f32x4*)(SSQ + (size_t)row * 8), q1 = *(const f32x4*)(SSQ + (size_t)row * 8 + 4);
;                 const float rq = rsqrtf((((q0[0] + q0[1]) + (q0[2] + q0[3])) + ((q1[0] + q1[1]) + (q1[2] + q1[3]))) * (1.f / 384.f) + EPS);
;                 if (u.pn < 2) {
;                     const int head = u.pn * 4 + wc; float s = 0.f; f32x4 v[2][2];
; #pragma unroll
;                     for (int bj = 0; bj < 2; ++bj)
; #pragma unroll
;                         for (int n = 0; n < 2; ++n) { v[bj][n] = acc[ai][bj][m][n] * rq; const f32x4 x = v[bj][n]; s += (x[0] * x[0] + x[1] * x[1]) + (x[2] * x[2] + x[3] * x[3]); }
;                     s += __shfl_xor(s, 16); s += __shfl_xor(s, 32);
;                     const float r2 = rsqrtf(s * (1.f / 64.f) + EPS) * QSCALE;
; #pragma unroll
;                     for (int bj = 0; bj < 2; ++bj) { const f32x4 g0 = *(const f32x4*)(qng + bj * 32 + fq * 8), g1 = *(const f32x4*)(qng + bj * 32 + fq * 8 + 4);
;                         const f32x4 a = v[bj][0] * r2 * g0, b = v[bj][1] * r2 * g1;
;                         u32x4 w; w.x = cvt_pk_bf16(a[0], a[1]); w.y = cvt_pk_bf16(a[2], a[3]); w.z = cvt_pk_bf16(b[0], b[1]); w.w = cvt_pk_bf16(b[2], b[3]);
;                         *(u32x4*)(Q + (size_t)row * 768 + head * 96 + bj * 32 + fq * 8) = w; }
.LBB0_588:
	s_mov_b64 s[8:9], 0x380
	s_andn2_b64 vcc, exec, s[10:11]
	s_mov_b64 s[10:11], s[62:63]
	s_cbranch_vccnz .LBB0_590
	v_pk_mul_f32 v[46:47], v[46:47], v[76:77] op_sel_hi:[1,0]
	v_pk_mul_f32 v[48:49], v[44:45], v[76:77] op_sel_hi:[1,0]
	v_pk_mul_f32 v[44:45], v[46:47], v[46:47]
	v_pk_mul_f32 v[50:51], v[48:49], v[48:49]
	v_pk_mul_f32 v[36:37], v[36:37], v[76:77] op_sel_hi:[1,0]
	v_pk_mov_b32 v[52:53], v[50:51], v[44:45] op_sel:[1,0]
	v_mov_b32_e32 v51, v45
	v_pk_add_f32 v[44:45], v[52:53], v[50:51]
	v_pk_mul_f32 v[50:51], v[42:43], v[76:77] op_sel_hi:[1,0]
	v_pk_mul_f32 v[52:53], v[40:41], v[76:77] op_sel_hi:[1,0]
	v_pk_mul_f32 v[40:41], v[50:51], v[50:51]
	v_pk_mul_f32 v[42:43], v[52:53], v[52:53]
	v_pk_mul_f32 v[38:39], v[38:39], v[76:77] op_sel_hi:[1,0]
	v_pk_mov_b32 v[54:55], v[42:43], v[40:41] op_sel:[1,0]
	v_mov_b32_e32 v43, v41
	v_pk_add_f32 v[40:41], v[54:55], v[42:43]
	v_pk_add_f32 v[44:45], v[44:45], v[44:45] op_sel_hi:[0,1]
	v_pk_add_f32 v[54:55], v[40:41], v[40:41] op_sel_hi:[0,1]
	v_mul_f32_e32 v40, v36, v36
	v_pk_fma_f32 v[56:57], v[36:37], v[36:37], v[40:41] op_sel_hi:[1,1,0]
	v_mul_f32_e32 v40, v38, v38
	v_pk_fma_f32 v[58:59], v[38:39], v[38:39], v[40:41] op_sel_hi:[1,1,0]
	v_pk_mul_f32 v[40:41], v[34:35], v[76:77] op_sel_hi:[1,0]
	v_pk_mul_f32 v[42:43], v[32:33], v[76:77] op_sel_hi:[1,0]
	v_mul_f32_e32 v44, v40, v40
	v_mul_f32_e32 v56, v42, v42
	v_mul_f32_e32 v58, v43, v43
	v_mul_f32_e32 v54, v41, v41
	v_pk_add_f32 v[32:33], v[56:57], v[58:59]
	v_pk_add_f32 v[34:35], v[44:45], v[54:55]
	v_mad_i64_i32 v[74:75], s[8:9], v72, s78, 0
	v_pk_add_f32 v[32:33], v[32:33], v[34:35]
	v_and_b32_e32 v34, 64, v188
	v_add_f32_e32 v32, v32, v33
	v_xor_b32_e32 v33, 16, v188
	v_add_u32_e32 v34, 64, v34
	v_cmp_lt_i32_e32 vcc, v33, v34
	s_mov_b64 s[10:11], s[82:83]
	s_nop 0
	v_cndmask_b32_e32 v33, v188, v33, vcc
	v_lshlrev_b32_e32 v33, 2, v33
	ds_bpermute_b32 v33, v33, v32
	s_waitcnt lgkmcnt(0)
	v_add_f32_e32 v32, v32, v33
	v_xor_b32_e32 v33, 32, v188
	v_cmp_lt_i32_e32 vcc, v33, v34
	s_nop 1
	v_cndmask_b32_e32 v33, v188, v33, vcc
	v_lshlrev_b32_e32 v33, 2, v33
	ds_bpermute_b32 v33, v33, v32
	s_waitcnt lgkmcnt(0)
	v_add_f32_e32 v32, v32, v33
	v_fmamk_f32 v32, v32, 0x3c800000, v187
	v_cmp_gt_f32_e32 vcc, s45, v32
	v_mul_f32_e32 v33, 0x4b800000, v32
	s_nop 0
	v_cndmask_b32_e32 v32, v32, v33, vcc
	v_rsq_f32_e32 v32, v32
	s_nop 0
	v_mul_f32_e32 v33, 0x45800000, v32
	v_cndmask_b32_e32 v32, v32, v33, vcc
	v_mul_f32_e32 v44, 0x3e16c740, v32
	v_pk_mul_f32 v[46:47], v[46:47], v[44:45] op_sel_hi:[1,0]
	v_pk_mul_f32 v[52:53], v[52:53], v[44:45] op_sel_hi:[1,0]
	v_pk_mul_f32 v[50:51], v[50:51], v[44:45] op_sel_hi:[1,0]
	v_pk_mul_f32 v[48:49], v[48:49], v[44:45] op_sel_hi:[1,0]
	v_pk_mul_f32 v[36:37], v[36:37], v[44:45] op_sel_hi:[1,0]
	v_pk_mul_f32 v[38:39], v[38:39], v[44:45] op_sel_hi:[1,0]
	v_pk_mul_f32 v[42:43], v[42:43], v[44:45] op_sel_hi:[1,0]
	v_pk_mul_f32 v[40:41], v[40:41], v[44:45] op_sel_hi:[1,0]
	v_pk_mul_f32 v[50:51], v[218:219], v[50:51]
	v_pk_mul_f32 v[46:47], v[214:215], v[46:47]
	v_pk_mul_f32 v[34:35], v[216:217], v[52:53]
	v_cvt_pk_bf16_f32 v33, v46, v47
	v_mov_b64_e32 v[46:47], s[42:43]
	v_mad_i64_i32 v[46:47], s[8:9], v72, s78, v[46:47]
	v_lshl_add_u64 v[46:47], s[82:83], 1, v[46:47]
	v_lshl_add_u64 v[46:47], v[166:167], 1, v[46:47]
	v_pk_mul_f32 v[48:49], v[212:213], v[48:49]
	v_cvt_pk_bf16_f32 v34, v34, v35
	v_cvt_pk_bf16_f32 v35, v50, v51
	s_mov_b64 s[8:9], 64
	v_cvt_pk_bf16_f32 v32, v48, v49
	global_store_dwordx4 v[46:47], v[32:35], off
	s_nop 1
	v_pk_mul_f32 v[34:35], v[226:227], v[40:41]
	v_pk_mul_f32 v[38:39], v[222:223], v[38:39]
	v_pk_mul_f32 v[36:37], v[220:221], v[36:37]
	v_pk_mul_f32 v[32:33], v[224:225], v[42:43]
	v_cvt_pk_bf16_f32 v48, v36, v37
	v_cvt_pk_bf16_f32 v49, v38, v39
	v_cvt_pk_bf16_f32 v51, v34, v35
	s_nop 0
	v_cvt_pk_bf16_f32 v50, v32, v33
.LBB0_590:
	v_lshl_add_u64 v[32:33], s[42:43], 0, v[74:75]
	v_lshl_add_u64 v[32:33], s[10:11], 1, v[32:33]
	v_lshl_add_u64 v[32:33], v[32:33], 0, s[8:9]
	v_add_u32_e32 v56, 0xa0, v170
	v_lshl_add_u64 v[32:33], v[166:167], 1, v[32:33]
	v_ashrrev_i32_e32 v57, 31, v56
	global_store_dwordx4 v[32:33], v[48:51], off
	v_lshlrev_b64 v[32:33], 5, v[56:57]
	v_lshl_add_u64 v[36:37], s[68:69], 0, v[32:33]
	s_and_b64 vcc, exec, s[4:5]
	s_mov_b64 s[10:11], -1
	s_waitcnt vmcnt(2)
	v_mov_b64_e32 v[32:33], v[230:231]
	v_mov_b64_e32 v[34:35], v[232:233]
	v_mov_b64_e32 v[36:37], v[234:235]
	v_mov_b64_e32 v[38:39], v[236:237]
	v_add_u32_e32 v228, 0xb0, v170
	v_ashrrev_i32_e32 v229, 31, v228
	v_lshlrev_b64 v[228:229], 5, v[228:229]
	v_lshl_add_u64 v[228:229], s[68:69], 0, v[228:229]
	global_load_dwordx4 v[230:233], v[228:229], off
	global_load_dwordx4 v[234:237], v[228:229], off offset:16
	v_mov_b32_e32 v40, v32
	v_mov_b32_e32 v41, v36
	v_mov_b32_e32 v36, v33
	v_mov_b32_e32 v32, v34
	v_mov_b32_e32 v33, v38
	v_mov_b32_e32 v38, v35
	v_pk_add_f32 v[34:35], v[40:41], v[36:37]
	v_pk_add_f32 v[32:33], v[32:33], v[38:39]
	s_nop 0
	v_pk_add_f32 v[32:33], v[34:35], v[32:33]
	s_nop 0
	v_add_f32_e32 v32, v32, v33
	v_fmamk_f32 v32, v32, 0x3b2aaaab, v187
	v_mul_f32_e32 v33, 0x4b800000, v32
	v_cmp_gt_f32_e64 s[8:9], s45, v32
	s_nop 1
	v_cndmask_b32_e64 v32, v32, v33, s[8:9]
	v_rsq_f32_e32 v32, v32
	s_nop 0
	v_mul_f32_e32 v33, 0x45800000, v32
	v_cndmask_b32_e64 v60, v32, v33, s[8:9]
	s_cbranch_vccnz .LBB0_592
; __device__ __forceinline__ unsigned cvt_pk_bf16(float lo, float hi) { unsigned r; asm("v_cvt_pk_bf16_f32 %0, %1, %2" : "=v"(r) : "v"(lo), "v"(hi)); return r; }
;     __device__ __forceinline__ void epi(Acc& acc, const Unit& u, int wr, int wc, int fr, int fq) const {
;     ...
;                     const int pos = row < MP ? (row & 4095) : 2048 + ((row - MP) & 63);
;                     const float* rp = rope + (size_t)pos * 32 + (fq & 1) * 8;
;                     const f32x4 c0 = *(const f32x4*)rp, c1 = *(const f32x4*)(rp + 4), s0 = *(const f32x4*)(rp + 16), s1 = *(const f32x4*)(rp + 20);
;                     const f32x4 g0 = *(const f32x4*)(qrg + fq * 8), g1 = *(const f32x4*)(qrg + fq * 8 + 4);
;                     const float sg = fq < 2 ? -1.f : 1.f;
; #pragma unroll
;                     for (int bj = 0; bj < 2; ++bj) { const int head = bj * 4 + wc;
;                         f32x4 v0 = acc[ai][bj][m][0] * rq, v1 = acc[ai][bj][m][1] * rq;
;                         float s = (v0[0] * v0[0] + v0[1] * v0[1]) + (v0[2] * v0[2] + v0[3] * v0[3]) + (v1[0] * v1[0] + v1[1] * v1[1]) + (v1[2] * v1[2] + v1[3] * v1[3]);
;                         s += __shfl_xor(s, 16); s += __shfl_xor(s, 32);
;                         const float r2 = rsqrtf(s * (1.f / 32.f) + EPS);
;                         v0 = v0 * r2 * g0; v1 = v1 * r2 * g1;
;                         f32x4 p0, p1;
; #pragma unroll
;                         for (int e = 0; e < 4; ++e) { p0[e] = __shfl_xor(v0[e], 32); p1[e] = __shfl_xor(v1[e], 32); }
;                         const f32x4 r0 = (v0 * c0 + p0 * s0 * sg) * QSCALE, r1 = (v1 * c1 + p1 * s1 * sg) * QSCALE;
;                         u32x4 w; w.x = cvt_pk_bf16(r0[0], r0[1]); w.y = cvt_pk_bf16(r0[2], r0[3]); w.z = cvt_pk_bf16(r1[0], r1[1]); w.w = cvt_pk_bf16(r1[2], r1[3]);
;                         *(u32x4*)(Q + (size_t)row * 768 + head * 96 + 64 + fq * 8) = w; }
	v_cmp_gt_i32_e32 vcc, s50, v56
	v_and_b32_e32 v32, 0xfff, v56
	v_mov_b32_e32 v173, v161
	v_cndmask_b32_e32 v32, v121, v32, vcc
	v_lshlrev_b32_e32 v160, 7, v32
	v_lshl_add_u64 v[32:33], s[76:77], 0, v[160:161]
	v_lshl_add_u64 v[40:41], v[32:33], 0, v[172:173]
	global_load_dwordx4 v[36:39], v[40:41], off offset:16
	global_load_dwordx4 v[44:47], v[40:41], off
	global_load_dwordx4 v[32:35], v[40:41], off offset:80
	s_nop 0
	global_load_dwordx4 v[40:43], v[40:41], off offset:64
	s_nop 0
	global_load_dwordx4 v[48:51], v[174:175], off offset:16
	global_load_dwordx4 v[52:55], v[174:175], off
	v_and_b32_e32 v58, 64, v188
	v_xor_b32_e32 v57, 16, v188
	v_add_u32_e32 v58, 64, v58
	v_cmp_lt_i32_e32 vcc, v57, v58
	s_mov_b64 s[10:11], 0
	s_nop 0
	v_cndmask_b32_e32 v57, v188, v57, vcc
	v_lshlrev_b32_e32 v61, 2, v57
	v_pk_mul_f32 v[62:63], v[30:31], v[60:61] op_sel_hi:[1,0]
	v_pk_mul_f32 v[64:65], v[28:29], v[60:61] op_sel_hi:[1,0]
	v_pk_mul_f32 v[70:71], v[62:63], v[62:63]
	v_pk_mul_f32 v[72:73], v[64:65], v[64:65]
	v_pk_mul_f32 v[66:67], v[26:27], v[60:61] op_sel_hi:[1,0]
	v_pk_mul_f32 v[68:69], v[24:25], v[60:61] op_sel_hi:[1,0]
	v_pk_mov_b32 v[74:75], v[72:73], v[70:71] op_sel:[1,0]
	v_mov_b32_e32 v73, v71
	v_pk_add_f32 v[70:71], v[74:75], v[72:73]
	v_pk_mul_f32 v[72:73], v[66:67], v[66:67]
	v_pk_mul_f32 v[74:75], v[68:69], v[68:69]
	v_mov_b32_e32 v76, v72
	v_mov_b32_e32 v77, v74
	v_mov_b32_e32 v74, v73
	v_pk_add_f32 v[72:73], v[76:77], v[74:75]
	v_add_f32_e32 v70, v70, v71
	v_add_f32_e32 v70, v73, v70
	v_add_f32_e32 v70, v72, v70
	ds_bpermute_b32 v71, v61, v70
	v_xor_b32_e32 v57, 32, v188
	v_cmp_lt_i32_e32 vcc, v57, v58
	v_mad_i64_i32 v[58:59], s[8:9], v56, s78, 0
	s_nop 0
	v_cndmask_b32_e32 v57, v188, v57, vcc
	v_lshlrev_b32_e32 v57, 2, v57
	s_waitcnt lgkmcnt(0)
	v_add_f32_e32 v70, v70, v71
	ds_bpermute_b32 v71, v57, v70
	s_waitcnt lgkmcnt(0)
	v_add_f32_e32 v70, v70, v71
	v_fmamk_f32 v70, v70, 0x3d000000, v187
	v_cmp_gt_f32_e32 vcc, s45, v70
	v_mul_f32_e32 v71, 0x4b800000, v70
	s_nop 0
	v_cndmask_b32_e32 v70, v70, v71, vcc
	v_rsq_f32_e32 v70, v70
	s_nop 0
	v_mul_f32_e32 v71, 0x45800000, v70
	v_cndmask_b32_e32 v70, v70, v71, vcc
	v_pk_mul_f32 v[64:65], v[64:65], v[70:71] op_sel_hi:[1,0]
	v_pk_mul_f32 v[62:63], v[62:63], v[70:71] op_sel_hi:[1,0]
	v_pk_mul_f32 v[68:69], v[68:69], v[70:71] op_sel_hi:[1,0]
	v_pk_mul_f32 v[66:67], v[66:67], v[70:71] op_sel_hi:[1,0]
	s_waitcnt vmcnt(1)
	v_pk_mul_f32 v[68:69], v[48:49], v[68:69]
	s_waitcnt vmcnt(0)
	v_pk_mul_f32 v[64:65], v[52:53], v[64:65]
	v_pk_mul_f32 v[62:63], v[54:55], v[62:63]
	ds_bpermute_b32 v70, v57, v64
	ds_bpermute_b32 v71, v57, v65
	ds_bpermute_b32 v74, v57, v62
	ds_bpermute_b32 v75, v57, v63
	v_pk_mul_f32 v[66:67], v[50:51], v[66:67]
	ds_bpermute_b32 v72, v57, v68
	ds_bpermute_b32 v73, v57, v69
	ds_bpermute_b32 v76, v57, v66
	ds_bpermute_b32 v77, v57, v67
	v_pk_mul_f32 v[78:79], v[46:47], v[62:63]
	v_pk_mul_f32 v[62:63], v[44:45], v[64:65]
	s_waitcnt lgkmcnt(6)
	v_pk_mul_f32 v[70:71], v[40:41], v[70:71]
	s_waitcnt lgkmcnt(4)
	v_pk_mul_f32 v[64:65], v[42:43], v[74:75]
	v_pk_fma_f32 v[70:71], v[168:169], v[70:71], v[62:63]
	v_mov_b32_e32 v62, v168
	v_mov_b32_e32 v63, v168
	v_pk_fma_f32 v[64:65], v[62:63], v[64:65], v[78:79]
	v_pk_mul_f32 v[66:67], v[38:39], v[66:67]
	v_pk_mul_f32 v[74:75], v[64:65], s[52:53] op_sel_hi:[1,0]
	v_pk_mul_f32 v[64:65], v[70:71], s[52:53] op_sel_hi:[1,0]
	v_pk_mul_f32 v[68:69], v[36:37], v[68:69]
	s_waitcnt lgkmcnt(0)
	v_pk_mul_f32 v[70:71], v[34:35], v[76:77]
	v_pk_mul_f32 v[72:73], v[32:33], v[72:73]
	v_pk_fma_f32 v[66:67], v[62:63], v[70:71], v[66:67]
	v_pk_fma_f32 v[68:69], v[168:169], v[72:73], v[68:69]
	v_pk_mul_f32 v[70:71], v[66:67], s[52:53] op_sel_hi:[1,0]
	v_pk_mul_f32 v[66:67], v[68:69], s[52:53] op_sel_hi:[1,0]
	v_mov_b64_e32 v[68:69], s[64:65]
	v_mad_i64_i32 v[68:69], s[8:9], v56, s78, v[68:69]
	v_cvt_pk_bf16_f32 v64, v64, v65
	v_cvt_pk_bf16_f32 v65, v74, v75
	v_cvt_pk_bf16_f32 v66, v66, v67
	v_cvt_pk_bf16_f32 v67, v70, v71
	v_lshl_add_u64 v[68:69], v[166:167], 1, v[68:69]
	global_store_dwordx4 v[68:69], v[64:67], off offset:128
	v_pk_mul_f32 v[68:69], v[18:19], v[60:61] op_sel_hi:[1,0]
	v_pk_mul_f32 v[70:71], v[16:17], v[60:61] op_sel_hi:[1,0]
	v_pk_mul_f32 v[64:65], v[22:23], v[60:61] op_sel_hi:[1,0]
	v_pk_mul_f32 v[66:67], v[20:21], v[60:61] op_sel_hi:[1,0]
	v_pk_mul_f32 v[72:73], v[64:65], v[64:65]
	v_pk_mul_f32 v[74:75], v[66:67], v[66:67]
	s_nop 0
	v_pk_mov_b32 v[76:77], v[74:75], v[72:73] op_sel:[1,0]
	v_mov_b32_e32 v75, v73
	v_pk_add_f32 v[72:73], v[76:77], v[74:75]
	v_pk_mul_f32 v[74:75], v[68:69], v[68:69]
	v_pk_mul_f32 v[76:77], v[70:71], v[70:71]
	v_mov_b32_e32 v78, v74
	v_mov_b32_e32 v79, v76
	v_mov_b32_e32 v76, v75
	v_pk_add_f32 v[74:75], v[78:79], v[76:77]
	v_add_f32_e32 v72, v72, v73
	v_add_f32_e32 v72, v75, v72
	v_add_f32_e32 v72, v74, v72
	ds_bpermute_b32 v61, v61, v72
	s_waitcnt lgkmcnt(0)
	v_add_f32_e32 v61, v72, v61
	ds_bpermute_b32 v72, v57, v61
	s_waitcnt lgkmcnt(0)
	v_add_f32_e32 v61, v61, v72
	v_fmamk_f32 v61, v61, 0x3d000000, v187
	v_cmp_gt_f32_e32 vcc, s45, v61
	v_mul_f32_e32 v72, 0x4b800000, v61
	s_nop 0
	v_cndmask_b32_e32 v61, v61, v72, vcc
	v_rsq_f32_e32 v61, v61
	s_nop 0
	v_mul_f32_e32 v72, 0x45800000, v61
	v_cndmask_b32_e32 v72, v61, v72, vcc
	v_pk_mul_f32 v[66:67], v[66:67], v[72:73] op_sel_hi:[1,0]
	v_pk_mul_f32 v[64:65], v[64:65], v[72:73] op_sel_hi:[1,0]
	v_pk_mul_f32 v[52:53], v[52:53], v[66:67]
	v_pk_mul_f32 v[54:55], v[54:55], v[64:65]
	v_pk_mul_f32 v[64:65], v[70:71], v[72:73] op_sel_hi:[1,0]
	v_pk_mul_f32 v[66:67], v[68:69], v[72:73] op_sel_hi:[1,0]
	v_pk_mul_f32 v[48:49], v[48:49], v[64:65]
	v_pk_mul_f32 v[50:51], v[50:51], v[66:67]
	ds_bpermute_b32 v66, v57, v48
	ds_bpermute_b32 v67, v57, v49
	ds_bpermute_b32 v70, v57, v50
	ds_bpermute_b32 v71, v57, v51
	ds_bpermute_b32 v64, v57, v52
	ds_bpermute_b32 v65, v57, v53
	ds_bpermute_b32 v68, v57, v54
	ds_bpermute_b32 v69, v57, v55
	v_pk_mul_f32 v[38:39], v[38:39], v[50:51]
	v_pk_mul_f32 v[36:37], v[36:37], v[48:49]
	s_waitcnt lgkmcnt(4)
	v_pk_mul_f32 v[34:35], v[34:35], v[70:71]
	v_pk_mul_f32 v[32:33], v[32:33], v[66:67]
	v_pk_mul_f32 v[46:47], v[46:47], v[54:55]
	v_pk_mul_f32 v[44:45], v[44:45], v[52:53]
	s_waitcnt lgkmcnt(0)
	v_pk_mul_f32 v[42:43], v[42:43], v[68:69]
	v_pk_mul_f32 v[40:41], v[40:41], v[64:65]
	v_pk_fma_f32 v[32:33], v[168:169], v[32:33], v[36:37]
	v_pk_fma_f32 v[34:35], v[62:63], v[34:35], v[38:39]
	v_pk_fma_f32 v[40:41], v[168:169], v[40:41], v[44:45]
	v_pk_fma_f32 v[42:43], v[62:63], v[42:43], v[46:47]
	v_pk_mul_f32 v[36:37], v[34:35], s[52:53] op_sel_hi:[1,0]
	v_pk_mul_f32 v[34:35], v[32:33], s[52:53] op_sel_hi:[1,0]
	v_pk_mul_f32 v[42:43], v[42:43], s[52:53] op_sel_hi:[1,0]
	v_pk_mul_f32 v[40:41], v[40:41], s[52:53] op_sel_hi:[1,0]
	v_cvt_pk_bf16_f32 v33, v42, v43
	v_cvt_pk_bf16_f32 v34, v34, v35
	v_cvt_pk_bf16_f32 v35, v36, v37
	s_nop 0
	v_cvt_pk_bf16_f32 v32, v40, v41
; __device__ __forceinline__ unsigned cvt_pk_bf16(float lo, float hi) { unsigned r; asm("v_cvt_pk_bf16_f32 %0, %1, %2" : "=v"(r) : "v"(lo), "v"(hi)); return r; }
;     __device__ __forceinline__ void epi(Acc& acc, const Unit& u, int wr, int wc, int fr, int fq) const {
;     ...
;             for (int m = 0; m < 4; ++m) { const int row = u.pm * 256 + ai * 128 + rl0 + m * 16;
;                 const f32x4 q0 = *(const f32x4*)(SSQ + (size_t)row * 8), q1 = *(const f32x4*)(SSQ + (size_t)row * 8 + 4);
;                 const float rq = rsqrtf((((q0[0] + q0[1]) + (q0[2] + q0[3])) + ((q1[0] + q1[1]) + (q1[2] + q1[3]))) * (1.f / 384.f) + EPS);
;                 if (u.pn < 2) {
;                     const int head = u.pn * 4 + wc; float s = 0.f; f32x4 v[2][2];
; #pragma unroll
;                     for (int bj = 0; bj < 2; ++bj)
; #pragma unroll
;                         for (int n = 0; n < 2; ++n) { v[bj][n] = acc[ai][bj][m][n] * rq; const f32x4 x = v[bj][n]; s += (x[0] * x[0] + x[1] * x[1]) + (x[2] * x[2] + x[3] * x[3]); }
;                     s += __shfl_xor(s, 16); s += __shfl_xor(s, 32);
;                     const float r2 = rsqrtf(s * (1.f / 64.f) + EPS) * QSCALE;
; #pragma unroll
;                     for (int bj = 0; bj < 2; ++bj) { const f32x4 g0 = *(const f32x4*)(qng + bj * 32 + fq * 8), g1 = *(const f32x4*)(qng + bj * 32 + fq * 8 + 4);
;                         const f32x4 a = v[bj][0] * r2 * g0, b = v[bj][1] * r2 * g1;
;                         u32x4 w; w.x = cvt_pk_bf16(a[0], a[1]); w.y = cvt_pk_bf16(a[2], a[3]); w.z = cvt_pk_bf16(b[0], b[1]); w.w = cvt_pk_bf16(b[2], b[3]);
;                         *(u32x4*)(Q + (size_t)row * 768 + head * 96 + bj * 32 + fq * 8) = w; }
.LBB0_592:
	s_mov_b64 s[8:9], 0x380
	s_andn2_b64 vcc, exec, s[10:11]
	s_mov_b64 s[10:11], s[62:63]
	s_cbranch_vccnz .LBB0_594
	v_pk_mul_f32 v[30:31], v[30:31], v[60:61] op_sel_hi:[1,0]
	v_pk_mul_f32 v[32:33], v[28:29], v[60:61] op_sel_hi:[1,0]
	v_pk_mul_f32 v[28:29], v[30:31], v[30:31]
	v_pk_mul_f32 v[34:35], v[32:33], v[32:33]
	v_pk_mul_f32 v[20:21], v[20:21], v[60:61] op_sel_hi:[1,0]
	v_pk_mov_b32 v[36:37], v[34:35], v[28:29] op_sel:[1,0]
	v_mov_b32_e32 v35, v29
	v_pk_add_f32 v[28:29], v[36:37], v[34:35]
	v_pk_mul_f32 v[34:35], v[26:27], v[60:61] op_sel_hi:[1,0]
	v_pk_mul_f32 v[36:37], v[24:25], v[60:61] op_sel_hi:[1,0]
	v_pk_mul_f32 v[24:25], v[34:35], v[34:35]
	v_pk_mul_f32 v[26:27], v[36:37], v[36:37]
	v_pk_mul_f32 v[22:23], v[22:23], v[60:61] op_sel_hi:[1,0]
	v_pk_mov_b32 v[38:39], v[26:27], v[24:25] op_sel:[1,0]
	v_mov_b32_e32 v27, v25
	v_pk_add_f32 v[24:25], v[38:39], v[26:27]
	v_pk_add_f32 v[28:29], v[28:29], v[28:29] op_sel_hi:[0,1]
	v_pk_add_f32 v[38:39], v[24:25], v[24:25] op_sel_hi:[0,1]
	v_mul_f32_e32 v24, v20, v20
	v_pk_fma_f32 v[40:41], v[20:21], v[20:21], v[24:25] op_sel_hi:[1,1,0]
	v_mul_f32_e32 v24, v22, v22
	v_pk_fma_f32 v[42:43], v[22:23], v[22:23], v[24:25] op_sel_hi:[1,1,0]
	v_pk_mul_f32 v[24:25], v[18:19], v[60:61] op_sel_hi:[1,0]
	v_pk_mul_f32 v[26:27], v[16:17], v[60:61] op_sel_hi:[1,0]
	v_mul_f32_e32 v28, v24, v24
	v_mul_f32_e32 v40, v26, v26
	v_mul_f32_e32 v42, v27, v27
	v_mul_f32_e32 v38, v25, v25
	v_pk_add_f32 v[16:17], v[40:41], v[42:43]
	v_pk_add_f32 v[18:19], v[28:29], v[38:39]
	v_mad_i64_i32 v[58:59], s[8:9], v56, s78, 0
	v_pk_add_f32 v[16:17], v[16:17], v[18:19]
	v_and_b32_e32 v18, 64, v188
	v_add_f32_e32 v16, v16, v17
	v_xor_b32_e32 v17, 16, v188
	v_add_u32_e32 v18, 64, v18
	v_cmp_lt_i32_e32 vcc, v17, v18
	s_mov_b64 s[10:11], s[82:83]
	s_nop 0
	v_cndmask_b32_e32 v17, v188, v17, vcc
	v_lshlrev_b32_e32 v17, 2, v17
	ds_bpermute_b32 v17, v17, v16
	s_waitcnt lgkmcnt(0)
	v_add_f32_e32 v16, v16, v17
	v_xor_b32_e32 v17, 32, v188
	v_cmp_lt_i32_e32 vcc, v17, v18
	s_nop 1
	v_cndmask_b32_e32 v17, v188, v17, vcc
	v_lshlrev_b32_e32 v17, 2, v17
	ds_bpermute_b32 v17, v17, v16
	s_waitcnt lgkmcnt(0)
	v_add_f32_e32 v16, v16, v17
	v_fmamk_f32 v16, v16, 0x3c800000, v187
	v_cmp_gt_f32_e32 vcc, s45, v16
	v_mul_f32_e32 v17, 0x4b800000, v16
	s_nop 0
	v_cndmask_b32_e32 v16, v16, v17, vcc
	v_rsq_f32_e32 v16, v16
	s_nop 0
	v_mul_f32_e32 v17, 0x45800000, v16
	v_cndmask_b32_e32 v16, v16, v17, vcc
	v_mul_f32_e32 v28, 0x3e16c740, v16
	v_pk_mul_f32 v[30:31], v[30:31], v[28:29] op_sel_hi:[1,0]
	v_pk_mul_f32 v[36:37], v[36:37], v[28:29] op_sel_hi:[1,0]
	v_pk_mul_f32 v[34:35], v[34:35], v[28:29] op_sel_hi:[1,0]
	v_pk_mul_f32 v[32:33], v[32:33], v[28:29] op_sel_hi:[1,0]
	v_pk_mul_f32 v[20:21], v[20:21], v[28:29] op_sel_hi:[1,0]
	v_pk_mul_f32 v[22:23], v[22:23], v[28:29] op_sel_hi:[1,0]
	v_pk_mul_f32 v[26:27], v[26:27], v[28:29] op_sel_hi:[1,0]
	v_pk_mul_f32 v[24:25], v[24:25], v[28:29] op_sel_hi:[1,0]
	v_pk_mul_f32 v[34:35], v[218:219], v[34:35]
	v_pk_mul_f32 v[30:31], v[214:215], v[30:31]
	v_pk_mul_f32 v[18:19], v[216:217], v[36:37]
	v_cvt_pk_bf16_f32 v17, v30, v31
	v_mov_b64_e32 v[30:31], s[42:43]
	v_mad_i64_i32 v[30:31], s[8:9], v56, s78, v[30:31]
	v_lshl_add_u64 v[30:31], s[82:83], 1, v[30:31]
	v_lshl_add_u64 v[30:31], v[166:167], 1, v[30:31]
	v_pk_mul_f32 v[32:33], v[212:213], v[32:33]
	v_cvt_pk_bf16_f32 v18, v18, v19
	v_cvt_pk_bf16_f32 v19, v34, v35
	s_mov_b64 s[8:9], 64
	v_cvt_pk_bf16_f32 v16, v32, v33
	global_store_dwordx4 v[30:31], v[16:19], off
	s_nop 1
	v_pk_mul_f32 v[18:19], v[226:227], v[24:25]
	v_pk_mul_f32 v[22:23], v[222:223], v[22:23]
	v_pk_mul_f32 v[20:21], v[220:221], v[20:21]
	v_pk_mul_f32 v[16:17], v[224:225], v[26:27]
	v_cvt_pk_bf16_f32 v32, v20, v21
	v_cvt_pk_bf16_f32 v33, v22, v23
	v_cvt_pk_bf16_f32 v35, v18, v19
	s_nop 0
	v_cvt_pk_bf16_f32 v34, v16, v17
.LBB0_594:
	v_lshl_add_u64 v[16:17], s[42:43], 0, v[58:59]
	v_lshl_add_u64 v[16:17], s[10:11], 1, v[16:17]
	v_lshl_add_u64 v[16:17], v[16:17], 0, s[8:9]
	v_add_u32_e32 v28, 0xb0, v170
	v_lshl_add_u64 v[16:17], v[166:167], 1, v[16:17]
	v_ashrrev_i32_e32 v29, 31, v28
	global_store_dwordx4 v[16:17], v[32:35], off
	v_lshlrev_b64 v[16:17], 5, v[28:29]
	v_lshl_add_u64 v[20:21], s[68:69], 0, v[16:17]
	s_and_b64 vcc, exec, s[4:5]
	s_waitcnt vmcnt(2)
	v_mov_b64_e32 v[16:17], v[230:231]
	v_mov_b64_e32 v[18:19], v[232:233]
	v_mov_b64_e32 v[20:21], v[234:235]
	v_mov_b64_e32 v[22:23], v[236:237]
	v_mov_b32_e32 v24, v16
	v_mov_b32_e32 v25, v20
	v_mov_b32_e32 v20, v17
	v_mov_b32_e32 v16, v18
	v_mov_b32_e32 v17, v22
	v_mov_b32_e32 v22, v19
	v_pk_add_f32 v[18:19], v[24:25], v[20:21]
	v_pk_add_f32 v[16:17], v[16:17], v[22:23]
	s_nop 0
	v_pk_add_f32 v[16:17], v[18:19], v[16:17]
	s_nop 0
	v_add_f32_e32 v16, v16, v17
	v_fmamk_f32 v16, v16, 0x3b2aaaab, v187
	v_mul_f32_e32 v17, 0x4b800000, v16
	v_cmp_gt_f32_e64 s[8:9], s45, v16
	s_nop 1
	v_cndmask_b32_e64 v16, v16, v17, s[8:9]
	v_rsq_f32_e32 v16, v16
	s_nop 0
	v_mul_f32_e32 v17, 0x45800000, v16
	v_cndmask_b32_e64 v30, v16, v17, s[8:9]
	s_mov_b64 s[8:9], -1
	s_cbranch_vccnz .LBB0_596
; __device__ __forceinline__ unsigned cvt_pk_bf16(float lo, float hi) { unsigned r; asm("v_cvt_pk_bf16_f32 %0, %1, %2" : "=v"(r) : "v"(lo), "v"(hi)); return r; }
;     __device__ __forceinline__ void epi(Acc& acc, const Unit& u, int wr, int wc, int fr, int fq) const {
;     ...
;                     const int pos = row < MP ? (row & 4095) : 2048 + ((row - MP) & 63);
;                     const float* rp = rope + (size_t)pos * 32 + (fq & 1) * 8;
;                     const f32x4 c0 = *(const f32x4*)rp, c1 = *(const f32x4*)(rp + 4), s0 = *(const f32x4*)(rp + 16), s1 = *(const f32x4*)(rp + 20);
;                     const f32x4 g0 = *(const f32x4*)(qrg + fq * 8), g1 = *(const f32x4*)(qrg + fq * 8 + 4);
;                     const float sg = fq < 2 ? -1.f : 1.f;
; #pragma unroll
;                     for (int bj = 0; bj < 2; ++bj) { const int head = bj * 4 + wc;
;                         f32x4 v0 = acc[ai][bj][m][0] * rq, v1 = acc[ai][bj][m][1] * rq;
;                         float s = (v0[0] * v0[0] + v0[1] * v0[1]) + (v0[2] * v0[2] + v0[3] * v0[3]) + (v1[0] * v1[0] + v1[1] * v1[1]) + (v1[2] * v1[2] + v1[3] * v1[3]);
;                         s += __shfl_xor(s, 16); s += __shfl_xor(s, 32);
;                         const float r2 = rsqrtf(s * (1.f / 32.f) + EPS);
;                         v0 = v0 * r2 * g0; v1 = v1 * r2 * g1;
;                         f32x4 p0, p1;
; #pragma unroll
;                         for (int e = 0; e < 4; ++e) { p0[e] = __shfl_xor(v0[e], 32); p1[e] = __shfl_xor(v1[e], 32); }
;                         const f32x4 r0 = (v0 * c0 + p0 * s0 * sg) * QSCALE, r1 = (v1 * c1 + p1 * s1 * sg) * QSCALE;
;                         u32x4 w; w.x = cvt_pk_bf16(r0[0], r0[1]); w.y = cvt_pk_bf16(r0[2], r0[3]); w.z = cvt_pk_bf16(r1[0], r1[1]); w.w = cvt_pk_bf16(r1[2], r1[3]);
;                         *(u32x4*)(Q + (size_t)row * 768 + head * 96 + 64 + fq * 8) = w; }
	global_load_dwordx4 v[34:37], v[174:175], off
	global_load_dwordx4 v[38:41], v[174:175], off offset:16
	v_and_b32_e32 v16, 0xfff, v28
	v_cmp_gt_i32_e32 vcc, s50, v28
	v_mov_b32_e32 v173, v161
	v_and_b32_e32 v31, 64, v188
	v_cndmask_b32_e32 v16, v105, v16, vcc
	v_lshlrev_b32_e32 v160, 7, v16
	v_lshl_add_u64 v[16:17], s[76:77], 0, v[160:161]
	v_lshl_add_u64 v[16:17], v[16:17], 0, v[172:173]
	global_load_dwordx4 v[42:45], v[16:17], off
	global_load_dwordx4 v[20:23], v[16:17], off offset:16
	global_load_dwordx4 v[24:27], v[16:17], off offset:64
	s_nop 0
	global_load_dwordx4 v[16:19], v[16:17], off offset:80
	v_pk_mul_f32 v[46:47], v[14:15], v[30:31] op_sel_hi:[1,0]
	v_pk_mul_f32 v[48:49], v[12:13], v[30:31] op_sel_hi:[1,0]
	v_pk_mul_f32 v[50:51], v[10:11], v[30:31] op_sel_hi:[1,0]
	v_pk_mul_f32 v[52:53], v[8:9], v[30:31] op_sel_hi:[1,0]
	v_pk_mul_f32 v[32:33], v[46:47], v[46:47]
	v_pk_mul_f32 v[54:55], v[48:49], v[48:49]
	v_pk_mul_f32 v[56:57], v[50:51], v[50:51]
	v_pk_mul_f32 v[58:59], v[52:53], v[52:53]
	v_pk_mov_b32 v[60:61], v[54:55], v[32:33] op_sel:[1,0]
	v_mov_b32_e32 v55, v33
	v_xor_b32_e32 v29, 16, v188
	v_add_u32_e32 v31, 64, v31
	v_mov_b32_e32 v32, v56
	v_mov_b32_e32 v33, v58
	v_mov_b32_e32 v58, v57
	v_pk_add_f32 v[54:55], v[60:61], v[54:55]
	v_cmp_lt_i32_e32 vcc, v29, v31
	v_pk_add_f32 v[32:33], v[32:33], v[58:59]
	v_add_f32_e32 v54, v54, v55
	v_cndmask_b32_e32 v29, v188, v29, vcc
	v_add_f32_e32 v33, v33, v54
	v_lshlrev_b32_e32 v29, 2, v29
	v_add_f32_e32 v32, v32, v33
	ds_bpermute_b32 v33, v29, v32
	v_xor_b32_e32 v54, 32, v188
	v_cmp_lt_i32_e32 vcc, v54, v31
	v_mov_b32_e32 v55, v168
	s_mov_b64 s[8:9], 0
	v_cndmask_b32_e32 v31, v188, v54, vcc
	v_lshlrev_b32_e32 v31, 2, v31
	s_waitcnt lgkmcnt(0)
	v_add_f32_e32 v58, v32, v33
	ds_bpermute_b32 v59, v31, v58
	v_mov_b32_e32 v54, v168
	v_pk_mul_f32 v[56:57], v[6:7], v[30:31] op_sel_hi:[1,0]
	v_pk_mul_f32 v[60:61], v[2:3], v[30:31] op_sel_hi:[1,0]
	v_pk_mul_f32 v[62:63], v[0:1], v[30:31] op_sel_hi:[1,0]
	s_waitcnt lgkmcnt(0)
	v_add_f32_e32 v58, v58, v59
	v_fmamk_f32 v58, v58, 0x3d000000, v187
	v_mul_f32_e32 v59, 0x4b800000, v58
	v_cmp_gt_f32_e32 vcc, s45, v58
	v_mad_i64_i32 v[32:33], s[4:5], v28, s78, 0
	s_nop 0
	v_cndmask_b32_e32 v58, v58, v59, vcc
	v_rsq_f32_e32 v64, v58
	v_pk_mul_f32 v[58:59], v[4:5], v[30:31] op_sel_hi:[1,0]
	v_mul_f32_e32 v65, 0x45800000, v64
	v_cndmask_b32_e32 v64, v64, v65, vcc
	v_pk_mul_f32 v[48:49], v[48:49], v[64:65] op_sel_hi:[1,0]
	v_pk_mul_f32 v[46:47], v[46:47], v[64:65] op_sel_hi:[1,0]
	v_pk_mul_f32 v[52:53], v[52:53], v[64:65] op_sel_hi:[1,0]
	v_pk_mul_f32 v[50:51], v[50:51], v[64:65] op_sel_hi:[1,0]
	s_waitcnt vmcnt(5)
	v_pk_mul_f32 v[46:47], v[36:37], v[46:47]
	v_pk_mul_f32 v[48:49], v[34:35], v[48:49]
	s_waitcnt vmcnt(4)
	v_pk_mul_f32 v[52:53], v[38:39], v[52:53]
	ds_bpermute_b32 v64, v31, v48
	ds_bpermute_b32 v65, v31, v49
	ds_bpermute_b32 v68, v31, v46
	ds_bpermute_b32 v69, v31, v47
	ds_bpermute_b32 v66, v31, v52
	ds_bpermute_b32 v67, v31, v53
	s_waitcnt vmcnt(3)
	v_pk_mul_f32 v[46:47], v[44:45], v[46:47]
	v_pk_mul_f32 v[48:49], v[42:43], v[48:49]
	s_waitcnt vmcnt(1) lgkmcnt(2)
	v_pk_mul_f32 v[68:69], v[26:27], v[68:69]
	v_pk_mul_f32 v[64:65], v[24:25], v[64:65]
	v_pk_mul_f32 v[52:53], v[20:21], v[52:53]
	s_waitcnt vmcnt(0) lgkmcnt(0)
	v_pk_mul_f32 v[66:67], v[16:17], v[66:67]
	v_pk_fma_f32 v[48:49], v[168:169], v[64:65], v[48:49]
	v_pk_fma_f32 v[46:47], v[54:55], v[68:69], v[46:47]
	v_pk_fma_f32 v[52:53], v[168:169], v[66:67], v[52:53]
	v_pk_mul_f32 v[64:65], v[46:47], s[52:53] op_sel_hi:[1,0]
	v_pk_mul_f32 v[46:47], v[48:49], s[52:53] op_sel_hi:[1,0]
	v_pk_mul_f32 v[48:49], v[56:57], v[56:57]
	v_pk_mul_f32 v[66:67], v[58:59], v[58:59]
	v_pk_mul_f32 v[50:51], v[40:41], v[50:51]
	v_pk_mov_b32 v[68:69], v[66:67], v[48:49] op_sel:[1,0]
	v_mov_b32_e32 v67, v49
	v_pk_add_f32 v[48:49], v[68:69], v[66:67]
	v_pk_mul_f32 v[66:67], v[60:61], v[60:61]
	v_pk_mul_f32 v[68:69], v[62:63], v[62:63]
	v_mov_b32_e32 v72, v66
	v_mov_b32_e32 v73, v68
	v_mov_b32_e32 v68, v67
	v_pk_add_f32 v[66:67], v[72:73], v[68:69]
	v_add_f32_e32 v48, v48, v49
	v_add_f32_e32 v48, v67, v48
	ds_bpermute_b32 v70, v31, v50
	ds_bpermute_b32 v71, v31, v51
	v_add_f32_e32 v66, v66, v48
	ds_bpermute_b32 v29, v29, v66
	v_pk_mul_f32 v[50:51], v[22:23], v[50:51]
	v_cvt_pk_bf16_f32 v46, v46, v47
	s_waitcnt lgkmcnt(1)
	v_pk_mul_f32 v[70:71], v[18:19], v[70:71]
	v_cvt_pk_bf16_f32 v47, v64, v65
	s_waitcnt lgkmcnt(0)
	v_add_f32_e32 v29, v66, v29
	v_pk_fma_f32 v[48:49], v[54:55], v[70:71], v[50:51]
	s_nop 0
	v_pk_mul_f32 v[50:51], v[48:49], s[52:53] op_sel_hi:[1,0]
	v_pk_mul_f32 v[48:49], v[52:53], s[52:53] op_sel_hi:[1,0]
	ds_bpermute_b32 v52, v31, v29
	v_cvt_pk_bf16_f32 v48, v48, v49
	v_cvt_pk_bf16_f32 v49, v50, v51
	v_mov_b64_e32 v[50:51], s[64:65]
	v_mad_i64_i32 v[50:51], s[4:5], v28, s78, v[50:51]
	s_waitcnt lgkmcnt(0)
	v_add_f32_e32 v29, v29, v52
	v_fmamk_f32 v29, v29, 0x3d000000, v187
	v_mul_f32_e32 v52, 0x4b800000, v29
	v_cmp_gt_f32_e32 vcc, s45, v29
	v_lshl_add_u64 v[50:51], v[166:167], 1, v[50:51]
	global_store_dwordx4 v[50:51], v[46:49], off offset:128
	v_cndmask_b32_e32 v29, v29, v52, vcc
	v_rsq_f32_e32 v29, v29
	s_nop 0
	v_mul_f32_e32 v46, 0x45800000, v29
	v_cndmask_b32_e32 v46, v29, v46, vcc
	v_pk_mul_f32 v[48:49], v[58:59], v[46:47] op_sel_hi:[1,0]
	v_pk_mul_f32 v[50:51], v[56:57], v[46:47] op_sel_hi:[1,0]
	v_pk_mul_f32 v[34:35], v[34:35], v[48:49]
	v_pk_mul_f32 v[48:49], v[62:63], v[46:47] op_sel_hi:[1,0]
	v_pk_mul_f32 v[46:47], v[60:61], v[46:47] op_sel_hi:[1,0]
	v_pk_mul_f32 v[38:39], v[38:39], v[48:49]
	v_pk_mul_f32 v[40:41], v[40:41], v[46:47]
	v_pk_mul_f32 v[36:37], v[36:37], v[50:51]
	ds_bpermute_b32 v48, v31, v38
	ds_bpermute_b32 v49, v31, v39
	ds_bpermute_b32 v52, v31, v40
	ds_bpermute_b32 v53, v31, v41
	ds_bpermute_b32 v46, v31, v34
	ds_bpermute_b32 v47, v31, v35
	ds_bpermute_b32 v50, v31, v36
	ds_bpermute_b32 v51, v31, v37
	v_pk_mul_f32 v[22:23], v[22:23], v[40:41]
	v_pk_mul_f32 v[20:21], v[20:21], v[38:39]
	s_waitcnt lgkmcnt(4)
	v_pk_mul_f32 v[18:19], v[18:19], v[52:53]
	v_pk_mul_f32 v[16:17], v[16:17], v[48:49]
	v_pk_mul_f32 v[36:37], v[44:45], v[36:37]
	v_pk_mul_f32 v[34:35], v[42:43], v[34:35]
	s_waitcnt lgkmcnt(0)
	v_pk_mul_f32 v[26:27], v[26:27], v[50:51]
	v_pk_mul_f32 v[24:25], v[24:25], v[46:47]
	v_pk_fma_f32 v[16:17], v[168:169], v[16:17], v[20:21]
	v_pk_fma_f32 v[18:19], v[54:55], v[18:19], v[22:23]
	v_pk_fma_f32 v[24:25], v[168:169], v[24:25], v[34:35]
	v_pk_fma_f32 v[26:27], v[54:55], v[26:27], v[36:37]
	v_pk_mul_f32 v[20:21], v[18:19], s[52:53] op_sel_hi:[1,0]
	v_pk_mul_f32 v[18:19], v[16:17], s[52:53] op_sel_hi:[1,0]
	v_pk_mul_f32 v[26:27], v[26:27], s[52:53] op_sel_hi:[1,0]
	v_pk_mul_f32 v[24:25], v[24:25], s[52:53] op_sel_hi:[1,0]
	v_cvt_pk_bf16_f32 v17, v26, v27
	v_cvt_pk_bf16_f32 v18, v18, v19
	v_cvt_pk_bf16_f32 v19, v20, v21
	s_nop 0
	v_cvt_pk_bf16_f32 v16, v24, v25
; __device__ __forceinline__ unsigned cvt_pk_bf16(float lo, float hi) { unsigned r; asm("v_cvt_pk_bf16_f32 %0, %1, %2" : "=v"(r) : "v"(lo), "v"(hi)); return r; }
;     __device__ __forceinline__ void epi(Acc& acc, const Unit& u, int wr, int wc, int fr, int fq) const {
;     ...
;                 if (u.pn < 2) {
;                     const int head = u.pn * 4 + wc; float s = 0.f; f32x4 v[2][2];
; #pragma unroll
;                     for (int bj = 0; bj < 2; ++bj)
; #pragma unroll
;                         for (int n = 0; n < 2; ++n) { v[bj][n] = acc[ai][bj][m][n] * rq; const f32x4 x = v[bj][n]; s += (x[0] * x[0] + x[1] * x[1]) + (x[2] * x[2] + x[3] * x[3]); }
;                     s += __shfl_xor(s, 16); s += __shfl_xor(s, 32);
;                     const float r2 = rsqrtf(s * (1.f / 64.f) + EPS) * QSCALE;
; #pragma unroll
;                     for (int bj = 0; bj < 2; ++bj) { const f32x4 g0 = *(const f32x4*)(qng + bj * 32 + fq * 8), g1 = *(const f32x4*)(qng + bj * 32 + fq * 8 + 4);
;                         const f32x4 a = v[bj][0] * r2 * g0, b = v[bj][1] * r2 * g1;
;                         u32x4 w; w.x = cvt_pk_bf16(a[0], a[1]); w.y = cvt_pk_bf16(a[2], a[3]); w.z = cvt_pk_bf16(b[0], b[1]); w.w = cvt_pk_bf16(b[2], b[3]);
;                         *(u32x4*)(Q + (size_t)row * 768 + head * 96 + bj * 32 + fq * 8) = w; }
.LBB0_596:
	s_mov_b64 s[4:5], 0x380
	s_andn2_b64 vcc, exec, s[8:9]
	s_mov_b64 s[8:9], s[62:63]
	s_cbranch_vccnz .LBB0_598
	v_pk_mul_f32 v[14:15], v[14:15], v[30:31] op_sel_hi:[1,0]
	v_pk_mul_f32 v[12:13], v[12:13], v[30:31] op_sel_hi:[1,0]
	v_pk_mul_f32 v[10:11], v[10:11], v[30:31] op_sel_hi:[1,0]
	v_pk_mul_f32 v[8:9], v[8:9], v[30:31] op_sel_hi:[1,0]
	v_pk_mul_f32 v[24:25], v[6:7], v[30:31] op_sel_hi:[1,0]
	v_pk_mul_f32 v[26:27], v[4:5], v[30:31] op_sel_hi:[1,0]
	v_pk_mul_f32 v[34:35], v[2:3], v[30:31] op_sel_hi:[1,0]
	v_pk_mul_f32 v[30:31], v[0:1], v[30:31] op_sel_hi:[1,0]
	v_pk_mul_f32 v[0:1], v[14:15], v[14:15]
	v_pk_mul_f32 v[2:3], v[12:13], v[12:13]
	v_pk_mul_f32 v[4:5], v[10:11], v[10:11]
	v_pk_mul_f32 v[6:7], v[8:9], v[8:9]
	v_and_b32_e32 v33, 64, v188
	v_pk_mov_b32 v[38:39], v[2:3], v[0:1] op_sel:[1,0]
	v_mov_b32_e32 v3, v1
	v_pk_mov_b32 v[0:1], v[6:7], v[4:5] op_sel:[1,0]
	v_mov_b32_e32 v7, v5
	v_mul_f32_e32 v32, v26, v26
	v_mul_f32_e32 v36, v24, v24
	v_add_u32_e32 v37, 64, v33
	v_pk_add_f32 v[2:3], v[38:39], v[2:3]
	v_pk_add_f32 v[0:1], v[0:1], v[6:7]
	v_pk_fma_f32 v[4:5], v[26:27], v[26:27], v[32:33] op_sel_hi:[1,1,0]
	v_pk_fma_f32 v[32:33], v[24:25], v[24:25], v[36:37] op_sel_hi:[1,1,0]
	v_pk_add_f32 v[2:3], v[2:3], v[2:3] op_sel_hi:[0,1]
	v_pk_add_f32 v[0:1], v[0:1], v[0:1] op_sel_hi:[0,1]
	v_xor_b32_e32 v29, 16, v188
	v_mul_f32_e32 v4, v30, v30
	v_mul_f32_e32 v32, v31, v31
	v_mul_f32_e32 v2, v34, v34
	v_mul_f32_e32 v0, v35, v35
	v_cmp_lt_i32_e32 vcc, v29, v37
	v_pk_add_f32 v[4:5], v[4:5], v[32:33]
	v_pk_add_f32 v[0:1], v[2:3], v[0:1]
	v_cndmask_b32_e32 v29, v188, v29, vcc
	v_pk_add_f32 v[0:1], v[4:5], v[0:1]
	v_lshlrev_b32_e32 v6, 2, v29
	v_add_f32_e32 v0, v0, v1
	ds_bpermute_b32 v1, v6, v0
	v_xor_b32_e32 v2, 32, v188
	v_cmp_lt_i32_e32 vcc, v2, v37
	v_mad_i64_i32 v[32:33], s[4:5], v28, s78, 0
	s_nop 0
	v_cndmask_b32_e32 v2, v188, v2, vcc
	v_lshlrev_b32_e32 v2, 2, v2
	s_waitcnt lgkmcnt(0)
	v_add_f32_e32 v3, v0, v1
	ds_bpermute_b32 v2, v2, v3
	v_mov_b64_e32 v[0:1], s[42:43]
	v_mad_i64_i32 v[0:1], s[4:5], v28, s78, v[0:1]
	v_lshl_add_u64 v[0:1], s[82:83], 1, v[0:1]
	s_waitcnt lgkmcnt(0)
	v_add_f32_e32 v2, v3, v2
	v_fmamk_f32 v2, v2, 0x3c800000, v187
	v_mul_f32_e32 v3, 0x4b800000, v2
	v_cmp_gt_f32_e32 vcc, s45, v2
	v_lshl_add_u64 v[4:5], v[166:167], 1, v[0:1]
	s_mov_b64 s[4:5], 64
	v_cndmask_b32_e32 v2, v2, v3, vcc
	v_rsq_f32_e32 v2, v2
	s_mov_b64 s[8:9], s[82:83]
	v_mul_f32_e32 v0, 0x45800000, v2
	v_cndmask_b32_e32 v0, v2, v0, vcc
	v_mul_f32_e32 v36, 0x3e16c740, v0
	v_pk_mul_f32 v[0:1], v[12:13], v[36:37] op_sel_hi:[1,0]
	v_pk_mul_f32 v[2:3], v[14:15], v[36:37] op_sel_hi:[1,0]
	v_pk_mul_f32 v[6:7], v[8:9], v[36:37] op_sel_hi:[1,0]
	v_pk_mul_f32 v[8:9], v[10:11], v[36:37] op_sel_hi:[1,0]
	v_pk_mul_f32 v[10:11], v[24:25], v[36:37] op_sel_hi:[1,0]
	v_pk_mul_f32 v[12:13], v[30:31], v[36:37] op_sel_hi:[1,0]
	v_pk_mul_f32 v[14:15], v[34:35], v[36:37] op_sel_hi:[1,0]
	v_pk_mul_f32 v[2:3], v[214:215], v[2:3]
	v_pk_mul_f32 v[0:1], v[212:213], v[0:1]
	v_pk_mul_f32 v[8:9], v[218:219], v[8:9]
	v_pk_mul_f32 v[6:7], v[216:217], v[6:7]
	v_cvt_pk_bf16_f32 v0, v0, v1
	v_cvt_pk_bf16_f32 v1, v2, v3
	v_cvt_pk_bf16_f32 v3, v8, v9
	v_pk_mul_f32 v[8:9], v[26:27], v[36:37] op_sel_hi:[1,0]
	v_cvt_pk_bf16_f32 v2, v6, v7
	global_store_dwordx4 v[4:5], v[0:3], off
	s_nop 1
	v_pk_mul_f32 v[2:3], v[222:223], v[10:11]
	v_pk_mul_f32 v[0:1], v[220:221], v[8:9]
	v_pk_mul_f32 v[6:7], v[226:227], v[14:15]
	v_pk_mul_f32 v[4:5], v[224:225], v[12:13]
	v_cvt_pk_bf16_f32 v16, v0, v1
	v_cvt_pk_bf16_f32 v17, v2, v3
	v_cvt_pk_bf16_f32 v19, v6, v7
	s_nop 0
	v_cvt_pk_bf16_f32 v18, v4, v5

; __device__ __forceinline__ int xcd_map(int L, int nwg) { const int q = nwg / NXCD, r = nwg % NXCD, xcd = L % NXCD, off = L / NXCD; return (xcd < r ? xcd * (q + 1) : r * (q + 1) + (xcd - r) * q) + off; }
;     __device__ __forceinline__ bool next(int i, Unit& u) const { const int L = i * G + c; if (L >= NTOT) return false; pg8::grouped(pg8::xcd_map(L, NTOT), NM, 3, u.pm, u.pn); u.kind = 0; return true; }
;     __device__ __forceinline__ bool next(int i, Unit& u) const { const int L = i * G + c; if (L >= NTOT) return false; pg8::grouped(pg8::xcd_map(L, NTOT), NM, NN, u.pm, u.pn); u.kind = 0; return true; }
;     __device__ __forceinline__ bool next(int i, Unit& u) const {
;         const int L = i * G + c; if (L >= NTOT) return false;
;         const int w = pg8::xcd_map(L, NTOT);
;         if (w < NA) { pg8::grouped(w, NM, 2, u.pm, u.pn); u.kind = 0; } else { pg8::grouped(w - NA, 2, NM, u.pm, u.pn); u.kind = 1; }
;         return true;
; __global__ void __launch_bounds__(512, 2) mega_fwd(Args a) {
;     ...
;         ProgKV P; P.K = 256; P.lda = 256; P.ldb = 256; P.G = G; P.c = (G == 256) ? ((bx + 140) & 255) : bx;
;         P.CKV = CKV; P.Wt = Wt_ukv; P.KN = KN; P.VVt = VVt; P.kng = kn_g;
;         pg8::gemm_phase(lds, P);
.LBB0_602:
	s_cmpk_lg_i32 s34, 0x100
	s_cselect_b64 s[68:69], -1, 0
	s_add_i32 s0, s2, 0x38
	s_and_b32 s3, s0, 0xff
	s_cmpk_eq_i32 s34, 0x100
	s_cselect_b64 s[12:13], -1, 0
	s_and_b64 s[0:1], s[12:13], exec
	s_cselect_b32 s3, s3, s2
	v_mov_b32_e32 v8, v211
	s_cmpk_lt_i32 s3, 0x308
	s_cselect_b64 s[50:51], -1, 0
	s_cmpk_gt_i32 s3, 0x307
	v_readfirstlane_b32 s1, v8
	s_cbranch_scc1 .LBB0_605
	s_ashr_i32 s0, s3, 31
	s_lshr_b32 s0, s0, 29
	s_add_i32 s0, s3, s0
	s_ashr_i32 s4, s0, 3
	s_and_b32 s0, s0, -8
	s_sub_i32 s0, s3, s0
	s_cmp_lt_i32 s0, 0
	s_movk_i32 s5, 0x62
	s_cselect_b32 s5, s5, 0x61
	s_mul_i32 s6, s5, s0
	s_add_i32 s6, s6, s4
	v_readlane_b32 s72, v238, 49
	s_cmpk_gt_i32 s6, 0x183
	v_readlane_b32 s73, v238, 50
	s_cbranch_scc0 .LBB0_606
	s_add_i32 s4, s6, 0xfe7c
	s_and_b32 s0, s6, 1
	s_bfe_u32 s48, s4, 0xf0001
	s_mov_b64 s[10:11], 0
	s_mov_b32 s39, 1
	s_cbranch_execz .LBB0_607
	s_branch .LBB0_608
